# gate epilogue: packed sigmoid divisions issued two row pairs at a time (independent Newton chains interleaved)
# speedup vs baseline: 1.0121x; 1.0059x over previous
.LBB0_627:
	ds_read_b128 v[146:149], v157
	ds_read_b128 v[150:153], v157 offset:1024
	ds_read_b128 v[160:163], v157 offset:2048
	ds_read_b128 v[170:173], v157 offset:3072
	s_add_u32 s12, s14, 0x100
	s_addc_u32 s13, s15, 0
	s_cmp_eq_u32 s42, 4
	s_cselect_b32 s19, s31, s13
	s_cselect_b32 s18, s30, s12
	s_cselect_b32 s17, s8, s33
	s_cselect_b32 s16, s9, s29
	v_lshl_add_u64 v[164:165], s[14:15], 0, v[138:139]
	s_add_i32 m0, s39, 0xc000
	ds_read_b128 v[174:177], v158
	ds_read_b128 v[178:181], v158 offset:1024
	ds_read_b128 v[182:185], v158 offset:2048
	ds_read_b128 v[186:189], v158 offset:3072
	ds_read_b128 v[190:193], v158 offset:4096
	ds_read_b128 v[194:197], v158 offset:5120
	ds_read_b128 v[198:201], v158 offset:6144
	ds_read_b128 v[202:205], v158 offset:7168
	global_load_lds_dwordx4 v[164:165], off
	v_lshl_add_u64 v[164:165], s[14:15], 0, v[136:137]
	s_add_i32 m0, s39, 0xe000
	s_nop 0
	global_load_lds_dwordx4 v[164:165], off
	s_waitcnt lgkmcnt(8)
	s_barrier
	s_waitcnt lgkmcnt(0)
	s_setprio 1
	s_waitcnt lgkmcnt(0)
	v_mfma_f32_16x16x32_bf16 v[124:127], v[146:149], v[174:177], v[124:127]
	v_mfma_f32_16x16x32_bf16 v[120:123], v[160:163], v[174:177], v[120:123]
	v_mfma_f32_16x16x32_bf16 v[108:111], v[146:149], v[182:185], v[108:111]
	v_mfma_f32_16x16x32_bf16 v[104:107], v[160:163], v[182:185], v[104:107]
	v_mfma_f32_16x16x32_bf16 v[92:95], v[146:149], v[190:193], v[92:95]
	v_mfma_f32_16x16x32_bf16 v[88:91], v[160:163], v[190:193], v[88:91]
	v_mfma_f32_16x16x32_bf16 v[76:79], v[146:149], v[198:201], v[76:79]
	v_mfma_f32_16x16x32_bf16 v[72:75], v[160:163], v[198:201], v[72:75]
	v_mfma_f32_16x16x32_bf16 v[124:127], v[150:153], v[178:181], v[124:127]
	v_mfma_f32_16x16x32_bf16 v[120:123], v[170:173], v[178:181], v[120:123]
	v_mfma_f32_16x16x32_bf16 v[108:111], v[150:153], v[186:189], v[108:111]
	v_mfma_f32_16x16x32_bf16 v[104:107], v[170:173], v[186:189], v[104:107]
	v_mfma_f32_16x16x32_bf16 v[92:95], v[150:153], v[194:197], v[92:95]
	v_mfma_f32_16x16x32_bf16 v[88:91], v[170:173], v[194:197], v[88:91]
	v_mfma_f32_16x16x32_bf16 v[76:79], v[150:153], v[202:205], v[76:79]
	v_mfma_f32_16x16x32_bf16 v[72:75], v[170:173], v[202:205], v[72:75]
	s_setprio 0
	s_barrier
	s_add_i32 s14, s59, s37
	v_lshl_add_u64 v[164:165], s[16:17], 0, v[132:133]
	s_mov_b32 m0, s14
	ds_read_b128 v[206:209], v159
	ds_read_b128 v[210:213], v159 offset:1024
	ds_read_b128 v[214:217], v159 offset:2048
	ds_read_b128 v[218:221], v159 offset:3072
	global_load_lds_dwordx4 v[164:165], off
	v_lshl_add_u64 v[222:223], s[16:17], 0, v[128:129]
	s_add_i32 m0, s14, 0x2000
	s_nop 0
	global_load_lds_dwordx4 v[222:223], off
	s_barrier
	s_waitcnt lgkmcnt(0)
	s_setprio 1
	s_waitcnt lgkmcnt(0)
	v_mfma_f32_16x16x32_bf16 v[116:119], v[206:209], v[174:177], v[116:119]
	v_mfma_f32_16x16x32_bf16 v[112:115], v[214:217], v[174:177], v[112:115]
	v_mfma_f32_16x16x32_bf16 v[100:103], v[206:209], v[182:185], v[100:103]
	v_mfma_f32_16x16x32_bf16 v[96:99], v[214:217], v[182:185], v[96:99]
	v_mfma_f32_16x16x32_bf16 v[84:87], v[206:209], v[190:193], v[84:87]
	v_mfma_f32_16x16x32_bf16 v[80:83], v[214:217], v[190:193], v[80:83]
	v_mfma_f32_16x16x32_bf16 v[68:71], v[206:209], v[198:201], v[68:71]
	v_mfma_f32_16x16x32_bf16 v[64:67], v[214:217], v[198:201], v[64:67]
	v_mfma_f32_16x16x32_bf16 v[116:119], v[210:213], v[178:181], v[116:119]
	v_mfma_f32_16x16x32_bf16 v[112:115], v[218:221], v[178:181], v[112:115]
	v_mfma_f32_16x16x32_bf16 v[100:103], v[210:213], v[186:189], v[100:103]
	v_mfma_f32_16x16x32_bf16 v[96:99], v[218:221], v[186:189], v[96:99]
	v_mfma_f32_16x16x32_bf16 v[84:87], v[210:213], v[194:197], v[84:87]
	v_mfma_f32_16x16x32_bf16 v[80:83], v[218:221], v[194:197], v[80:83]
	v_mfma_f32_16x16x32_bf16 v[68:71], v[210:213], v[202:205], v[68:71]
	v_mfma_f32_16x16x32_bf16 v[64:67], v[218:221], v[202:205], v[64:67]
	s_setprio 0
	s_mov_b32 m0, s39
	v_lshl_add_u64 v[224:225], s[18:19], 0, v[134:135]
	s_barrier
	ds_read_b128 v[174:177], v158 offset:16384
	ds_read_b128 v[178:181], v158 offset:17408
	ds_read_b128 v[182:185], v158 offset:18432
	ds_read_b128 v[186:189], v158 offset:19456
	ds_read_b128 v[190:193], v158 offset:20480
	ds_read_b128 v[194:197], v158 offset:21504
	ds_read_b128 v[198:201], v158 offset:22528
	ds_read_b128 v[202:205], v158 offset:23552
	global_load_lds_dwordx4 v[224:225], off
	v_lshl_add_u64 v[226:227], s[18:19], 0, v[130:131]
	s_mov_b32 m0, s51
	s_nop 0
	global_load_lds_dwordx4 v[226:227], off
	s_barrier
	s_waitcnt lgkmcnt(0)
	s_setprio 1
	s_waitcnt lgkmcnt(0)
	v_mfma_f32_16x16x32_bf16 v[60:63], v[146:149], v[174:177], v[60:63]
	v_mfma_f32_16x16x32_bf16 v[56:59], v[160:163], v[174:177], v[56:59]
	v_mfma_f32_16x16x32_bf16 v[44:47], v[146:149], v[182:185], v[44:47]
	v_mfma_f32_16x16x32_bf16 v[40:43], v[160:163], v[182:185], v[40:43]
	v_mfma_f32_16x16x32_bf16 v[28:31], v[146:149], v[190:193], v[28:31]
	v_mfma_f32_16x16x32_bf16 v[24:27], v[160:163], v[190:193], v[24:27]
	v_mfma_f32_16x16x32_bf16 v[12:15], v[146:149], v[198:201], v[12:15]
	v_mfma_f32_16x16x32_bf16 v[8:11], v[160:163], v[198:201], v[8:11]
	v_mfma_f32_16x16x32_bf16 v[60:63], v[150:153], v[178:181], v[60:63]
	v_mfma_f32_16x16x32_bf16 v[56:59], v[170:173], v[178:181], v[56:59]
	v_mfma_f32_16x16x32_bf16 v[44:47], v[150:153], v[186:189], v[44:47]
	v_mfma_f32_16x16x32_bf16 v[40:43], v[170:173], v[186:189], v[40:43]
	v_mfma_f32_16x16x32_bf16 v[28:31], v[150:153], v[194:197], v[28:31]
	v_mfma_f32_16x16x32_bf16 v[24:27], v[170:173], v[194:197], v[24:27]
	v_mfma_f32_16x16x32_bf16 v[12:15], v[150:153], v[202:205], v[12:15]
	v_mfma_f32_16x16x32_bf16 v[8:11], v[170:173], v[202:205], v[8:11]
	s_setprio 0
	s_barrier
	s_add_u32 s14, s16, 0x20000
	s_addc_u32 s15, s17, 0
	s_add_i32 s43, s60, s37
	v_lshl_add_u64 v[146:147], s[14:15], 0, v[132:133]
	s_mov_b32 m0, s43
	s_nop 0
	global_load_lds_dwordx4 v[146:147], off
	v_lshl_add_u64 v[146:147], s[14:15], 0, v[128:129]
	s_add_i32 m0, s43, 0x2000
	s_nop 0
	global_load_lds_dwordx4 v[146:147], off
	s_waitcnt vmcnt(6)
	s_barrier
	s_setprio 1
	v_mfma_f32_16x16x32_bf16 v[52:55], v[206:209], v[174:177], v[52:55]
	v_mfma_f32_16x16x32_bf16 v[48:51], v[214:217], v[174:177], v[48:51]
	v_mfma_f32_16x16x32_bf16 v[36:39], v[206:209], v[182:185], v[36:39]
	v_mfma_f32_16x16x32_bf16 v[32:35], v[214:217], v[182:185], v[32:35]
	v_mfma_f32_16x16x32_bf16 v[20:23], v[206:209], v[190:193], v[20:23]
	v_mfma_f32_16x16x32_bf16 v[16:19], v[214:217], v[190:193], v[16:19]
	v_mfma_f32_16x16x32_bf16 v[4:7], v[206:209], v[198:201], v[4:7]
	v_mfma_f32_16x16x32_bf16 v[0:3], v[214:217], v[198:201], v[0:3]
	v_mfma_f32_16x16x32_bf16 v[52:55], v[210:213], v[178:181], v[52:55]
	v_mfma_f32_16x16x32_bf16 v[48:51], v[218:221], v[178:181], v[48:51]
	v_mfma_f32_16x16x32_bf16 v[36:39], v[210:213], v[186:189], v[36:39]
	v_mfma_f32_16x16x32_bf16 v[32:35], v[218:221], v[186:189], v[32:35]
	v_mfma_f32_16x16x32_bf16 v[20:23], v[210:213], v[194:197], v[20:23]
	v_mfma_f32_16x16x32_bf16 v[16:19], v[218:221], v[194:197], v[16:19]
	v_mfma_f32_16x16x32_bf16 v[4:7], v[210:213], v[202:205], v[4:7]
	v_mfma_f32_16x16x32_bf16 v[0:3], v[218:221], v[202:205], v[0:3]
	s_setprio 0
	s_add_i32 s43, 0, 0x18000
	v_add_u32_e32 v170, s43, v155
	s_barrier
	ds_read_b128 v[146:149], v170
	ds_read_b128 v[150:153], v170 offset:1024
	ds_read_b128 v[160:163], v170 offset:2048
	ds_read_b128 v[170:173], v170 offset:3072
	s_add_u32 s14, s18, 0x110000
	s_addc_u32 s15, s19, 0
	s_mov_b32 m0, s53
	v_lshl_add_u64 v[206:207], s[14:15], 0, v[134:135]
	ds_read_b128 v[174:177], v158 offset:32768
	ds_read_b128 v[178:181], v158 offset:33792
	ds_read_b128 v[182:185], v158 offset:34816
	ds_read_b128 v[186:189], v158 offset:35840
	ds_read_b128 v[190:193], v158 offset:36864
	ds_read_b128 v[194:197], v158 offset:37888
	ds_read_b128 v[198:201], v158 offset:38912
	ds_read_b128 v[202:205], v158 offset:39936
	global_load_lds_dwordx4 v[206:207], off
	v_lshl_add_u64 v[206:207], s[14:15], 0, v[130:131]
	s_mov_b32 m0, s54
	s_nop 0
	global_load_lds_dwordx4 v[206:207], off
	s_waitcnt lgkmcnt(8)
	s_barrier
	s_waitcnt lgkmcnt(0)
	s_setprio 1
	s_waitcnt lgkmcnt(0)
	v_mfma_f32_16x16x32_bf16 v[124:127], v[146:149], v[174:177], v[124:127]
	v_mfma_f32_16x16x32_bf16 v[120:123], v[160:163], v[174:177], v[120:123]
	v_mfma_f32_16x16x32_bf16 v[108:111], v[146:149], v[182:185], v[108:111]
	v_mfma_f32_16x16x32_bf16 v[104:107], v[160:163], v[182:185], v[104:107]
	v_mfma_f32_16x16x32_bf16 v[92:95], v[146:149], v[190:193], v[92:95]
	v_mfma_f32_16x16x32_bf16 v[88:91], v[160:163], v[190:193], v[88:91]
	v_mfma_f32_16x16x32_bf16 v[76:79], v[146:149], v[198:201], v[76:79]
	v_mfma_f32_16x16x32_bf16 v[72:75], v[160:163], v[198:201], v[72:75]
	v_mfma_f32_16x16x32_bf16 v[124:127], v[150:153], v[178:181], v[124:127]
	v_mfma_f32_16x16x32_bf16 v[120:123], v[170:173], v[178:181], v[120:123]
	v_mfma_f32_16x16x32_bf16 v[108:111], v[150:153], v[186:189], v[108:111]
	v_mfma_f32_16x16x32_bf16 v[104:107], v[170:173], v[186:189], v[104:107]
	v_mfma_f32_16x16x32_bf16 v[92:95], v[150:153], v[194:197], v[92:95]
	v_mfma_f32_16x16x32_bf16 v[88:91], v[170:173], v[194:197], v[88:91]
	v_mfma_f32_16x16x32_bf16 v[76:79], v[150:153], v[202:205], v[76:79]
	v_mfma_f32_16x16x32_bf16 v[72:75], v[170:173], v[202:205], v[72:75]
	s_setprio 0
	s_barrier
	s_add_i32 s18, 0, 0x1c000
	s_add_i32 s14, s43, s37
	v_add_u32_e32 v218, s18, v155
	v_lshl_add_u64 v[164:165], v[164:165], 0, s[26:27]
	s_mov_b32 m0, s14
	ds_read_b128 v[206:209], v218
	ds_read_b128 v[210:213], v218 offset:1024
	ds_read_b128 v[214:217], v218 offset:2048
	ds_read_b128 v[218:221], v218 offset:3072
	global_load_lds_dwordx4 v[164:165], off
	v_lshl_add_u64 v[164:165], v[222:223], 0, s[26:27]
	s_add_i32 m0, s14, 0x2000
	s_nop 0
	global_load_lds_dwordx4 v[164:165], off
	s_barrier
	s_waitcnt lgkmcnt(0)
	s_setprio 1
	s_waitcnt lgkmcnt(0)
	v_mfma_f32_16x16x32_bf16 v[116:119], v[206:209], v[174:177], v[116:119]
	v_mfma_f32_16x16x32_bf16 v[112:115], v[214:217], v[174:177], v[112:115]
	v_mfma_f32_16x16x32_bf16 v[100:103], v[206:209], v[182:185], v[100:103]
	v_mfma_f32_16x16x32_bf16 v[96:99], v[214:217], v[182:185], v[96:99]
	v_mfma_f32_16x16x32_bf16 v[84:87], v[206:209], v[190:193], v[84:87]
	v_mfma_f32_16x16x32_bf16 v[80:83], v[214:217], v[190:193], v[80:83]
	v_mfma_f32_16x16x32_bf16 v[68:71], v[206:209], v[198:201], v[68:71]
	v_mfma_f32_16x16x32_bf16 v[64:67], v[214:217], v[198:201], v[64:67]
	v_mfma_f32_16x16x32_bf16 v[116:119], v[210:213], v[178:181], v[116:119]
	v_mfma_f32_16x16x32_bf16 v[112:115], v[218:221], v[178:181], v[112:115]
	v_mfma_f32_16x16x32_bf16 v[100:103], v[210:213], v[186:189], v[100:103]
	v_mfma_f32_16x16x32_bf16 v[96:99], v[218:221], v[186:189], v[96:99]
	v_mfma_f32_16x16x32_bf16 v[84:87], v[210:213], v[194:197], v[84:87]
	v_mfma_f32_16x16x32_bf16 v[80:83], v[218:221], v[194:197], v[80:83]
	v_mfma_f32_16x16x32_bf16 v[68:71], v[210:213], v[202:205], v[68:71]
	v_mfma_f32_16x16x32_bf16 v[64:67], v[218:221], v[202:205], v[64:67]
	s_setprio 0
	s_mov_b32 m0, s56
	v_lshl_add_u64 v[164:165], v[224:225], 0, s[26:27]
	s_barrier
	ds_read_b128 v[174:177], v158 offset:49152
	ds_read_b128 v[178:181], v158 offset:50176
	ds_read_b128 v[182:185], v158 offset:51200
	ds_read_b128 v[186:189], v158 offset:52224
	ds_read_b128 v[190:193], v158 offset:53248
	ds_read_b128 v[194:197], v158 offset:54272
	ds_read_b128 v[198:201], v158 offset:55296
	ds_read_b128 v[202:205], v158 offset:56320
	global_load_lds_dwordx4 v[164:165], off
	v_lshl_add_u64 v[164:165], v[226:227], 0, s[26:27]
	s_mov_b32 m0, s57
	s_nop 0
	global_load_lds_dwordx4 v[164:165], off
	s_barrier
	s_waitcnt lgkmcnt(0)
	s_setprio 1
	s_waitcnt lgkmcnt(0)
	v_mfma_f32_16x16x32_bf16 v[60:63], v[146:149], v[174:177], v[60:63]
	v_mfma_f32_16x16x32_bf16 v[56:59], v[160:163], v[174:177], v[56:59]
	v_mfma_f32_16x16x32_bf16 v[44:47], v[146:149], v[182:185], v[44:47]
	v_mfma_f32_16x16x32_bf16 v[40:43], v[160:163], v[182:185], v[40:43]
	v_mfma_f32_16x16x32_bf16 v[28:31], v[146:149], v[190:193], v[28:31]
	v_mfma_f32_16x16x32_bf16 v[24:27], v[160:163], v[190:193], v[24:27]
	v_mfma_f32_16x16x32_bf16 v[12:15], v[146:149], v[198:201], v[12:15]
	v_mfma_f32_16x16x32_bf16 v[8:11], v[160:163], v[198:201], v[8:11]
	v_mfma_f32_16x16x32_bf16 v[60:63], v[150:153], v[178:181], v[60:63]
	v_mfma_f32_16x16x32_bf16 v[56:59], v[170:173], v[178:181], v[56:59]
	v_mfma_f32_16x16x32_bf16 v[44:47], v[150:153], v[186:189], v[44:47]
	v_mfma_f32_16x16x32_bf16 v[40:43], v[170:173], v[186:189], v[40:43]
	v_mfma_f32_16x16x32_bf16 v[28:31], v[150:153], v[194:197], v[28:31]
	v_mfma_f32_16x16x32_bf16 v[24:27], v[170:173], v[194:197], v[24:27]
	v_mfma_f32_16x16x32_bf16 v[12:15], v[150:153], v[202:205], v[12:15]
	v_mfma_f32_16x16x32_bf16 v[8:11], v[170:173], v[202:205], v[8:11]
	s_setprio 0
	s_barrier
	s_add_u32 s14, s16, 0x20080
	s_addc_u32 s15, s17, 0
	s_add_i32 s16, s18, s37
	v_lshl_add_u64 v[146:147], s[14:15], 0, v[132:133]
	s_mov_b32 m0, s16
	s_nop 0
	global_load_lds_dwordx4 v[146:147], off
	v_lshl_add_u64 v[146:147], s[14:15], 0, v[128:129]
	s_add_i32 m0, s16, 0x2000
	s_nop 0
	global_load_lds_dwordx4 v[146:147], off
	s_waitcnt vmcnt(6)
	s_barrier
	s_setprio 1
	v_mfma_f32_16x16x32_bf16 v[52:55], v[206:209], v[174:177], v[52:55]
	v_mfma_f32_16x16x32_bf16 v[48:51], v[214:217], v[174:177], v[48:51]
	v_mfma_f32_16x16x32_bf16 v[36:39], v[206:209], v[182:185], v[36:39]
	v_mfma_f32_16x16x32_bf16 v[32:35], v[214:217], v[182:185], v[32:35]
	v_mfma_f32_16x16x32_bf16 v[20:23], v[206:209], v[190:193], v[20:23]
	v_mfma_f32_16x16x32_bf16 v[16:19], v[214:217], v[190:193], v[16:19]
	v_mfma_f32_16x16x32_bf16 v[4:7], v[206:209], v[198:201], v[4:7]
	v_mfma_f32_16x16x32_bf16 v[0:3], v[214:217], v[198:201], v[0:3]
	v_mfma_f32_16x16x32_bf16 v[52:55], v[210:213], v[178:181], v[52:55]
	v_mfma_f32_16x16x32_bf16 v[48:51], v[218:221], v[178:181], v[48:51]
	v_mfma_f32_16x16x32_bf16 v[36:39], v[210:213], v[186:189], v[36:39]
	v_mfma_f32_16x16x32_bf16 v[32:35], v[218:221], v[186:189], v[32:35]
	v_mfma_f32_16x16x32_bf16 v[20:23], v[210:213], v[194:197], v[20:23]
	v_mfma_f32_16x16x32_bf16 v[16:19], v[218:221], v[194:197], v[16:19]
	v_mfma_f32_16x16x32_bf16 v[4:7], v[210:213], v[202:205], v[4:7]
	v_mfma_f32_16x16x32_bf16 v[0:3], v[218:221], v[202:205], v[0:3]
	s_setprio 0
	s_add_i32 s42, s42, 2
	s_add_u32 s29, s29, 0x100
	s_addc_u32 s33, s33, 0
	s_cmp_gt_u32 s42, 5
	s_mov_b64 s[14:15], s[12:13]
	s_barrier
	s_cbranch_scc0 .LBB0_627
	v_lshl_or_b32 v148, s7, 8, v156
	v_lshl_add_u32 v160, s6, 8, v154
	v_ashrrev_i32_e32 v149, 31, v148
	v_mov_b64_e32 v[146:147], s[24:25]
	v_mad_i64_i32 v[150:151], s[6:7], v160, s61, v[146:147]
	v_lshlrev_b64 v[148:149], 1, v[148:149]
	v_lshl_add_u64 v[150:151], v[150:151], 0, v[148:149]
	v_add_co_u32_e32 v152, vcc, 0x1000, v150
	s_nop 1
	v_addc_co_u32_e32 v153, vcc, 0, v151, vcc
	v_subrev_u32_e32 v198, s24, v150
	v_add_u32_e32 v199, 0x1a00, v198
	global_load_dwordx4 v[200:203], v199, s[24:25]
	v_add_u32_e32 v199, 0x1b00, v198
	global_load_dwordx4 v[204:207], v199, s[24:25]
	v_add_u32_e32 v199, 0x23a00, v198
	global_load_dwordx4 v[208:211], v199, s[24:25]
	v_add_u32_e32 v199, 0x23b00, v198
	global_load_dwordx4 v[212:215], v199, s[24:25]
	v_add_u32_e32 v199, 0x45a00, v198
	global_load_dwordx4 v[216:219], v199, s[24:25]
	v_add_u32_e32 v199, 0x45b00, v198
	global_load_dwordx4 v[232:235], v199, s[24:25]
	s_waitcnt vmcnt(5)
	v_mov_b32_e32 v162, v200
	v_mov_b32_e32 v163, v201
	v_mov_b32_e32 v164, v202
	v_mov_b32_e32 v165, v203
	v_add_u32_e32 v199, 0x67a00, v198
	global_load_dwordx4 v[200:203], v199, s[24:25]
	s_mov_b32 s100, 0xbfb8aa3b
	v_lshlrev_b32_e32 v236, 16, v162
	v_and_b32_e32 v237, 0xffff0000, v162
	v_lshlrev_b32_e32 v238, 16, v164
	v_and_b32_e32 v239, 0xffff0000, v164
	v_lshlrev_b32_e32 v240, 16, v163
	v_and_b32_e32 v241, 0xffff0000, v163
	v_lshlrev_b32_e32 v242, 16, v165
	v_and_b32_e32 v243, 0xffff0000, v165
	v_pk_mul_f32 v[236:237], v[236:237], s[100:101] op_sel_hi:[1,0]
	v_pk_mul_f32 v[238:239], v[238:239], s[100:101] op_sel_hi:[1,0]
	v_pk_mul_f32 v[240:241], v[240:241], s[100:101] op_sel_hi:[1,0]
	v_pk_mul_f32 v[242:243], v[242:243], s[100:101] op_sel_hi:[1,0]
	v_exp_f32_e32 v236, v236
	v_exp_f32_e32 v237, v237
	v_exp_f32_e32 v238, v238
	v_exp_f32_e32 v239, v239
	v_exp_f32_e32 v240, v240
	v_exp_f32_e32 v241, v241
	v_exp_f32_e32 v242, v242
	v_exp_f32_e32 v243, v243
	s_nop 0
	v_pk_add_f32 v[236:237], v[236:237], 1.0 op_sel_hi:[1,0]
	v_pk_add_f32 v[238:239], v[238:239], 1.0 op_sel_hi:[1,0]
	v_pk_add_f32 v[240:241], v[240:241], 1.0 op_sel_hi:[1,0]
	v_pk_add_f32 v[242:243], v[242:243], 1.0 op_sel_hi:[1,0]
	v_rcp_f32_e32 v244, v236
	v_rcp_f32_e32 v245, v237
	v_rcp_f32_e32 v250, v238
	v_rcp_f32_e32 v251, v239
	v_pk_fma_f32 v[246:247], v[236:237], v[244:245], 1.0 op_sel_hi:[1,1,0] neg_lo:[1,0,0] neg_hi:[1,0,0]
	v_pk_fma_f32 v[252:253], v[238:239], v[250:251], 1.0 op_sel_hi:[1,1,0] neg_lo:[1,0,0] neg_hi:[1,0,0]
	v_pk_fma_f32 v[244:245], v[246:247], v[244:245], v[244:245]
	v_pk_fma_f32 v[250:251], v[252:253], v[250:251], v[250:251]
	v_pk_fma_f32 v[246:247], v[236:237], v[244:245], 1.0 op_sel_hi:[1,1,0] neg_lo:[1,0,0] neg_hi:[1,0,0]
	v_pk_fma_f32 v[252:253], v[238:239], v[250:251], 1.0 op_sel_hi:[1,1,0] neg_lo:[1,0,0] neg_hi:[1,0,0]
	v_pk_fma_f32 v[248:249], v[246:247], v[244:245], v[244:245]
; __device__ __forceinline__ u32x4 pack8(const f32x4 v0, const f32x4 v1) { u32x4 w; w.x = pk2(v0[0], v0[1]); w.y = pk2(v0[2], v0[3]); w.z = pk2(v1[0], v1[1]); w.w = pk2(v1[2], v1[3]); return w; }
; __device__ __forceinline__ void unpack8(const u32x4 w, f32x4& v0, f32x4& v1) { v0 = (f32x4){bflo(w.x), bfhi(w.x), bflo(w.y), bfhi(w.y)}; v1 = (f32x4){bflo(w.z), bfhi(w.z), bflo(w.w), bfhi(w.w)}; }
; __device__ __forceinline__ float sigmoidf_(float x) { return 1.0f / (1.0f + __expf(-x)); }
;     __device__ __forceinline__ void operator()(const f32x4 (&acc)[2][2][4][2], const Unit& u, int wr, int wc, int fr, int fq) const {
;         const int row0 = u.pm * 256 + wr * 64 + fr, col0 = u.pn * 256 + wc * 32 + 8 * fq;
; #pragma unroll
;         for (int ai = 0; ai < 2; ++ai)
; #pragma unroll
;             for (int m = 0; m < 4; ++m) {
;                 bf16_t* rowp = z + (size_t)(row0 + ai * 128 + m * 16) * DIN + col0;
; #pragma unroll
;                 for (int bj = 0; bj < 2; ++bj) {
;                     const u32x4 gw = *(const u32x4*)(rowp + (MODE == 0 ? O_GB : O_GA) + bj * 128);
;                     f32x4 g0, g1; unpack8(gw, g0, g1);
;                     f32x4 v0, v1;
; #pragma unroll
;                     for (int j = 0; j < 4; ++j) { v0[j] = sigmoidf_(g0[j]) * acc[ai][bj][m][0][j]; v1[j] = sigmoidf_(g1[j]) * acc[ai][bj][m][1][j]; }
;                     if (MODE == 1) { const u32x4 mw = *(const u32x4*)(rowp + bj * 128); f32x4 m0, m1; unpack8(mw, m0, m1); v0 += m0; v1 += m1; }
;                     *(u32x4*)(rowp + bj * 128) = pack8(v0, v1); }
	v_pk_fma_f32 v[254:255], v[252:253], v[250:251], v[250:251]
	v_pk_fma_f32 v[246:247], v[236:237], v[248:249], 1.0 op_sel_hi:[1,1,0] neg_lo:[1,0,0] neg_hi:[1,0,0]
	v_pk_fma_f32 v[252:253], v[238:239], v[254:255], 1.0 op_sel_hi:[1,1,0] neg_lo:[1,0,0] neg_hi:[1,0,0]
	v_pk_fma_f32 v[248:249], v[246:247], v[244:245], v[248:249]
	v_pk_fma_f32 v[254:255], v[252:253], v[250:251], v[254:255]
	v_div_fixup_f32 v236, v248, v236, 1.0
	v_div_fixup_f32 v237, v249, v237, 1.0
	v_div_fixup_f32 v238, v254, v238, 1.0
	v_div_fixup_f32 v239, v255, v239, 1.0
	v_rcp_f32_e32 v244, v240
	v_rcp_f32_e32 v245, v241
	v_rcp_f32_e32 v250, v242
	v_rcp_f32_e32 v251, v243
	v_pk_fma_f32 v[246:247], v[240:241], v[244:245], 1.0 op_sel_hi:[1,1,0] neg_lo:[1,0,0] neg_hi:[1,0,0]
	v_pk_fma_f32 v[252:253], v[242:243], v[250:251], 1.0 op_sel_hi:[1,1,0] neg_lo:[1,0,0] neg_hi:[1,0,0]
	v_pk_fma_f32 v[244:245], v[246:247], v[244:245], v[244:245]
	v_pk_fma_f32 v[250:251], v[252:253], v[250:251], v[250:251]
	v_pk_fma_f32 v[246:247], v[240:241], v[244:245], 1.0 op_sel_hi:[1,1,0] neg_lo:[1,0,0] neg_hi:[1,0,0]
	v_pk_fma_f32 v[252:253], v[242:243], v[250:251], 1.0 op_sel_hi:[1,1,0] neg_lo:[1,0,0] neg_hi:[1,0,0]
	v_pk_fma_f32 v[248:249], v[246:247], v[244:245], v[244:245]
	v_pk_fma_f32 v[254:255], v[252:253], v[250:251], v[250:251]
	v_pk_fma_f32 v[246:247], v[240:241], v[248:249], 1.0 op_sel_hi:[1,1,0] neg_lo:[1,0,0] neg_hi:[1,0,0]
	v_pk_fma_f32 v[252:253], v[242:243], v[254:255], 1.0 op_sel_hi:[1,1,0] neg_lo:[1,0,0] neg_hi:[1,0,0]
	v_pk_fma_f32 v[248:249], v[246:247], v[244:245], v[248:249]
	v_pk_fma_f32 v[254:255], v[252:253], v[250:251], v[254:255]
	v_div_fixup_f32 v240, v248, v240, 1.0
	v_div_fixup_f32 v241, v249, v241, 1.0
	v_div_fixup_f32 v242, v254, v242, 1.0
	v_div_fixup_f32 v243, v255, v243, 1.0
	s_mov_b64 vcc, s[12:13]
	s_mov_b64 vcc, s[14:15]
	v_mul_f32_e32 v124, v124, v236
	s_mov_b64 vcc, s[16:17]
	v_mul_f32_e32 v161, v120, v238
	v_mul_f32_e32 v120, v125, v237
	v_mul_f32_e32 v125, v121, v239
	s_mov_b64 vcc, s[18:19]
	v_mul_f32_e32 v126, v126, v240
	v_mul_f32_e32 v162, v122, v242
	v_mul_f32_e32 v121, v127, v241
	v_mul_f32_e32 v123, v123, v243
	v_cvt_pk_bf16_f32 v120, v124, v120
	v_cvt_pk_bf16_f32 v121, v126, v121
	v_cvt_pk_bf16_f32 v122, v161, v125
	v_cvt_pk_bf16_f32 v123, v162, v123
	s_mov_b64 s[16:17], s[34:35]
	global_store_dwordx4 v[150:151], v[120:123], off
	s_mov_b64 s[14:15], s[30:31]
	s_waitcnt vmcnt(6)
	v_mov_b32_e32 v124, v204
	v_mov_b32_e32 v125, v205
	v_mov_b32_e32 v126, v206
	v_mov_b32_e32 v127, v207
	v_add_u32_e32 v199, 0x67b00, v198
	global_load_dwordx4 v[204:207], v199, s[24:25]
	s_mov_b32 s100, 0xbfb8aa3b
	v_lshlrev_b32_e32 v236, 16, v124
	v_and_b32_e32 v237, 0xffff0000, v124
	v_lshlrev_b32_e32 v238, 16, v126
	v_and_b32_e32 v239, 0xffff0000, v126
	v_lshlrev_b32_e32 v240, 16, v125
	v_and_b32_e32 v241, 0xffff0000, v125
	v_lshlrev_b32_e32 v242, 16, v127
	v_and_b32_e32 v243, 0xffff0000, v127
	v_pk_mul_f32 v[236:237], v[236:237], s[100:101] op_sel_hi:[1,0]
	v_pk_mul_f32 v[238:239], v[238:239], s[100:101] op_sel_hi:[1,0]
	v_pk_mul_f32 v[240:241], v[240:241], s[100:101] op_sel_hi:[1,0]
	v_pk_mul_f32 v[242:243], v[242:243], s[100:101] op_sel_hi:[1,0]
	v_exp_f32_e32 v236, v236
	v_exp_f32_e32 v237, v237
	v_exp_f32_e32 v238, v238
	v_exp_f32_e32 v239, v239
	v_exp_f32_e32 v240, v240
	v_exp_f32_e32 v241, v241
	v_exp_f32_e32 v242, v242
	v_exp_f32_e32 v243, v243
	s_nop 0
	v_pk_add_f32 v[236:237], v[236:237], 1.0 op_sel_hi:[1,0]
	v_pk_add_f32 v[238:239], v[238:239], 1.0 op_sel_hi:[1,0]
	v_pk_add_f32 v[240:241], v[240:241], 1.0 op_sel_hi:[1,0]
	v_pk_add_f32 v[242:243], v[242:243], 1.0 op_sel_hi:[1,0]
	v_rcp_f32_e32 v244, v236
	v_rcp_f32_e32 v245, v237
	v_rcp_f32_e32 v250, v238
	v_rcp_f32_e32 v251, v239
	v_pk_fma_f32 v[246:247], v[236:237], v[244:245], 1.0 op_sel_hi:[1,1,0] neg_lo:[1,0,0] neg_hi:[1,0,0]
	v_pk_fma_f32 v[252:253], v[238:239], v[250:251], 1.0 op_sel_hi:[1,1,0] neg_lo:[1,0,0] neg_hi:[1,0,0]
	v_pk_fma_f32 v[244:245], v[246:247], v[244:245], v[244:245]
	v_pk_fma_f32 v[250:251], v[252:253], v[250:251], v[250:251]
	v_pk_fma_f32 v[246:247], v[236:237], v[244:245], 1.0 op_sel_hi:[1,1,0] neg_lo:[1,0,0] neg_hi:[1,0,0]
	v_pk_fma_f32 v[252:253], v[238:239], v[250:251], 1.0 op_sel_hi:[1,1,0] neg_lo:[1,0,0] neg_hi:[1,0,0]
	v_pk_fma_f32 v[248:249], v[246:247], v[244:245], v[244:245]
	v_pk_fma_f32 v[254:255], v[252:253], v[250:251], v[250:251]
	v_pk_fma_f32 v[246:247], v[236:237], v[248:249], 1.0 op_sel_hi:[1,1,0] neg_lo:[1,0,0] neg_hi:[1,0,0]
	v_pk_fma_f32 v[252:253], v[238:239], v[254:255], 1.0 op_sel_hi:[1,1,0] neg_lo:[1,0,0] neg_hi:[1,0,0]
	v_pk_fma_f32 v[248:249], v[246:247], v[244:245], v[248:249]
	v_pk_fma_f32 v[254:255], v[252:253], v[250:251], v[254:255]
	v_div_fixup_f32 v236, v248, v236, 1.0
	v_div_fixup_f32 v237, v249, v237, 1.0
	v_div_fixup_f32 v238, v254, v238, 1.0
	v_div_fixup_f32 v239, v255, v239, 1.0
	v_rcp_f32_e32 v244, v240
	v_rcp_f32_e32 v245, v241
	v_rcp_f32_e32 v250, v242
	v_rcp_f32_e32 v251, v243
	v_pk_fma_f32 v[246:247], v[240:241], v[244:245], 1.0 op_sel_hi:[1,1,0] neg_lo:[1,0,0] neg_hi:[1,0,0]
	v_pk_fma_f32 v[252:253], v[242:243], v[250:251], 1.0 op_sel_hi:[1,1,0] neg_lo:[1,0,0] neg_hi:[1,0,0]
	v_pk_fma_f32 v[244:245], v[246:247], v[244:245], v[244:245]
	v_pk_fma_f32 v[250:251], v[252:253], v[250:251], v[250:251]
	v_pk_fma_f32 v[246:247], v[240:241], v[244:245], 1.0 op_sel_hi:[1,1,0] neg_lo:[1,0,0] neg_hi:[1,0,0]
	v_pk_fma_f32 v[252:253], v[242:243], v[250:251], 1.0 op_sel_hi:[1,1,0] neg_lo:[1,0,0] neg_hi:[1,0,0]
	v_pk_fma_f32 v[248:249], v[246:247], v[244:245], v[244:245]
	v_pk_fma_f32 v[254:255], v[252:253], v[250:251], v[250:251]
	v_pk_fma_f32 v[246:247], v[240:241], v[248:249], 1.0 op_sel_hi:[1,1,0] neg_lo:[1,0,0] neg_hi:[1,0,0]
	v_pk_fma_f32 v[252:253], v[242:243], v[254:255], 1.0 op_sel_hi:[1,1,0] neg_lo:[1,0,0] neg_hi:[1,0,0]
	v_pk_fma_f32 v[248:249], v[246:247], v[244:245], v[248:249]
	v_pk_fma_f32 v[254:255], v[252:253], v[250:251], v[254:255]
	v_div_fixup_f32 v240, v248, v240, 1.0
	v_div_fixup_f32 v241, v249, v241, 1.0
	v_div_fixup_f32 v242, v254, v242, 1.0
	v_div_fixup_f32 v243, v255, v243, 1.0
	s_mov_b64 vcc, s[12:13]
	v_pk_mul_f32 v[116:117], v[116:117], v[236:237]
	v_pk_mul_f32 v[112:113], v[112:113], v[238:239]
	v_pk_mul_f32 v[118:119], v[118:119], v[240:241]
	v_pk_mul_f32 v[120:121], v[114:115], v[242:243]
	v_cvt_pk_bf16_f32 v114, v116, v117
	v_cvt_pk_bf16_f32 v115, v118, v119
	v_cvt_pk_bf16_f32 v116, v112, v113
	v_or_b32_e32 v112, 16, v160
	v_mad_i64_i32 v[112:113], s[6:7], v112, s61, v[146:147]
	v_lshl_add_u64 v[112:113], v[112:113], 0, v[148:149]
	v_add_co_u32_e32 v122, vcc, s62, v112
	v_cvt_pk_bf16_f32 v117, v120, v121
	global_store_dwordx4 v[150:151], v[114:117], off offset:256
	s_nop 0
	v_addc_co_u32_e32 v123, vcc, 0, v113, vcc
	s_waitcnt vmcnt(7)
; __device__ __forceinline__ u32x4 pack8(const f32x4 v0, const f32x4 v1) { u32x4 w; w.x = pk2(v0[0], v0[1]); w.y = pk2(v0[2], v0[3]); w.z = pk2(v1[0], v1[1]); w.w = pk2(v1[2], v1[3]); return w; }
; __device__ __forceinline__ void unpack8(const u32x4 w, f32x4& v0, f32x4& v1) { v0 = (f32x4){bflo(w.x), bfhi(w.x), bflo(w.y), bfhi(w.y)}; v1 = (f32x4){bflo(w.z), bfhi(w.z), bflo(w.w), bfhi(w.w)}; }
; __device__ __forceinline__ float sigmoidf_(float x) { return 1.0f / (1.0f + __expf(-x)); }
;     __device__ __forceinline__ void operator()(const f32x4 (&acc)[2][2][4][2], const Unit& u, int wr, int wc, int fr, int fq) const {
;         const int row0 = u.pm * 256 + wr * 64 + fr, col0 = u.pn * 256 + wc * 32 + 8 * fq;
; #pragma unroll
;         for (int ai = 0; ai < 2; ++ai)
; #pragma unroll
;             for (int m = 0; m < 4; ++m) {
;                 bf16_t* rowp = z + (size_t)(row0 + ai * 128 + m * 16) * DIN + col0;
; #pragma unroll
;                 for (int bj = 0; bj < 2; ++bj) {
;                     const u32x4 gw = *(const u32x4*)(rowp + (MODE == 0 ? O_GB : O_GA) + bj * 128);
;                     f32x4 g0, g1; unpack8(gw, g0, g1);
;                     f32x4 v0, v1;
; #pragma unroll
;                     for (int j = 0; j < 4; ++j) { v0[j] = sigmoidf_(g0[j]) * acc[ai][bj][m][0][j]; v1[j] = sigmoidf_(g1[j]) * acc[ai][bj][m][1][j]; }
;                     if (MODE == 1) { const u32x4 mw = *(const u32x4*)(rowp + bj * 128); f32x4 m0, m1; unpack8(mw, m0, m1); v0 += m0; v1 += m1; }
;                     *(u32x4*)(rowp + bj * 128) = pack8(v0, v1); }
	v_mov_b32_e32 v118, v208
	v_mov_b32_e32 v119, v209
	v_mov_b32_e32 v120, v210
	v_mov_b32_e32 v121, v211
	v_add_u32_e32 v199, 0x111a00, v198
	global_load_dwordx4 v[208:211], v199, s[24:25]
	s_mov_b32 s100, 0xbfb8aa3b
	v_lshlrev_b32_e32 v236, 16, v118
	v_and_b32_e32 v237, 0xffff0000, v118
	v_lshlrev_b32_e32 v238, 16, v120
	v_and_b32_e32 v239, 0xffff0000, v120
	v_lshlrev_b32_e32 v240, 16, v119
	v_and_b32_e32 v241, 0xffff0000, v119
	v_lshlrev_b32_e32 v242, 16, v121
	v_and_b32_e32 v243, 0xffff0000, v121
	v_pk_mul_f32 v[236:237], v[236:237], s[100:101] op_sel_hi:[1,0]
	v_pk_mul_f32 v[238:239], v[238:239], s[100:101] op_sel_hi:[1,0]
	v_pk_mul_f32 v[240:241], v[240:241], s[100:101] op_sel_hi:[1,0]
	v_pk_mul_f32 v[242:243], v[242:243], s[100:101] op_sel_hi:[1,0]
	v_exp_f32_e32 v236, v236
	v_exp_f32_e32 v237, v237
	v_exp_f32_e32 v238, v238
	v_exp_f32_e32 v239, v239
	v_exp_f32_e32 v240, v240
	v_exp_f32_e32 v241, v241
	v_exp_f32_e32 v242, v242
	v_exp_f32_e32 v243, v243
	s_nop 0
	v_pk_add_f32 v[236:237], v[236:237], 1.0 op_sel_hi:[1,0]
	v_pk_add_f32 v[238:239], v[238:239], 1.0 op_sel_hi:[1,0]
	v_pk_add_f32 v[240:241], v[240:241], 1.0 op_sel_hi:[1,0]
	v_pk_add_f32 v[242:243], v[242:243], 1.0 op_sel_hi:[1,0]
	v_rcp_f32_e32 v244, v236
	v_rcp_f32_e32 v245, v237
	v_rcp_f32_e32 v250, v238
	v_rcp_f32_e32 v251, v239
	v_pk_fma_f32 v[246:247], v[236:237], v[244:245], 1.0 op_sel_hi:[1,1,0] neg_lo:[1,0,0] neg_hi:[1,0,0]
	v_pk_fma_f32 v[252:253], v[238:239], v[250:251], 1.0 op_sel_hi:[1,1,0] neg_lo:[1,0,0] neg_hi:[1,0,0]
	v_pk_fma_f32 v[244:245], v[246:247], v[244:245], v[244:245]
	v_pk_fma_f32 v[250:251], v[252:253], v[250:251], v[250:251]
	v_pk_fma_f32 v[246:247], v[236:237], v[244:245], 1.0 op_sel_hi:[1,1,0] neg_lo:[1,0,0] neg_hi:[1,0,0]
	v_pk_fma_f32 v[252:253], v[238:239], v[250:251], 1.0 op_sel_hi:[1,1,0] neg_lo:[1,0,0] neg_hi:[1,0,0]
	v_pk_fma_f32 v[248:249], v[246:247], v[244:245], v[244:245]
	v_pk_fma_f32 v[254:255], v[252:253], v[250:251], v[250:251]
	v_pk_fma_f32 v[246:247], v[236:237], v[248:249], 1.0 op_sel_hi:[1,1,0] neg_lo:[1,0,0] neg_hi:[1,0,0]
	v_pk_fma_f32 v[252:253], v[238:239], v[254:255], 1.0 op_sel_hi:[1,1,0] neg_lo:[1,0,0] neg_hi:[1,0,0]
	v_pk_fma_f32 v[248:249], v[246:247], v[244:245], v[248:249]
	v_pk_fma_f32 v[254:255], v[252:253], v[250:251], v[254:255]
	v_div_fixup_f32 v236, v248, v236, 1.0
	v_div_fixup_f32 v237, v249, v237, 1.0
	v_div_fixup_f32 v238, v254, v238, 1.0
	v_div_fixup_f32 v239, v255, v239, 1.0
	v_rcp_f32_e32 v244, v240
	v_rcp_f32_e32 v245, v241
	v_rcp_f32_e32 v250, v242
	v_rcp_f32_e32 v251, v243
	v_pk_fma_f32 v[246:247], v[240:241], v[244:245], 1.0 op_sel_hi:[1,1,0] neg_lo:[1,0,0] neg_hi:[1,0,0]
	v_pk_fma_f32 v[252:253], v[242:243], v[250:251], 1.0 op_sel_hi:[1,1,0] neg_lo:[1,0,0] neg_hi:[1,0,0]
	v_pk_fma_f32 v[244:245], v[246:247], v[244:245], v[244:245]
	v_pk_fma_f32 v[250:251], v[252:253], v[250:251], v[250:251]
	v_pk_fma_f32 v[246:247], v[240:241], v[244:245], 1.0 op_sel_hi:[1,1,0] neg_lo:[1,0,0] neg_hi:[1,0,0]
	v_pk_fma_f32 v[252:253], v[242:243], v[250:251], 1.0 op_sel_hi:[1,1,0] neg_lo:[1,0,0] neg_hi:[1,0,0]
	v_pk_fma_f32 v[248:249], v[246:247], v[244:245], v[244:245]
	v_pk_fma_f32 v[254:255], v[252:253], v[250:251], v[250:251]
	v_pk_fma_f32 v[246:247], v[240:241], v[248:249], 1.0 op_sel_hi:[1,1,0] neg_lo:[1,0,0] neg_hi:[1,0,0]
	v_pk_fma_f32 v[252:253], v[242:243], v[254:255], 1.0 op_sel_hi:[1,1,0] neg_lo:[1,0,0] neg_hi:[1,0,0]
	v_pk_fma_f32 v[248:249], v[246:247], v[244:245], v[248:249]
	v_pk_fma_f32 v[254:255], v[252:253], v[250:251], v[254:255]
	v_div_fixup_f32 v240, v248, v240, 1.0
	v_div_fixup_f32 v241, v249, v241, 1.0
	v_div_fixup_f32 v242, v254, v242, 1.0
	v_div_fixup_f32 v243, v255, v243, 1.0
	v_mul_f32_e32 v108, v108, v236
	v_mul_f32_e32 v114, v104, v238
	v_mul_f32_e32 v104, v109, v237
	v_mul_f32_e32 v109, v105, v239
	v_mul_f32_e32 v105, v110, v240
	v_mul_f32_e32 v110, v106, v242
	v_mul_f32_e32 v106, v111, v241
	v_mul_f32_e32 v107, v107, v243
	v_cvt_pk_bf16_f32 v104, v108, v104
	v_cvt_pk_bf16_f32 v105, v105, v106
	v_cvt_pk_bf16_f32 v106, v114, v109
	v_cvt_pk_bf16_f32 v107, v110, v107
	s_waitcnt vmcnt(7)
	v_mov_b32_e32 v108, v212
	v_mov_b32_e32 v109, v213
	v_mov_b32_e32 v110, v214
	v_mov_b32_e32 v111, v215
	v_add_u32_e32 v199, 0x111b00, v198
	global_load_dwordx4 v[212:215], v199, s[24:25]
	s_mov_b32 s100, 0xbfb8aa3b
	v_lshlrev_b32_e32 v236, 16, v108
	v_and_b32_e32 v237, 0xffff0000, v108
	v_lshlrev_b32_e32 v238, 16, v110
	v_and_b32_e32 v239, 0xffff0000, v110
	v_lshlrev_b32_e32 v240, 16, v109
	v_and_b32_e32 v241, 0xffff0000, v109
	v_lshlrev_b32_e32 v242, 16, v111
	v_and_b32_e32 v243, 0xffff0000, v111
	v_pk_mul_f32 v[236:237], v[236:237], s[100:101] op_sel_hi:[1,0]
	v_pk_mul_f32 v[238:239], v[238:239], s[100:101] op_sel_hi:[1,0]
	v_pk_mul_f32 v[240:241], v[240:241], s[100:101] op_sel_hi:[1,0]
	v_pk_mul_f32 v[242:243], v[242:243], s[100:101] op_sel_hi:[1,0]
	v_exp_f32_e32 v236, v236
	v_exp_f32_e32 v237, v237
	v_exp_f32_e32 v238, v238
	v_exp_f32_e32 v239, v239
	v_exp_f32_e32 v240, v240
	v_exp_f32_e32 v241, v241
	v_exp_f32_e32 v242, v242
	v_exp_f32_e32 v243, v243
	s_nop 0
	v_pk_add_f32 v[236:237], v[236:237], 1.0 op_sel_hi:[1,0]
	v_pk_add_f32 v[238:239], v[238:239], 1.0 op_sel_hi:[1,0]
	v_pk_add_f32 v[240:241], v[240:241], 1.0 op_sel_hi:[1,0]
	v_pk_add_f32 v[242:243], v[242:243], 1.0 op_sel_hi:[1,0]
	v_rcp_f32_e32 v244, v236
	v_rcp_f32_e32 v245, v237
	v_rcp_f32_e32 v250, v238
	v_rcp_f32_e32 v251, v239
	v_pk_fma_f32 v[246:247], v[236:237], v[244:245], 1.0 op_sel_hi:[1,1,0] neg_lo:[1,0,0] neg_hi:[1,0,0]
	v_pk_fma_f32 v[252:253], v[238:239], v[250:251], 1.0 op_sel_hi:[1,1,0] neg_lo:[1,0,0] neg_hi:[1,0,0]
; __device__ __forceinline__ u32x4 pack8(const f32x4 v0, const f32x4 v1) { u32x4 w; w.x = pk2(v0[0], v0[1]); w.y = pk2(v0[2], v0[3]); w.z = pk2(v1[0], v1[1]); w.w = pk2(v1[2], v1[3]); return w; }
; __device__ __forceinline__ void unpack8(const u32x4 w, f32x4& v0, f32x4& v1) { v0 = (f32x4){bflo(w.x), bfhi(w.x), bflo(w.y), bfhi(w.y)}; v1 = (f32x4){bflo(w.z), bfhi(w.z), bflo(w.w), bfhi(w.w)}; }
; __device__ __forceinline__ float sigmoidf_(float x) { return 1.0f / (1.0f + __expf(-x)); }
;     __device__ __forceinline__ void operator()(const f32x4 (&acc)[2][2][4][2], const Unit& u, int wr, int wc, int fr, int fq) const {
;         const int row0 = u.pm * 256 + wr * 64 + fr, col0 = u.pn * 256 + wc * 32 + 8 * fq;
; #pragma unroll
;         for (int ai = 0; ai < 2; ++ai)
; #pragma unroll
;             for (int m = 0; m < 4; ++m) {
;                 bf16_t* rowp = z + (size_t)(row0 + ai * 128 + m * 16) * DIN + col0;
; #pragma unroll
;                 for (int bj = 0; bj < 2; ++bj) {
;                     const u32x4 gw = *(const u32x4*)(rowp + (MODE == 0 ? O_GB : O_GA) + bj * 128);
;                     f32x4 g0, g1; unpack8(gw, g0, g1);
;                     f32x4 v0, v1;
; #pragma unroll
;                     for (int j = 0; j < 4; ++j) { v0[j] = sigmoidf_(g0[j]) * acc[ai][bj][m][0][j]; v1[j] = sigmoidf_(g1[j]) * acc[ai][bj][m][1][j]; }
;                     if (MODE == 1) { const u32x4 mw = *(const u32x4*)(rowp + bj * 128); f32x4 m0, m1; unpack8(mw, m0, m1); v0 += m0; v1 += m1; }
;                     *(u32x4*)(rowp + bj * 128) = pack8(v0, v1); }
	v_pk_fma_f32 v[244:245], v[246:247], v[244:245], v[244:245]
	v_pk_fma_f32 v[250:251], v[252:253], v[250:251], v[250:251]
	v_pk_fma_f32 v[246:247], v[236:237], v[244:245], 1.0 op_sel_hi:[1,1,0] neg_lo:[1,0,0] neg_hi:[1,0,0]
	v_pk_fma_f32 v[252:253], v[238:239], v[250:251], 1.0 op_sel_hi:[1,1,0] neg_lo:[1,0,0] neg_hi:[1,0,0]
	v_pk_fma_f32 v[248:249], v[246:247], v[244:245], v[244:245]
	v_pk_fma_f32 v[254:255], v[252:253], v[250:251], v[250:251]
	v_pk_fma_f32 v[246:247], v[236:237], v[248:249], 1.0 op_sel_hi:[1,1,0] neg_lo:[1,0,0] neg_hi:[1,0,0]
	v_pk_fma_f32 v[252:253], v[238:239], v[254:255], 1.0 op_sel_hi:[1,1,0] neg_lo:[1,0,0] neg_hi:[1,0,0]
	v_pk_fma_f32 v[248:249], v[246:247], v[244:245], v[248:249]
	v_pk_fma_f32 v[254:255], v[252:253], v[250:251], v[254:255]
	v_div_fixup_f32 v236, v248, v236, 1.0
	v_div_fixup_f32 v237, v249, v237, 1.0
	v_div_fixup_f32 v238, v254, v238, 1.0
	v_div_fixup_f32 v239, v255, v239, 1.0
	v_rcp_f32_e32 v244, v240
	v_rcp_f32_e32 v245, v241
	v_rcp_f32_e32 v250, v242
	v_rcp_f32_e32 v251, v243
	v_pk_fma_f32 v[246:247], v[240:241], v[244:245], 1.0 op_sel_hi:[1,1,0] neg_lo:[1,0,0] neg_hi:[1,0,0]
	v_pk_fma_f32 v[252:253], v[242:243], v[250:251], 1.0 op_sel_hi:[1,1,0] neg_lo:[1,0,0] neg_hi:[1,0,0]
	v_pk_fma_f32 v[244:245], v[246:247], v[244:245], v[244:245]
	v_pk_fma_f32 v[250:251], v[252:253], v[250:251], v[250:251]
	v_pk_fma_f32 v[246:247], v[240:241], v[244:245], 1.0 op_sel_hi:[1,1,0] neg_lo:[1,0,0] neg_hi:[1,0,0]
	v_pk_fma_f32 v[252:253], v[242:243], v[250:251], 1.0 op_sel_hi:[1,1,0] neg_lo:[1,0,0] neg_hi:[1,0,0]
	v_pk_fma_f32 v[248:249], v[246:247], v[244:245], v[244:245]
	v_pk_fma_f32 v[254:255], v[252:253], v[250:251], v[250:251]
	v_pk_fma_f32 v[246:247], v[240:241], v[248:249], 1.0 op_sel_hi:[1,1,0] neg_lo:[1,0,0] neg_hi:[1,0,0]
	v_pk_fma_f32 v[252:253], v[242:243], v[254:255], 1.0 op_sel_hi:[1,1,0] neg_lo:[1,0,0] neg_hi:[1,0,0]
	v_pk_fma_f32 v[248:249], v[246:247], v[244:245], v[248:249]
	v_pk_fma_f32 v[254:255], v[252:253], v[250:251], v[254:255]
	v_div_fixup_f32 v240, v248, v240, 1.0
	v_div_fixup_f32 v241, v249, v241, 1.0
	v_div_fixup_f32 v242, v254, v242, 1.0
	v_div_fixup_f32 v243, v255, v243, 1.0
	global_store_dwordx4 v[112:113], v[104:107], off
	s_nop 0
	v_pk_mul_f32 v[100:101], v[100:101], v[236:237]
	v_pk_mul_f32 v[96:97], v[96:97], v[238:239]
	v_pk_mul_f32 v[102:103], v[102:103], v[240:241]
	v_pk_mul_f32 v[104:105], v[98:99], v[242:243]
	v_cvt_pk_bf16_f32 v98, v100, v101
	v_cvt_pk_bf16_f32 v99, v102, v103
	v_cvt_pk_bf16_f32 v100, v96, v97
	v_or_b32_e32 v96, 32, v160
	v_mad_i64_i32 v[96:97], s[6:7], v96, s61, v[146:147]
	v_lshl_add_u64 v[96:97], v[96:97], 0, v[148:149]
	v_add_co_u32_e32 v106, vcc, s62, v96
	v_cvt_pk_bf16_f32 v101, v104, v105
	global_store_dwordx4 v[112:113], v[98:101], off offset:256
	s_nop 0
	v_addc_co_u32_e32 v107, vcc, 0, v97, vcc
	s_waitcnt vmcnt(9)
	v_mov_b32_e32 v102, v216
	v_mov_b32_e32 v103, v217
	v_mov_b32_e32 v104, v218
	v_mov_b32_e32 v105, v219
	v_add_u32_e32 v199, 0x133a00, v198
	global_load_dwordx4 v[216:219], v199, s[24:25]
	s_mov_b32 s100, 0xbfb8aa3b
	v_lshlrev_b32_e32 v236, 16, v102
	v_and_b32_e32 v237, 0xffff0000, v102
	v_lshlrev_b32_e32 v238, 16, v104
	v_and_b32_e32 v239, 0xffff0000, v104
	v_lshlrev_b32_e32 v240, 16, v103
	v_and_b32_e32 v241, 0xffff0000, v103
	v_lshlrev_b32_e32 v242, 16, v105
	v_and_b32_e32 v243, 0xffff0000, v105
	v_pk_mul_f32 v[236:237], v[236:237], s[100:101] op_sel_hi:[1,0]
	v_pk_mul_f32 v[238:239], v[238:239], s[100:101] op_sel_hi:[1,0]
	v_pk_mul_f32 v[240:241], v[240:241], s[100:101] op_sel_hi:[1,0]
	v_pk_mul_f32 v[242:243], v[242:243], s[100:101] op_sel_hi:[1,0]
	v_exp_f32_e32 v236, v236
	v_exp_f32_e32 v237, v237
	v_exp_f32_e32 v238, v238
	v_exp_f32_e32 v239, v239
	v_exp_f32_e32 v240, v240
	v_exp_f32_e32 v241, v241
	v_exp_f32_e32 v242, v242
	v_exp_f32_e32 v243, v243
	s_nop 0
	v_pk_add_f32 v[236:237], v[236:237], 1.0 op_sel_hi:[1,0]
	v_pk_add_f32 v[238:239], v[238:239], 1.0 op_sel_hi:[1,0]
	v_pk_add_f32 v[240:241], v[240:241], 1.0 op_sel_hi:[1,0]
	v_pk_add_f32 v[242:243], v[242:243], 1.0 op_sel_hi:[1,0]
	v_rcp_f32_e32 v244, v236
	v_rcp_f32_e32 v245, v237
	v_rcp_f32_e32 v250, v238
	v_rcp_f32_e32 v251, v239
	v_pk_fma_f32 v[246:247], v[236:237], v[244:245], 1.0 op_sel_hi:[1,1,0] neg_lo:[1,0,0] neg_hi:[1,0,0]
	v_pk_fma_f32 v[252:253], v[238:239], v[250:251], 1.0 op_sel_hi:[1,1,0] neg_lo:[1,0,0] neg_hi:[1,0,0]
	v_pk_fma_f32 v[244:245], v[246:247], v[244:245], v[244:245]
	v_pk_fma_f32 v[250:251], v[252:253], v[250:251], v[250:251]
	v_pk_fma_f32 v[246:247], v[236:237], v[244:245], 1.0 op_sel_hi:[1,1,0] neg_lo:[1,0,0] neg_hi:[1,0,0]
	v_pk_fma_f32 v[252:253], v[238:239], v[250:251], 1.0 op_sel_hi:[1,1,0] neg_lo:[1,0,0] neg_hi:[1,0,0]
	v_pk_fma_f32 v[248:249], v[246:247], v[244:245], v[244:245]
	v_pk_fma_f32 v[254:255], v[252:253], v[250:251], v[250:251]
	v_pk_fma_f32 v[246:247], v[236:237], v[248:249], 1.0 op_sel_hi:[1,1,0] neg_lo:[1,0,0] neg_hi:[1,0,0]
	v_pk_fma_f32 v[252:253], v[238:239], v[254:255], 1.0 op_sel_hi:[1,1,0] neg_lo:[1,0,0] neg_hi:[1,0,0]
	v_pk_fma_f32 v[248:249], v[246:247], v[244:245], v[248:249]
	v_pk_fma_f32 v[254:255], v[252:253], v[250:251], v[254:255]
	v_div_fixup_f32 v236, v248, v236, 1.0
	v_div_fixup_f32 v237, v249, v237, 1.0
	v_div_fixup_f32 v238, v254, v238, 1.0
	v_div_fixup_f32 v239, v255, v239, 1.0
	v_rcp_f32_e32 v244, v240
	v_rcp_f32_e32 v245, v241
	v_rcp_f32_e32 v250, v242
	v_rcp_f32_e32 v251, v243
	v_pk_fma_f32 v[246:247], v[240:241], v[244:245], 1.0 op_sel_hi:[1,1,0] neg_lo:[1,0,0] neg_hi:[1,0,0]
	v_pk_fma_f32 v[252:253], v[242:243], v[250:251], 1.0 op_sel_hi:[1,1,0] neg_lo:[1,0,0] neg_hi:[1,0,0]
	v_pk_fma_f32 v[244:245], v[246:247], v[244:245], v[244:245]
	v_pk_fma_f32 v[250:251], v[252:253], v[250:251], v[250:251]
	v_pk_fma_f32 v[246:247], v[240:241], v[244:245], 1.0 op_sel_hi:[1,1,0] neg_lo:[1,0,0] neg_hi:[1,0,0]
	v_pk_fma_f32 v[252:253], v[242:243], v[250:251], 1.0 op_sel_hi:[1,1,0] neg_lo:[1,0,0] neg_hi:[1,0,0]
	v_pk_fma_f32 v[248:249], v[246:247], v[244:245], v[244:245]
	v_pk_fma_f32 v[254:255], v[252:253], v[250:251], v[250:251]
	v_pk_fma_f32 v[246:247], v[240:241], v[248:249], 1.0 op_sel_hi:[1,1,0] neg_lo:[1,0,0] neg_hi:[1,0,0]
	v_pk_fma_f32 v[252:253], v[242:243], v[254:255], 1.0 op_sel_hi:[1,1,0] neg_lo:[1,0,0] neg_hi:[1,0,0]
	v_pk_fma_f32 v[248:249], v[246:247], v[244:245], v[248:249]
	v_pk_fma_f32 v[254:255], v[252:253], v[250:251], v[254:255]
	v_div_fixup_f32 v240, v248, v240, 1.0
	v_div_fixup_f32 v241, v249, v241, 1.0
	v_div_fixup_f32 v242, v254, v242, 1.0
	v_div_fixup_f32 v243, v255, v243, 1.0
	v_mul_f32_e32 v92, v92, v236
	v_mul_f32_e32 v98, v88, v238
	v_mul_f32_e32 v88, v93, v237
	v_mul_f32_e32 v93, v89, v239
	v_mul_f32_e32 v89, v94, v240
	v_mul_f32_e32 v94, v90, v242
	v_mul_f32_e32 v90, v95, v241
	v_mul_f32_e32 v91, v91, v243
	v_cvt_pk_bf16_f32 v88, v92, v88
	v_cvt_pk_bf16_f32 v89, v89, v90
	v_cvt_pk_bf16_f32 v90, v98, v93
	v_cvt_pk_bf16_f32 v91, v94, v91
	s_waitcnt vmcnt(9)
; __device__ __forceinline__ u32x4 pack8(const f32x4 v0, const f32x4 v1) { u32x4 w; w.x = pk2(v0[0], v0[1]); w.y = pk2(v0[2], v0[3]); w.z = pk2(v1[0], v1[1]); w.w = pk2(v1[2], v1[3]); return w; }
; __device__ __forceinline__ void unpack8(const u32x4 w, f32x4& v0, f32x4& v1) { v0 = (f32x4){bflo(w.x), bfhi(w.x), bflo(w.y), bfhi(w.y)}; v1 = (f32x4){bflo(w.z), bfhi(w.z), bflo(w.w), bfhi(w.w)}; }
; __device__ __forceinline__ float sigmoidf_(float x) { return 1.0f / (1.0f + __expf(-x)); }
;     __device__ __forceinline__ void operator()(const f32x4 (&acc)[2][2][4][2], const Unit& u, int wr, int wc, int fr, int fq) const {
;         const int row0 = u.pm * 256 + wr * 64 + fr, col0 = u.pn * 256 + wc * 32 + 8 * fq;
; #pragma unroll
;         for (int ai = 0; ai < 2; ++ai)
; #pragma unroll
;             for (int m = 0; m < 4; ++m) {
;                 bf16_t* rowp = z + (size_t)(row0 + ai * 128 + m * 16) * DIN + col0;
; #pragma unroll
;                 for (int bj = 0; bj < 2; ++bj) {
;                     const u32x4 gw = *(const u32x4*)(rowp + (MODE == 0 ? O_GB : O_GA) + bj * 128);
;                     f32x4 g0, g1; unpack8(gw, g0, g1);
;                     f32x4 v0, v1;
; #pragma unroll
;                     for (int j = 0; j < 4; ++j) { v0[j] = sigmoidf_(g0[j]) * acc[ai][bj][m][0][j]; v1[j] = sigmoidf_(g1[j]) * acc[ai][bj][m][1][j]; }
;                     if (MODE == 1) { const u32x4 mw = *(const u32x4*)(rowp + bj * 128); f32x4 m0, m1; unpack8(mw, m0, m1); v0 += m0; v1 += m1; }
;                     *(u32x4*)(rowp + bj * 128) = pack8(v0, v1); }
	v_mov_b32_e32 v92, v232
	v_mov_b32_e32 v93, v233
	v_mov_b32_e32 v94, v234
	v_mov_b32_e32 v95, v235
	v_add_u32_e32 v199, 0x133b00, v198
	global_load_dwordx4 v[232:235], v199, s[24:25]
	s_mov_b32 s100, 0xbfb8aa3b
	v_lshlrev_b32_e32 v236, 16, v92
	v_and_b32_e32 v237, 0xffff0000, v92
	v_lshlrev_b32_e32 v238, 16, v94
	v_and_b32_e32 v239, 0xffff0000, v94
	v_lshlrev_b32_e32 v240, 16, v93
	v_and_b32_e32 v241, 0xffff0000, v93
	v_lshlrev_b32_e32 v242, 16, v95
	v_and_b32_e32 v243, 0xffff0000, v95
	v_pk_mul_f32 v[236:237], v[236:237], s[100:101] op_sel_hi:[1,0]
	v_pk_mul_f32 v[238:239], v[238:239], s[100:101] op_sel_hi:[1,0]
	v_pk_mul_f32 v[240:241], v[240:241], s[100:101] op_sel_hi:[1,0]
	v_pk_mul_f32 v[242:243], v[242:243], s[100:101] op_sel_hi:[1,0]
	v_exp_f32_e32 v236, v236
	v_exp_f32_e32 v237, v237
	v_exp_f32_e32 v238, v238
	v_exp_f32_e32 v239, v239
	v_exp_f32_e32 v240, v240
	v_exp_f32_e32 v241, v241
	v_exp_f32_e32 v242, v242
	v_exp_f32_e32 v243, v243
	s_nop 0
	v_pk_add_f32 v[236:237], v[236:237], 1.0 op_sel_hi:[1,0]
	v_pk_add_f32 v[238:239], v[238:239], 1.0 op_sel_hi:[1,0]
	v_pk_add_f32 v[240:241], v[240:241], 1.0 op_sel_hi:[1,0]
	v_pk_add_f32 v[242:243], v[242:243], 1.0 op_sel_hi:[1,0]
	v_rcp_f32_e32 v244, v236
	v_rcp_f32_e32 v245, v237
	v_rcp_f32_e32 v250, v238
	v_rcp_f32_e32 v251, v239
	v_pk_fma_f32 v[246:247], v[236:237], v[244:245], 1.0 op_sel_hi:[1,1,0] neg_lo:[1,0,0] neg_hi:[1,0,0]
	v_pk_fma_f32 v[252:253], v[238:239], v[250:251], 1.0 op_sel_hi:[1,1,0] neg_lo:[1,0,0] neg_hi:[1,0,0]
	v_pk_fma_f32 v[244:245], v[246:247], v[244:245], v[244:245]
	v_pk_fma_f32 v[250:251], v[252:253], v[250:251], v[250:251]
	v_pk_fma_f32 v[246:247], v[236:237], v[244:245], 1.0 op_sel_hi:[1,1,0] neg_lo:[1,0,0] neg_hi:[1,0,0]
	v_pk_fma_f32 v[252:253], v[238:239], v[250:251], 1.0 op_sel_hi:[1,1,0] neg_lo:[1,0,0] neg_hi:[1,0,0]
	v_pk_fma_f32 v[248:249], v[246:247], v[244:245], v[244:245]
	v_pk_fma_f32 v[254:255], v[252:253], v[250:251], v[250:251]
	v_pk_fma_f32 v[246:247], v[236:237], v[248:249], 1.0 op_sel_hi:[1,1,0] neg_lo:[1,0,0] neg_hi:[1,0,0]
	v_pk_fma_f32 v[252:253], v[238:239], v[254:255], 1.0 op_sel_hi:[1,1,0] neg_lo:[1,0,0] neg_hi:[1,0,0]
	v_pk_fma_f32 v[248:249], v[246:247], v[244:245], v[248:249]
	v_pk_fma_f32 v[254:255], v[252:253], v[250:251], v[254:255]
	v_div_fixup_f32 v236, v248, v236, 1.0
	v_div_fixup_f32 v237, v249, v237, 1.0
	v_div_fixup_f32 v238, v254, v238, 1.0
	v_div_fixup_f32 v239, v255, v239, 1.0
	v_rcp_f32_e32 v244, v240
	v_rcp_f32_e32 v245, v241
	v_rcp_f32_e32 v250, v242
	v_rcp_f32_e32 v251, v243
	v_pk_fma_f32 v[246:247], v[240:241], v[244:245], 1.0 op_sel_hi:[1,1,0] neg_lo:[1,0,0] neg_hi:[1,0,0]
	v_pk_fma_f32 v[252:253], v[242:243], v[250:251], 1.0 op_sel_hi:[1,1,0] neg_lo:[1,0,0] neg_hi:[1,0,0]
	v_pk_fma_f32 v[244:245], v[246:247], v[244:245], v[244:245]
	v_pk_fma_f32 v[250:251], v[252:253], v[250:251], v[250:251]
	v_pk_fma_f32 v[246:247], v[240:241], v[244:245], 1.0 op_sel_hi:[1,1,0] neg_lo:[1,0,0] neg_hi:[1,0,0]
	v_pk_fma_f32 v[252:253], v[242:243], v[250:251], 1.0 op_sel_hi:[1,1,0] neg_lo:[1,0,0] neg_hi:[1,0,0]
	v_pk_fma_f32 v[248:249], v[246:247], v[244:245], v[244:245]
	v_pk_fma_f32 v[254:255], v[252:253], v[250:251], v[250:251]
	v_pk_fma_f32 v[246:247], v[240:241], v[248:249], 1.0 op_sel_hi:[1,1,0] neg_lo:[1,0,0] neg_hi:[1,0,0]
	v_pk_fma_f32 v[252:253], v[242:243], v[254:255], 1.0 op_sel_hi:[1,1,0] neg_lo:[1,0,0] neg_hi:[1,0,0]
	v_pk_fma_f32 v[248:249], v[246:247], v[244:245], v[248:249]
	v_pk_fma_f32 v[254:255], v[252:253], v[250:251], v[254:255]
	v_div_fixup_f32 v240, v248, v240, 1.0
	v_div_fixup_f32 v241, v249, v241, 1.0
	v_div_fixup_f32 v242, v254, v242, 1.0
	v_div_fixup_f32 v243, v255, v243, 1.0
	global_store_dwordx4 v[96:97], v[88:91], off
	s_nop 0
	v_pk_mul_f32 v[84:85], v[84:85], v[236:237]
	v_pk_mul_f32 v[80:81], v[80:81], v[238:239]
	v_pk_mul_f32 v[86:87], v[86:87], v[240:241]
	v_pk_mul_f32 v[88:89], v[82:83], v[242:243]
	v_cvt_pk_bf16_f32 v82, v84, v85
	v_cvt_pk_bf16_f32 v83, v86, v87
	v_cvt_pk_bf16_f32 v84, v80, v81
	v_or_b32_e32 v80, 48, v160
	v_mad_i64_i32 v[80:81], s[6:7], v80, s61, v[146:147]
	v_lshl_add_u64 v[80:81], v[80:81], 0, v[148:149]
	v_add_co_u32_e32 v90, vcc, s62, v80
	v_cvt_pk_bf16_f32 v85, v88, v89
	global_store_dwordx4 v[96:97], v[82:85], off offset:256
	s_nop 0
	v_addc_co_u32_e32 v91, vcc, 0, v81, vcc
	s_waitcnt vmcnt(11)
; __device__ __forceinline__ u32x4 pack8(const f32x4 v0, const f32x4 v1) { u32x4 w; w.x = pk2(v0[0], v0[1]); w.y = pk2(v0[2], v0[3]); w.z = pk2(v1[0], v1[1]); w.w = pk2(v1[2], v1[3]); return w; }
; __device__ __forceinline__ void unpack8(const u32x4 w, f32x4& v0, f32x4& v1) { v0 = (f32x4){bflo(w.x), bfhi(w.x), bflo(w.y), bfhi(w.y)}; v1 = (f32x4){bflo(w.z), bfhi(w.z), bflo(w.w), bfhi(w.w)}; }
; __device__ __forceinline__ float sigmoidf_(float x) { return 1.0f / (1.0f + __expf(-x)); }
;     __device__ __forceinline__ void operator()(const f32x4 (&acc)[2][2][4][2], const Unit& u, int wr, int wc, int fr, int fq) const {
;         const int row0 = u.pm * 256 + wr * 64 + fr, col0 = u.pn * 256 + wc * 32 + 8 * fq;
; #pragma unroll
;         for (int ai = 0; ai < 2; ++ai)
; #pragma unroll
;             for (int m = 0; m < 4; ++m) {
;                 bf16_t* rowp = z + (size_t)(row0 + ai * 128 + m * 16) * DIN + col0;
; #pragma unroll
;                 for (int bj = 0; bj < 2; ++bj) {
;                     const u32x4 gw = *(const u32x4*)(rowp + (MODE == 0 ? O_GB : O_GA) + bj * 128);
;                     f32x4 g0, g1; unpack8(gw, g0, g1);
;                     f32x4 v0, v1;
; #pragma unroll
;                     for (int j = 0; j < 4; ++j) { v0[j] = sigmoidf_(g0[j]) * acc[ai][bj][m][0][j]; v1[j] = sigmoidf_(g1[j]) * acc[ai][bj][m][1][j]; }
;                     if (MODE == 1) { const u32x4 mw = *(const u32x4*)(rowp + bj * 128); f32x4 m0, m1; unpack8(mw, m0, m1); v0 += m0; v1 += m1; }
;                     *(u32x4*)(rowp + bj * 128) = pack8(v0, v1); }
	v_mov_b32_e32 v86, v200
	v_mov_b32_e32 v87, v201
	v_mov_b32_e32 v88, v202
	v_mov_b32_e32 v89, v203
	v_add_u32_e32 v199, 0x155a00, v198
	global_load_dwordx4 v[200:203], v199, s[24:25]
	s_mov_b32 s100, 0xbfb8aa3b
	v_lshlrev_b32_e32 v236, 16, v86
	v_and_b32_e32 v237, 0xffff0000, v86
	v_lshlrev_b32_e32 v238, 16, v88
	v_and_b32_e32 v239, 0xffff0000, v88
	v_lshlrev_b32_e32 v240, 16, v87
	v_and_b32_e32 v241, 0xffff0000, v87
	v_lshlrev_b32_e32 v242, 16, v89
	v_and_b32_e32 v243, 0xffff0000, v89
	v_pk_mul_f32 v[236:237], v[236:237], s[100:101] op_sel_hi:[1,0]
	v_pk_mul_f32 v[238:239], v[238:239], s[100:101] op_sel_hi:[1,0]
	v_pk_mul_f32 v[240:241], v[240:241], s[100:101] op_sel_hi:[1,0]
	v_pk_mul_f32 v[242:243], v[242:243], s[100:101] op_sel_hi:[1,0]
	v_exp_f32_e32 v236, v236
	v_exp_f32_e32 v237, v237
	v_exp_f32_e32 v238, v238
	v_exp_f32_e32 v239, v239
	v_exp_f32_e32 v240, v240
	v_exp_f32_e32 v241, v241
	v_exp_f32_e32 v242, v242
	v_exp_f32_e32 v243, v243
	s_nop 0
	v_pk_add_f32 v[236:237], v[236:237], 1.0 op_sel_hi:[1,0]
	v_pk_add_f32 v[238:239], v[238:239], 1.0 op_sel_hi:[1,0]
	v_pk_add_f32 v[240:241], v[240:241], 1.0 op_sel_hi:[1,0]
	v_pk_add_f32 v[242:243], v[242:243], 1.0 op_sel_hi:[1,0]
	v_rcp_f32_e32 v244, v236
	v_rcp_f32_e32 v245, v237
	v_rcp_f32_e32 v250, v238
	v_rcp_f32_e32 v251, v239
	v_pk_fma_f32 v[246:247], v[236:237], v[244:245], 1.0 op_sel_hi:[1,1,0] neg_lo:[1,0,0] neg_hi:[1,0,0]
	v_pk_fma_f32 v[252:253], v[238:239], v[250:251], 1.0 op_sel_hi:[1,1,0] neg_lo:[1,0,0] neg_hi:[1,0,0]
	v_pk_fma_f32 v[244:245], v[246:247], v[244:245], v[244:245]
	v_pk_fma_f32 v[250:251], v[252:253], v[250:251], v[250:251]
	v_pk_fma_f32 v[246:247], v[236:237], v[244:245], 1.0 op_sel_hi:[1,1,0] neg_lo:[1,0,0] neg_hi:[1,0,0]
	v_pk_fma_f32 v[252:253], v[238:239], v[250:251], 1.0 op_sel_hi:[1,1,0] neg_lo:[1,0,0] neg_hi:[1,0,0]
	v_pk_fma_f32 v[248:249], v[246:247], v[244:245], v[244:245]
	v_pk_fma_f32 v[254:255], v[252:253], v[250:251], v[250:251]
	v_pk_fma_f32 v[246:247], v[236:237], v[248:249], 1.0 op_sel_hi:[1,1,0] neg_lo:[1,0,0] neg_hi:[1,0,0]
	v_pk_fma_f32 v[252:253], v[238:239], v[254:255], 1.0 op_sel_hi:[1,1,0] neg_lo:[1,0,0] neg_hi:[1,0,0]
	v_pk_fma_f32 v[248:249], v[246:247], v[244:245], v[248:249]
	v_pk_fma_f32 v[254:255], v[252:253], v[250:251], v[254:255]
	v_div_fixup_f32 v236, v248, v236, 1.0
	v_div_fixup_f32 v237, v249, v237, 1.0
	v_div_fixup_f32 v238, v254, v238, 1.0
	v_div_fixup_f32 v239, v255, v239, 1.0
	v_rcp_f32_e32 v244, v240
	v_rcp_f32_e32 v245, v241
	v_rcp_f32_e32 v250, v242
	v_rcp_f32_e32 v251, v243
	v_pk_fma_f32 v[246:247], v[240:241], v[244:245], 1.0 op_sel_hi:[1,1,0] neg_lo:[1,0,0] neg_hi:[1,0,0]
	v_pk_fma_f32 v[252:253], v[242:243], v[250:251], 1.0 op_sel_hi:[1,1,0] neg_lo:[1,0,0] neg_hi:[1,0,0]
	v_pk_fma_f32 v[244:245], v[246:247], v[244:245], v[244:245]
	v_pk_fma_f32 v[250:251], v[252:253], v[250:251], v[250:251]
	v_pk_fma_f32 v[246:247], v[240:241], v[244:245], 1.0 op_sel_hi:[1,1,0] neg_lo:[1,0,0] neg_hi:[1,0,0]
	v_pk_fma_f32 v[252:253], v[242:243], v[250:251], 1.0 op_sel_hi:[1,1,0] neg_lo:[1,0,0] neg_hi:[1,0,0]
	v_pk_fma_f32 v[248:249], v[246:247], v[244:245], v[244:245]
	v_pk_fma_f32 v[254:255], v[252:253], v[250:251], v[250:251]
	v_pk_fma_f32 v[246:247], v[240:241], v[248:249], 1.0 op_sel_hi:[1,1,0] neg_lo:[1,0,0] neg_hi:[1,0,0]
	v_pk_fma_f32 v[252:253], v[242:243], v[254:255], 1.0 op_sel_hi:[1,1,0] neg_lo:[1,0,0] neg_hi:[1,0,0]
	v_pk_fma_f32 v[248:249], v[246:247], v[244:245], v[248:249]
	v_pk_fma_f32 v[254:255], v[252:253], v[250:251], v[254:255]
	v_div_fixup_f32 v240, v248, v240, 1.0
	v_div_fixup_f32 v241, v249, v241, 1.0
	v_div_fixup_f32 v242, v254, v242, 1.0
	v_div_fixup_f32 v243, v255, v243, 1.0
	v_mul_f32_e32 v76, v76, v236
	v_mul_f32_e32 v82, v72, v238
	v_mul_f32_e32 v72, v77, v237
	v_mul_f32_e32 v77, v73, v239
	v_mul_f32_e32 v73, v78, v240
	v_mul_f32_e32 v78, v74, v242
	v_mul_f32_e32 v74, v79, v241
	v_mul_f32_e32 v75, v75, v243
	v_cvt_pk_bf16_f32 v72, v76, v72
	v_cvt_pk_bf16_f32 v73, v73, v74
	v_cvt_pk_bf16_f32 v74, v82, v77
	v_cvt_pk_bf16_f32 v75, v78, v75
	s_waitcnt vmcnt(10)
	v_mov_b32_e32 v76, v204
	v_mov_b32_e32 v77, v205
	v_mov_b32_e32 v78, v206
	v_mov_b32_e32 v79, v207
	v_add_u32_e32 v199, 0x155b00, v198
	global_load_dwordx4 v[204:207], v199, s[24:25]
	s_mov_b32 s100, 0xbfb8aa3b
	v_lshlrev_b32_e32 v236, 16, v76
	v_and_b32_e32 v237, 0xffff0000, v76
	v_lshlrev_b32_e32 v238, 16, v78
	v_and_b32_e32 v239, 0xffff0000, v78
	v_lshlrev_b32_e32 v240, 16, v77
	v_and_b32_e32 v241, 0xffff0000, v77
	v_lshlrev_b32_e32 v242, 16, v79
	v_and_b32_e32 v243, 0xffff0000, v79
	v_pk_mul_f32 v[236:237], v[236:237], s[100:101] op_sel_hi:[1,0]
	v_pk_mul_f32 v[238:239], v[238:239], s[100:101] op_sel_hi:[1,0]
	v_pk_mul_f32 v[240:241], v[240:241], s[100:101] op_sel_hi:[1,0]
	v_pk_mul_f32 v[242:243], v[242:243], s[100:101] op_sel_hi:[1,0]
	v_exp_f32_e32 v236, v236
	v_exp_f32_e32 v237, v237
	v_exp_f32_e32 v238, v238
	v_exp_f32_e32 v239, v239
	v_exp_f32_e32 v240, v240
	v_exp_f32_e32 v241, v241
	v_exp_f32_e32 v242, v242
	v_exp_f32_e32 v243, v243
	s_nop 0
	v_pk_add_f32 v[236:237], v[236:237], 1.0 op_sel_hi:[1,0]
	v_pk_add_f32 v[238:239], v[238:239], 1.0 op_sel_hi:[1,0]
	v_pk_add_f32 v[240:241], v[240:241], 1.0 op_sel_hi:[1,0]
	v_pk_add_f32 v[242:243], v[242:243], 1.0 op_sel_hi:[1,0]
	v_rcp_f32_e32 v244, v236
	v_rcp_f32_e32 v245, v237
	v_rcp_f32_e32 v250, v238
	v_rcp_f32_e32 v251, v239
	v_pk_fma_f32 v[246:247], v[236:237], v[244:245], 1.0 op_sel_hi:[1,1,0] neg_lo:[1,0,0] neg_hi:[1,0,0]
	v_pk_fma_f32 v[252:253], v[238:239], v[250:251], 1.0 op_sel_hi:[1,1,0] neg_lo:[1,0,0] neg_hi:[1,0,0]
	v_pk_fma_f32 v[244:245], v[246:247], v[244:245], v[244:245]
; __device__ __forceinline__ u32x4 pack8(const f32x4 v0, const f32x4 v1) { u32x4 w; w.x = pk2(v0[0], v0[1]); w.y = pk2(v0[2], v0[3]); w.z = pk2(v1[0], v1[1]); w.w = pk2(v1[2], v1[3]); return w; }
; __device__ __forceinline__ void unpack8(const u32x4 w, f32x4& v0, f32x4& v1) { v0 = (f32x4){bflo(w.x), bfhi(w.x), bflo(w.y), bfhi(w.y)}; v1 = (f32x4){bflo(w.z), bfhi(w.z), bflo(w.w), bfhi(w.w)}; }
; __device__ __forceinline__ float sigmoidf_(float x) { return 1.0f / (1.0f + __expf(-x)); }
;     __device__ __forceinline__ void operator()(const f32x4 (&acc)[2][2][4][2], const Unit& u, int wr, int wc, int fr, int fq) const {
;         const int row0 = u.pm * 256 + wr * 64 + fr, col0 = u.pn * 256 + wc * 32 + 8 * fq;
; #pragma unroll
;         for (int ai = 0; ai < 2; ++ai)
; #pragma unroll
;             for (int m = 0; m < 4; ++m) {
;                 bf16_t* rowp = z + (size_t)(row0 + ai * 128 + m * 16) * DIN + col0;
; #pragma unroll
;                 for (int bj = 0; bj < 2; ++bj) {
;                     const u32x4 gw = *(const u32x4*)(rowp + (MODE == 0 ? O_GB : O_GA) + bj * 128);
;                     f32x4 g0, g1; unpack8(gw, g0, g1);
;                     f32x4 v0, v1;
; #pragma unroll
;                     for (int j = 0; j < 4; ++j) { v0[j] = sigmoidf_(g0[j]) * acc[ai][bj][m][0][j]; v1[j] = sigmoidf_(g1[j]) * acc[ai][bj][m][1][j]; }
;                     if (MODE == 1) { const u32x4 mw = *(const u32x4*)(rowp + bj * 128); f32x4 m0, m1; unpack8(mw, m0, m1); v0 += m0; v1 += m1; }
;                     *(u32x4*)(rowp + bj * 128) = pack8(v0, v1); }
	v_pk_fma_f32 v[250:251], v[252:253], v[250:251], v[250:251]
	v_pk_fma_f32 v[246:247], v[236:237], v[244:245], 1.0 op_sel_hi:[1,1,0] neg_lo:[1,0,0] neg_hi:[1,0,0]
	v_pk_fma_f32 v[252:253], v[238:239], v[250:251], 1.0 op_sel_hi:[1,1,0] neg_lo:[1,0,0] neg_hi:[1,0,0]
	v_pk_fma_f32 v[248:249], v[246:247], v[244:245], v[244:245]
	v_pk_fma_f32 v[254:255], v[252:253], v[250:251], v[250:251]
	v_pk_fma_f32 v[246:247], v[236:237], v[248:249], 1.0 op_sel_hi:[1,1,0] neg_lo:[1,0,0] neg_hi:[1,0,0]
	v_pk_fma_f32 v[252:253], v[238:239], v[254:255], 1.0 op_sel_hi:[1,1,0] neg_lo:[1,0,0] neg_hi:[1,0,0]
	v_pk_fma_f32 v[248:249], v[246:247], v[244:245], v[248:249]
	v_pk_fma_f32 v[254:255], v[252:253], v[250:251], v[254:255]
	v_div_fixup_f32 v236, v248, v236, 1.0
	v_div_fixup_f32 v237, v249, v237, 1.0
	v_div_fixup_f32 v238, v254, v238, 1.0
	v_div_fixup_f32 v239, v255, v239, 1.0
	v_rcp_f32_e32 v244, v240
	v_rcp_f32_e32 v245, v241
	v_rcp_f32_e32 v250, v242
	v_rcp_f32_e32 v251, v243
	v_pk_fma_f32 v[246:247], v[240:241], v[244:245], 1.0 op_sel_hi:[1,1,0] neg_lo:[1,0,0] neg_hi:[1,0,0]
	v_pk_fma_f32 v[252:253], v[242:243], v[250:251], 1.0 op_sel_hi:[1,1,0] neg_lo:[1,0,0] neg_hi:[1,0,0]
	v_pk_fma_f32 v[244:245], v[246:247], v[244:245], v[244:245]
	v_pk_fma_f32 v[250:251], v[252:253], v[250:251], v[250:251]
	v_pk_fma_f32 v[246:247], v[240:241], v[244:245], 1.0 op_sel_hi:[1,1,0] neg_lo:[1,0,0] neg_hi:[1,0,0]
	v_pk_fma_f32 v[252:253], v[242:243], v[250:251], 1.0 op_sel_hi:[1,1,0] neg_lo:[1,0,0] neg_hi:[1,0,0]
	v_pk_fma_f32 v[248:249], v[246:247], v[244:245], v[244:245]
	v_pk_fma_f32 v[254:255], v[252:253], v[250:251], v[250:251]
	v_pk_fma_f32 v[246:247], v[240:241], v[248:249], 1.0 op_sel_hi:[1,1,0] neg_lo:[1,0,0] neg_hi:[1,0,0]
	v_pk_fma_f32 v[252:253], v[242:243], v[254:255], 1.0 op_sel_hi:[1,1,0] neg_lo:[1,0,0] neg_hi:[1,0,0]
	v_pk_fma_f32 v[248:249], v[246:247], v[244:245], v[248:249]
	v_pk_fma_f32 v[254:255], v[252:253], v[250:251], v[254:255]
	v_div_fixup_f32 v240, v248, v240, 1.0
	v_div_fixup_f32 v241, v249, v241, 1.0
	v_div_fixup_f32 v242, v254, v242, 1.0
	v_div_fixup_f32 v243, v255, v243, 1.0
	global_store_dwordx4 v[80:81], v[72:75], off
	s_nop 0
	v_pk_mul_f32 v[68:69], v[68:69], v[236:237]
	v_pk_mul_f32 v[64:65], v[64:65], v[238:239]
	v_pk_mul_f32 v[70:71], v[70:71], v[240:241]
	v_pk_mul_f32 v[72:73], v[66:67], v[242:243]
	v_cvt_pk_bf16_f32 v66, v68, v69
	v_cvt_pk_bf16_f32 v67, v70, v71
	v_cvt_pk_bf16_f32 v68, v64, v65
	v_add_u32_e32 v64, 0x80, v160
	v_mad_i64_i32 v[64:65], s[6:7], v64, s61, v[146:147]
	v_lshl_add_u64 v[64:65], v[64:65], 0, v[148:149]
	v_add_co_u32_e32 v74, vcc, s62, v64
	v_cvt_pk_bf16_f32 v69, v72, v73
	global_store_dwordx4 v[80:81], v[66:69], off offset:256
	s_nop 0
	v_addc_co_u32_e32 v75, vcc, 0, v65, vcc
	s_waitcnt vmcnt(11)
	v_mov_b32_e32 v70, v208
	v_mov_b32_e32 v71, v209
	v_mov_b32_e32 v72, v210
	v_mov_b32_e32 v73, v211
	v_add_u32_e32 v199, 0x177a00, v198
	global_load_dwordx4 v[208:211], v199, s[24:25]
	s_mov_b32 s100, 0xbfb8aa3b
	v_lshlrev_b32_e32 v236, 16, v70
	v_and_b32_e32 v237, 0xffff0000, v70
	v_lshlrev_b32_e32 v238, 16, v72
	v_and_b32_e32 v239, 0xffff0000, v72
	v_lshlrev_b32_e32 v240, 16, v71
	v_and_b32_e32 v241, 0xffff0000, v71
	v_lshlrev_b32_e32 v242, 16, v73
	v_and_b32_e32 v243, 0xffff0000, v73
	v_pk_mul_f32 v[236:237], v[236:237], s[100:101] op_sel_hi:[1,0]
	v_pk_mul_f32 v[238:239], v[238:239], s[100:101] op_sel_hi:[1,0]
	v_pk_mul_f32 v[240:241], v[240:241], s[100:101] op_sel_hi:[1,0]
	v_pk_mul_f32 v[242:243], v[242:243], s[100:101] op_sel_hi:[1,0]
	v_exp_f32_e32 v236, v236
	v_exp_f32_e32 v237, v237
	v_exp_f32_e32 v238, v238
	v_exp_f32_e32 v239, v239
	v_exp_f32_e32 v240, v240
	v_exp_f32_e32 v241, v241
	v_exp_f32_e32 v242, v242
	v_exp_f32_e32 v243, v243
	s_nop 0
	v_pk_add_f32 v[236:237], v[236:237], 1.0 op_sel_hi:[1,0]
	v_pk_add_f32 v[238:239], v[238:239], 1.0 op_sel_hi:[1,0]
	v_pk_add_f32 v[240:241], v[240:241], 1.0 op_sel_hi:[1,0]
	v_pk_add_f32 v[242:243], v[242:243], 1.0 op_sel_hi:[1,0]
	v_rcp_f32_e32 v244, v236
	v_rcp_f32_e32 v245, v237
	v_rcp_f32_e32 v250, v238
	v_rcp_f32_e32 v251, v239
	v_pk_fma_f32 v[246:247], v[236:237], v[244:245], 1.0 op_sel_hi:[1,1,0] neg_lo:[1,0,0] neg_hi:[1,0,0]
	v_pk_fma_f32 v[252:253], v[238:239], v[250:251], 1.0 op_sel_hi:[1,1,0] neg_lo:[1,0,0] neg_hi:[1,0,0]
	v_pk_fma_f32 v[244:245], v[246:247], v[244:245], v[244:245]
	v_pk_fma_f32 v[250:251], v[252:253], v[250:251], v[250:251]
	v_pk_fma_f32 v[246:247], v[236:237], v[244:245], 1.0 op_sel_hi:[1,1,0] neg_lo:[1,0,0] neg_hi:[1,0,0]
	v_pk_fma_f32 v[252:253], v[238:239], v[250:251], 1.0 op_sel_hi:[1,1,0] neg_lo:[1,0,0] neg_hi:[1,0,0]
	v_pk_fma_f32 v[248:249], v[246:247], v[244:245], v[244:245]
	v_pk_fma_f32 v[254:255], v[252:253], v[250:251], v[250:251]
	v_pk_fma_f32 v[246:247], v[236:237], v[248:249], 1.0 op_sel_hi:[1,1,0] neg_lo:[1,0,0] neg_hi:[1,0,0]
	v_pk_fma_f32 v[252:253], v[238:239], v[254:255], 1.0 op_sel_hi:[1,1,0] neg_lo:[1,0,0] neg_hi:[1,0,0]
	v_pk_fma_f32 v[248:249], v[246:247], v[244:245], v[248:249]
	v_pk_fma_f32 v[254:255], v[252:253], v[250:251], v[254:255]
	v_div_fixup_f32 v236, v248, v236, 1.0
	v_div_fixup_f32 v237, v249, v237, 1.0
	v_div_fixup_f32 v238, v254, v238, 1.0
	v_div_fixup_f32 v239, v255, v239, 1.0
	v_rcp_f32_e32 v244, v240
	v_rcp_f32_e32 v245, v241
	v_rcp_f32_e32 v250, v242
	v_rcp_f32_e32 v251, v243
	v_pk_fma_f32 v[246:247], v[240:241], v[244:245], 1.0 op_sel_hi:[1,1,0] neg_lo:[1,0,0] neg_hi:[1,0,0]
	v_pk_fma_f32 v[252:253], v[242:243], v[250:251], 1.0 op_sel_hi:[1,1,0] neg_lo:[1,0,0] neg_hi:[1,0,0]
	v_pk_fma_f32 v[244:245], v[246:247], v[244:245], v[244:245]
	v_pk_fma_f32 v[250:251], v[252:253], v[250:251], v[250:251]
	v_pk_fma_f32 v[246:247], v[240:241], v[244:245], 1.0 op_sel_hi:[1,1,0] neg_lo:[1,0,0] neg_hi:[1,0,0]
	v_pk_fma_f32 v[252:253], v[242:243], v[250:251], 1.0 op_sel_hi:[1,1,0] neg_lo:[1,0,0] neg_hi:[1,0,0]
	v_pk_fma_f32 v[248:249], v[246:247], v[244:245], v[244:245]
	v_pk_fma_f32 v[254:255], v[252:253], v[250:251], v[250:251]
	v_pk_fma_f32 v[246:247], v[240:241], v[248:249], 1.0 op_sel_hi:[1,1,0] neg_lo:[1,0,0] neg_hi:[1,0,0]
	v_pk_fma_f32 v[252:253], v[242:243], v[254:255], 1.0 op_sel_hi:[1,1,0] neg_lo:[1,0,0] neg_hi:[1,0,0]
	v_pk_fma_f32 v[248:249], v[246:247], v[244:245], v[248:249]
	v_pk_fma_f32 v[254:255], v[252:253], v[250:251], v[254:255]
	v_div_fixup_f32 v240, v248, v240, 1.0
	v_div_fixup_f32 v241, v249, v241, 1.0
	v_div_fixup_f32 v242, v254, v242, 1.0
	v_div_fixup_f32 v243, v255, v243, 1.0
	v_mul_f32_e32 v60, v60, v236
	v_mul_f32_e32 v66, v56, v238
	v_mul_f32_e32 v56, v61, v237
	v_mul_f32_e32 v61, v57, v239
	v_mul_f32_e32 v57, v62, v240
	v_mul_f32_e32 v62, v58, v242
	v_mul_f32_e32 v58, v63, v241
	v_mul_f32_e32 v59, v59, v243
	v_cvt_pk_bf16_f32 v56, v60, v56
	v_cvt_pk_bf16_f32 v57, v57, v58
	v_cvt_pk_bf16_f32 v58, v66, v61
	v_cvt_pk_bf16_f32 v59, v62, v59
	s_waitcnt vmcnt(11)
; __device__ __forceinline__ u32x4 pack8(const f32x4 v0, const f32x4 v1) { u32x4 w; w.x = pk2(v0[0], v0[1]); w.y = pk2(v0[2], v0[3]); w.z = pk2(v1[0], v1[1]); w.w = pk2(v1[2], v1[3]); return w; }
; __device__ __forceinline__ void unpack8(const u32x4 w, f32x4& v0, f32x4& v1) { v0 = (f32x4){bflo(w.x), bfhi(w.x), bflo(w.y), bfhi(w.y)}; v1 = (f32x4){bflo(w.z), bfhi(w.z), bflo(w.w), bfhi(w.w)}; }
; __device__ __forceinline__ float sigmoidf_(float x) { return 1.0f / (1.0f + __expf(-x)); }
;     __device__ __forceinline__ void operator()(const f32x4 (&acc)[2][2][4][2], const Unit& u, int wr, int wc, int fr, int fq) const {
;         const int row0 = u.pm * 256 + wr * 64 + fr, col0 = u.pn * 256 + wc * 32 + 8 * fq;
; #pragma unroll
;         for (int ai = 0; ai < 2; ++ai)
; #pragma unroll
;             for (int m = 0; m < 4; ++m) {
;                 bf16_t* rowp = z + (size_t)(row0 + ai * 128 + m * 16) * DIN + col0;
; #pragma unroll
;                 for (int bj = 0; bj < 2; ++bj) {
;                     const u32x4 gw = *(const u32x4*)(rowp + (MODE == 0 ? O_GB : O_GA) + bj * 128);
;                     f32x4 g0, g1; unpack8(gw, g0, g1);
;                     f32x4 v0, v1;
; #pragma unroll
;                     for (int j = 0; j < 4; ++j) { v0[j] = sigmoidf_(g0[j]) * acc[ai][bj][m][0][j]; v1[j] = sigmoidf_(g1[j]) * acc[ai][bj][m][1][j]; }
;                     if (MODE == 1) { const u32x4 mw = *(const u32x4*)(rowp + bj * 128); f32x4 m0, m1; unpack8(mw, m0, m1); v0 += m0; v1 += m1; }
;                     *(u32x4*)(rowp + bj * 128) = pack8(v0, v1); }
	v_mov_b32_e32 v60, v212
	v_mov_b32_e32 v61, v213
	v_mov_b32_e32 v62, v214
	v_mov_b32_e32 v63, v215
	v_add_u32_e32 v199, 0x177b00, v198
	global_load_dwordx4 v[212:215], v199, s[24:25]
	s_mov_b32 s100, 0xbfb8aa3b
	v_lshlrev_b32_e32 v236, 16, v60
	v_and_b32_e32 v237, 0xffff0000, v60
	v_lshlrev_b32_e32 v238, 16, v62
	v_and_b32_e32 v239, 0xffff0000, v62
	v_lshlrev_b32_e32 v240, 16, v61
	v_and_b32_e32 v241, 0xffff0000, v61
	v_lshlrev_b32_e32 v242, 16, v63
	v_and_b32_e32 v243, 0xffff0000, v63
	v_pk_mul_f32 v[236:237], v[236:237], s[100:101] op_sel_hi:[1,0]
	v_pk_mul_f32 v[238:239], v[238:239], s[100:101] op_sel_hi:[1,0]
	v_pk_mul_f32 v[240:241], v[240:241], s[100:101] op_sel_hi:[1,0]
	v_pk_mul_f32 v[242:243], v[242:243], s[100:101] op_sel_hi:[1,0]
	v_exp_f32_e32 v236, v236
	v_exp_f32_e32 v237, v237
	v_exp_f32_e32 v238, v238
	v_exp_f32_e32 v239, v239
	v_exp_f32_e32 v240, v240
	v_exp_f32_e32 v241, v241
	v_exp_f32_e32 v242, v242
	v_exp_f32_e32 v243, v243
	s_nop 0
	v_pk_add_f32 v[236:237], v[236:237], 1.0 op_sel_hi:[1,0]
	v_pk_add_f32 v[238:239], v[238:239], 1.0 op_sel_hi:[1,0]
	v_pk_add_f32 v[240:241], v[240:241], 1.0 op_sel_hi:[1,0]
	v_pk_add_f32 v[242:243], v[242:243], 1.0 op_sel_hi:[1,0]
	v_rcp_f32_e32 v244, v236
	v_rcp_f32_e32 v245, v237
	v_rcp_f32_e32 v250, v238
	v_rcp_f32_e32 v251, v239
	v_pk_fma_f32 v[246:247], v[236:237], v[244:245], 1.0 op_sel_hi:[1,1,0] neg_lo:[1,0,0] neg_hi:[1,0,0]
	v_pk_fma_f32 v[252:253], v[238:239], v[250:251], 1.0 op_sel_hi:[1,1,0] neg_lo:[1,0,0] neg_hi:[1,0,0]
	v_pk_fma_f32 v[244:245], v[246:247], v[244:245], v[244:245]
	v_pk_fma_f32 v[250:251], v[252:253], v[250:251], v[250:251]
	v_pk_fma_f32 v[246:247], v[236:237], v[244:245], 1.0 op_sel_hi:[1,1,0] neg_lo:[1,0,0] neg_hi:[1,0,0]
	v_pk_fma_f32 v[252:253], v[238:239], v[250:251], 1.0 op_sel_hi:[1,1,0] neg_lo:[1,0,0] neg_hi:[1,0,0]
	v_pk_fma_f32 v[248:249], v[246:247], v[244:245], v[244:245]
	v_pk_fma_f32 v[254:255], v[252:253], v[250:251], v[250:251]
	v_pk_fma_f32 v[246:247], v[236:237], v[248:249], 1.0 op_sel_hi:[1,1,0] neg_lo:[1,0,0] neg_hi:[1,0,0]
	v_pk_fma_f32 v[252:253], v[238:239], v[254:255], 1.0 op_sel_hi:[1,1,0] neg_lo:[1,0,0] neg_hi:[1,0,0]
	v_pk_fma_f32 v[248:249], v[246:247], v[244:245], v[248:249]
	v_pk_fma_f32 v[254:255], v[252:253], v[250:251], v[254:255]
	v_div_fixup_f32 v236, v248, v236, 1.0
	v_div_fixup_f32 v237, v249, v237, 1.0
	v_div_fixup_f32 v238, v254, v238, 1.0
	v_div_fixup_f32 v239, v255, v239, 1.0
	v_rcp_f32_e32 v244, v240
	v_rcp_f32_e32 v245, v241
	v_rcp_f32_e32 v250, v242
	v_rcp_f32_e32 v251, v243
	v_pk_fma_f32 v[246:247], v[240:241], v[244:245], 1.0 op_sel_hi:[1,1,0] neg_lo:[1,0,0] neg_hi:[1,0,0]
	v_pk_fma_f32 v[252:253], v[242:243], v[250:251], 1.0 op_sel_hi:[1,1,0] neg_lo:[1,0,0] neg_hi:[1,0,0]
	v_pk_fma_f32 v[244:245], v[246:247], v[244:245], v[244:245]
	v_pk_fma_f32 v[250:251], v[252:253], v[250:251], v[250:251]
	v_pk_fma_f32 v[246:247], v[240:241], v[244:245], 1.0 op_sel_hi:[1,1,0] neg_lo:[1,0,0] neg_hi:[1,0,0]
	v_pk_fma_f32 v[252:253], v[242:243], v[250:251], 1.0 op_sel_hi:[1,1,0] neg_lo:[1,0,0] neg_hi:[1,0,0]
	v_pk_fma_f32 v[248:249], v[246:247], v[244:245], v[244:245]
	v_pk_fma_f32 v[254:255], v[252:253], v[250:251], v[250:251]
	v_pk_fma_f32 v[246:247], v[240:241], v[248:249], 1.0 op_sel_hi:[1,1,0] neg_lo:[1,0,0] neg_hi:[1,0,0]
	v_pk_fma_f32 v[252:253], v[242:243], v[254:255], 1.0 op_sel_hi:[1,1,0] neg_lo:[1,0,0] neg_hi:[1,0,0]
	v_pk_fma_f32 v[248:249], v[246:247], v[244:245], v[248:249]
	v_pk_fma_f32 v[254:255], v[252:253], v[250:251], v[254:255]
	v_div_fixup_f32 v240, v248, v240, 1.0
	v_div_fixup_f32 v241, v249, v241, 1.0
	v_div_fixup_f32 v242, v254, v242, 1.0
	v_div_fixup_f32 v243, v255, v243, 1.0
	global_store_dwordx4 v[64:65], v[56:59], off
	s_nop 0
	v_pk_mul_f32 v[52:53], v[52:53], v[236:237]
	v_pk_mul_f32 v[48:49], v[48:49], v[238:239]
	v_pk_mul_f32 v[54:55], v[54:55], v[240:241]
	v_pk_mul_f32 v[56:57], v[50:51], v[242:243]
	v_cvt_pk_bf16_f32 v50, v52, v53
	v_cvt_pk_bf16_f32 v51, v54, v55
	v_cvt_pk_bf16_f32 v52, v48, v49
	v_add_u32_e32 v48, 0x90, v160
	v_mad_i64_i32 v[48:49], s[6:7], v48, s61, v[146:147]
	v_lshl_add_u64 v[48:49], v[48:49], 0, v[148:149]
	v_add_co_u32_e32 v58, vcc, s62, v48
	v_cvt_pk_bf16_f32 v53, v56, v57
	global_store_dwordx4 v[64:65], v[50:53], off offset:256
	s_nop 0
	v_addc_co_u32_e32 v59, vcc, 0, v49, vcc
	s_waitcnt vmcnt(11)
; __device__ __forceinline__ u32x4 pack8(const f32x4 v0, const f32x4 v1) { u32x4 w; w.x = pk2(v0[0], v0[1]); w.y = pk2(v0[2], v0[3]); w.z = pk2(v1[0], v1[1]); w.w = pk2(v1[2], v1[3]); return w; }
; __device__ __forceinline__ void unpack8(const u32x4 w, f32x4& v0, f32x4& v1) { v0 = (f32x4){bflo(w.x), bfhi(w.x), bflo(w.y), bfhi(w.y)}; v1 = (f32x4){bflo(w.z), bfhi(w.z), bflo(w.w), bfhi(w.w)}; }
; __device__ __forceinline__ float sigmoidf_(float x) { return 1.0f / (1.0f + __expf(-x)); }
;     __device__ __forceinline__ void operator()(const f32x4 (&acc)[2][2][4][2], const Unit& u, int wr, int wc, int fr, int fq) const {
;         const int row0 = u.pm * 256 + wr * 64 + fr, col0 = u.pn * 256 + wc * 32 + 8 * fq;
; #pragma unroll
;         for (int ai = 0; ai < 2; ++ai)
; #pragma unroll
;             for (int m = 0; m < 4; ++m) {
;                 bf16_t* rowp = z + (size_t)(row0 + ai * 128 + m * 16) * DIN + col0;
; #pragma unroll
;                 for (int bj = 0; bj < 2; ++bj) {
;                     const u32x4 gw = *(const u32x4*)(rowp + (MODE == 0 ? O_GB : O_GA) + bj * 128);
;                     f32x4 g0, g1; unpack8(gw, g0, g1);
;                     f32x4 v0, v1;
; #pragma unroll
;                     for (int j = 0; j < 4; ++j) { v0[j] = sigmoidf_(g0[j]) * acc[ai][bj][m][0][j]; v1[j] = sigmoidf_(g1[j]) * acc[ai][bj][m][1][j]; }
;                     if (MODE == 1) { const u32x4 mw = *(const u32x4*)(rowp + bj * 128); f32x4 m0, m1; unpack8(mw, m0, m1); v0 += m0; v1 += m1; }
;                     *(u32x4*)(rowp + bj * 128) = pack8(v0, v1); }
	v_mov_b32_e32 v54, v216
	v_mov_b32_e32 v55, v217
	v_mov_b32_e32 v56, v218
	v_mov_b32_e32 v57, v219
	s_mov_b32 s100, 0xbfb8aa3b
	v_lshlrev_b32_e32 v236, 16, v54
	v_and_b32_e32 v237, 0xffff0000, v54
	v_lshlrev_b32_e32 v238, 16, v56
	v_and_b32_e32 v239, 0xffff0000, v56
	v_lshlrev_b32_e32 v240, 16, v55
	v_and_b32_e32 v241, 0xffff0000, v55
	v_lshlrev_b32_e32 v242, 16, v57
	v_and_b32_e32 v243, 0xffff0000, v57
	v_pk_mul_f32 v[236:237], v[236:237], s[100:101] op_sel_hi:[1,0]
	v_pk_mul_f32 v[238:239], v[238:239], s[100:101] op_sel_hi:[1,0]
	v_pk_mul_f32 v[240:241], v[240:241], s[100:101] op_sel_hi:[1,0]
	v_pk_mul_f32 v[242:243], v[242:243], s[100:101] op_sel_hi:[1,0]
	v_exp_f32_e32 v236, v236
	v_exp_f32_e32 v237, v237
	v_exp_f32_e32 v238, v238
	v_exp_f32_e32 v239, v239
	v_exp_f32_e32 v240, v240
	v_exp_f32_e32 v241, v241
	v_exp_f32_e32 v242, v242
	v_exp_f32_e32 v243, v243
	s_nop 0
	v_pk_add_f32 v[236:237], v[236:237], 1.0 op_sel_hi:[1,0]
	v_pk_add_f32 v[238:239], v[238:239], 1.0 op_sel_hi:[1,0]
	v_pk_add_f32 v[240:241], v[240:241], 1.0 op_sel_hi:[1,0]
	v_pk_add_f32 v[242:243], v[242:243], 1.0 op_sel_hi:[1,0]
	v_rcp_f32_e32 v244, v236
	v_rcp_f32_e32 v245, v237
	v_rcp_f32_e32 v250, v238
	v_rcp_f32_e32 v251, v239
	v_pk_fma_f32 v[246:247], v[236:237], v[244:245], 1.0 op_sel_hi:[1,1,0] neg_lo:[1,0,0] neg_hi:[1,0,0]
	v_pk_fma_f32 v[252:253], v[238:239], v[250:251], 1.0 op_sel_hi:[1,1,0] neg_lo:[1,0,0] neg_hi:[1,0,0]
	v_pk_fma_f32 v[244:245], v[246:247], v[244:245], v[244:245]
	v_pk_fma_f32 v[250:251], v[252:253], v[250:251], v[250:251]
	v_pk_fma_f32 v[246:247], v[236:237], v[244:245], 1.0 op_sel_hi:[1,1,0] neg_lo:[1,0,0] neg_hi:[1,0,0]
	v_pk_fma_f32 v[252:253], v[238:239], v[250:251], 1.0 op_sel_hi:[1,1,0] neg_lo:[1,0,0] neg_hi:[1,0,0]
	v_pk_fma_f32 v[248:249], v[246:247], v[244:245], v[244:245]
	v_pk_fma_f32 v[254:255], v[252:253], v[250:251], v[250:251]
	v_pk_fma_f32 v[246:247], v[236:237], v[248:249], 1.0 op_sel_hi:[1,1,0] neg_lo:[1,0,0] neg_hi:[1,0,0]
	v_pk_fma_f32 v[252:253], v[238:239], v[254:255], 1.0 op_sel_hi:[1,1,0] neg_lo:[1,0,0] neg_hi:[1,0,0]
	v_pk_fma_f32 v[248:249], v[246:247], v[244:245], v[248:249]
	v_pk_fma_f32 v[254:255], v[252:253], v[250:251], v[254:255]
	v_div_fixup_f32 v236, v248, v236, 1.0
	v_div_fixup_f32 v237, v249, v237, 1.0
	v_div_fixup_f32 v238, v254, v238, 1.0
	v_div_fixup_f32 v239, v255, v239, 1.0
	v_rcp_f32_e32 v244, v240
	v_rcp_f32_e32 v245, v241
	v_rcp_f32_e32 v250, v242
	v_rcp_f32_e32 v251, v243
	v_pk_fma_f32 v[246:247], v[240:241], v[244:245], 1.0 op_sel_hi:[1,1,0] neg_lo:[1,0,0] neg_hi:[1,0,0]
	v_pk_fma_f32 v[252:253], v[242:243], v[250:251], 1.0 op_sel_hi:[1,1,0] neg_lo:[1,0,0] neg_hi:[1,0,0]
	v_pk_fma_f32 v[244:245], v[246:247], v[244:245], v[244:245]
	v_pk_fma_f32 v[250:251], v[252:253], v[250:251], v[250:251]
	v_pk_fma_f32 v[246:247], v[240:241], v[244:245], 1.0 op_sel_hi:[1,1,0] neg_lo:[1,0,0] neg_hi:[1,0,0]
	v_pk_fma_f32 v[252:253], v[242:243], v[250:251], 1.0 op_sel_hi:[1,1,0] neg_lo:[1,0,0] neg_hi:[1,0,0]
	v_pk_fma_f32 v[248:249], v[246:247], v[244:245], v[244:245]
	v_pk_fma_f32 v[254:255], v[252:253], v[250:251], v[250:251]
	v_pk_fma_f32 v[246:247], v[240:241], v[248:249], 1.0 op_sel_hi:[1,1,0] neg_lo:[1,0,0] neg_hi:[1,0,0]
	v_pk_fma_f32 v[252:253], v[242:243], v[254:255], 1.0 op_sel_hi:[1,1,0] neg_lo:[1,0,0] neg_hi:[1,0,0]
	v_pk_fma_f32 v[248:249], v[246:247], v[244:245], v[248:249]
	v_pk_fma_f32 v[254:255], v[252:253], v[250:251], v[254:255]
	v_div_fixup_f32 v240, v248, v240, 1.0
	v_div_fixup_f32 v241, v249, v241, 1.0
	v_div_fixup_f32 v242, v254, v242, 1.0
	v_div_fixup_f32 v243, v255, v243, 1.0
	v_mul_f32_e32 v44, v44, v236
	v_mul_f32_e32 v50, v40, v238
	v_mul_f32_e32 v40, v45, v237
	v_mul_f32_e32 v45, v41, v239
	v_mul_f32_e32 v41, v46, v240
	v_mul_f32_e32 v46, v42, v242
	v_mul_f32_e32 v42, v47, v241
	v_mul_f32_e32 v43, v43, v243
	v_cvt_pk_bf16_f32 v40, v44, v40
	v_cvt_pk_bf16_f32 v41, v41, v42
	v_cvt_pk_bf16_f32 v42, v50, v45
	v_cvt_pk_bf16_f32 v43, v46, v43
	s_waitcnt vmcnt(10)
	v_mov_b32_e32 v44, v232
	v_mov_b32_e32 v45, v233
	v_mov_b32_e32 v46, v234
	v_mov_b32_e32 v47, v235
	s_mov_b32 s100, 0xbfb8aa3b
	v_lshlrev_b32_e32 v236, 16, v44
	v_and_b32_e32 v237, 0xffff0000, v44
	v_lshlrev_b32_e32 v238, 16, v46
	v_and_b32_e32 v239, 0xffff0000, v46
	v_lshlrev_b32_e32 v240, 16, v45
	v_and_b32_e32 v241, 0xffff0000, v45
	v_lshlrev_b32_e32 v242, 16, v47
	v_and_b32_e32 v243, 0xffff0000, v47
	v_pk_mul_f32 v[236:237], v[236:237], s[100:101] op_sel_hi:[1,0]
	v_pk_mul_f32 v[238:239], v[238:239], s[100:101] op_sel_hi:[1,0]
	v_pk_mul_f32 v[240:241], v[240:241], s[100:101] op_sel_hi:[1,0]
	v_pk_mul_f32 v[242:243], v[242:243], s[100:101] op_sel_hi:[1,0]
	v_exp_f32_e32 v236, v236
	v_exp_f32_e32 v237, v237
	v_exp_f32_e32 v238, v238
	v_exp_f32_e32 v239, v239
	v_exp_f32_e32 v240, v240
	v_exp_f32_e32 v241, v241
	v_exp_f32_e32 v242, v242
	v_exp_f32_e32 v243, v243
	s_nop 0
	v_pk_add_f32 v[236:237], v[236:237], 1.0 op_sel_hi:[1,0]
	v_pk_add_f32 v[238:239], v[238:239], 1.0 op_sel_hi:[1,0]
	v_pk_add_f32 v[240:241], v[240:241], 1.0 op_sel_hi:[1,0]
	v_pk_add_f32 v[242:243], v[242:243], 1.0 op_sel_hi:[1,0]
	v_rcp_f32_e32 v244, v236
	v_rcp_f32_e32 v245, v237
	v_rcp_f32_e32 v250, v238
	v_rcp_f32_e32 v251, v239
	v_pk_fma_f32 v[246:247], v[236:237], v[244:245], 1.0 op_sel_hi:[1,1,0] neg_lo:[1,0,0] neg_hi:[1,0,0]
	v_pk_fma_f32 v[252:253], v[238:239], v[250:251], 1.0 op_sel_hi:[1,1,0] neg_lo:[1,0,0] neg_hi:[1,0,0]
	v_pk_fma_f32 v[244:245], v[246:247], v[244:245], v[244:245]
	v_pk_fma_f32 v[250:251], v[252:253], v[250:251], v[250:251]
	v_pk_fma_f32 v[246:247], v[236:237], v[244:245], 1.0 op_sel_hi:[1,1,0] neg_lo:[1,0,0] neg_hi:[1,0,0]
; __device__ __forceinline__ u32x4 pack8(const f32x4 v0, const f32x4 v1) { u32x4 w; w.x = pk2(v0[0], v0[1]); w.y = pk2(v0[2], v0[3]); w.z = pk2(v1[0], v1[1]); w.w = pk2(v1[2], v1[3]); return w; }
; __device__ __forceinline__ void unpack8(const u32x4 w, f32x4& v0, f32x4& v1) { v0 = (f32x4){bflo(w.x), bfhi(w.x), bflo(w.y), bfhi(w.y)}; v1 = (f32x4){bflo(w.z), bfhi(w.z), bflo(w.w), bfhi(w.w)}; }
; __device__ __forceinline__ float sigmoidf_(float x) { return 1.0f / (1.0f + __expf(-x)); }
;     __device__ __forceinline__ void operator()(const f32x4 (&acc)[2][2][4][2], const Unit& u, int wr, int wc, int fr, int fq) const {
;         const int row0 = u.pm * 256 + wr * 64 + fr, col0 = u.pn * 256 + wc * 32 + 8 * fq;
; #pragma unroll
;         for (int ai = 0; ai < 2; ++ai)
; #pragma unroll
;             for (int m = 0; m < 4; ++m) {
;                 bf16_t* rowp = z + (size_t)(row0 + ai * 128 + m * 16) * DIN + col0;
; #pragma unroll
;                 for (int bj = 0; bj < 2; ++bj) {
;                     const u32x4 gw = *(const u32x4*)(rowp + (MODE == 0 ? O_GB : O_GA) + bj * 128);
;                     f32x4 g0, g1; unpack8(gw, g0, g1);
;                     f32x4 v0, v1;
; #pragma unroll
;                     for (int j = 0; j < 4; ++j) { v0[j] = sigmoidf_(g0[j]) * acc[ai][bj][m][0][j]; v1[j] = sigmoidf_(g1[j]) * acc[ai][bj][m][1][j]; }
;                     if (MODE == 1) { const u32x4 mw = *(const u32x4*)(rowp + bj * 128); f32x4 m0, m1; unpack8(mw, m0, m1); v0 += m0; v1 += m1; }
;                     *(u32x4*)(rowp + bj * 128) = pack8(v0, v1); }
	v_pk_fma_f32 v[252:253], v[238:239], v[250:251], 1.0 op_sel_hi:[1,1,0] neg_lo:[1,0,0] neg_hi:[1,0,0]
	v_pk_fma_f32 v[248:249], v[246:247], v[244:245], v[244:245]
	v_pk_fma_f32 v[254:255], v[252:253], v[250:251], v[250:251]
	v_pk_fma_f32 v[246:247], v[236:237], v[248:249], 1.0 op_sel_hi:[1,1,0] neg_lo:[1,0,0] neg_hi:[1,0,0]
	v_pk_fma_f32 v[252:253], v[238:239], v[254:255], 1.0 op_sel_hi:[1,1,0] neg_lo:[1,0,0] neg_hi:[1,0,0]
	v_pk_fma_f32 v[248:249], v[246:247], v[244:245], v[248:249]
	v_pk_fma_f32 v[254:255], v[252:253], v[250:251], v[254:255]
	v_div_fixup_f32 v236, v248, v236, 1.0
	v_div_fixup_f32 v237, v249, v237, 1.0
	v_div_fixup_f32 v238, v254, v238, 1.0
	v_div_fixup_f32 v239, v255, v239, 1.0
	v_rcp_f32_e32 v244, v240
	v_rcp_f32_e32 v245, v241
	v_rcp_f32_e32 v250, v242
	v_rcp_f32_e32 v251, v243
	v_pk_fma_f32 v[246:247], v[240:241], v[244:245], 1.0 op_sel_hi:[1,1,0] neg_lo:[1,0,0] neg_hi:[1,0,0]
	v_pk_fma_f32 v[252:253], v[242:243], v[250:251], 1.0 op_sel_hi:[1,1,0] neg_lo:[1,0,0] neg_hi:[1,0,0]
	v_pk_fma_f32 v[244:245], v[246:247], v[244:245], v[244:245]
	v_pk_fma_f32 v[250:251], v[252:253], v[250:251], v[250:251]
	v_pk_fma_f32 v[246:247], v[240:241], v[244:245], 1.0 op_sel_hi:[1,1,0] neg_lo:[1,0,0] neg_hi:[1,0,0]
	v_pk_fma_f32 v[252:253], v[242:243], v[250:251], 1.0 op_sel_hi:[1,1,0] neg_lo:[1,0,0] neg_hi:[1,0,0]
	v_pk_fma_f32 v[248:249], v[246:247], v[244:245], v[244:245]
	v_pk_fma_f32 v[254:255], v[252:253], v[250:251], v[250:251]
	v_pk_fma_f32 v[246:247], v[240:241], v[248:249], 1.0 op_sel_hi:[1,1,0] neg_lo:[1,0,0] neg_hi:[1,0,0]
	v_pk_fma_f32 v[252:253], v[242:243], v[254:255], 1.0 op_sel_hi:[1,1,0] neg_lo:[1,0,0] neg_hi:[1,0,0]
	v_pk_fma_f32 v[248:249], v[246:247], v[244:245], v[248:249]
	v_pk_fma_f32 v[254:255], v[252:253], v[250:251], v[254:255]
	v_div_fixup_f32 v240, v248, v240, 1.0
	v_div_fixup_f32 v241, v249, v241, 1.0
	v_div_fixup_f32 v242, v254, v242, 1.0
	v_div_fixup_f32 v243, v255, v243, 1.0
	global_store_dwordx4 v[48:49], v[40:43], off
	s_nop 0
	v_pk_mul_f32 v[36:37], v[36:37], v[236:237]
	v_pk_mul_f32 v[32:33], v[32:33], v[238:239]
	v_pk_mul_f32 v[38:39], v[38:39], v[240:241]
	v_pk_mul_f32 v[40:41], v[34:35], v[242:243]
	v_cvt_pk_bf16_f32 v34, v36, v37
	v_cvt_pk_bf16_f32 v35, v38, v39
	v_cvt_pk_bf16_f32 v36, v32, v33
	v_add_u32_e32 v32, 0xa0, v160
	v_mad_i64_i32 v[32:33], s[6:7], v32, s61, v[146:147]
	v_lshl_add_u64 v[32:33], v[32:33], 0, v[148:149]
	v_add_co_u32_e32 v42, vcc, s62, v32
	v_cvt_pk_bf16_f32 v37, v40, v41
	global_store_dwordx4 v[48:49], v[34:37], off offset:256
	s_nop 0
	v_addc_co_u32_e32 v43, vcc, 0, v33, vcc
	s_waitcnt vmcnt(9)
	v_mov_b32_e32 v38, v200
	v_mov_b32_e32 v39, v201
	v_mov_b32_e32 v40, v202
	v_mov_b32_e32 v41, v203
	s_mov_b32 s100, 0xbfb8aa3b
	v_lshlrev_b32_e32 v236, 16, v38
	v_and_b32_e32 v237, 0xffff0000, v38
	v_lshlrev_b32_e32 v238, 16, v40
	v_and_b32_e32 v239, 0xffff0000, v40
	v_lshlrev_b32_e32 v240, 16, v39
	v_and_b32_e32 v241, 0xffff0000, v39
	v_lshlrev_b32_e32 v242, 16, v41
	v_and_b32_e32 v243, 0xffff0000, v41
	v_pk_mul_f32 v[236:237], v[236:237], s[100:101] op_sel_hi:[1,0]
	v_pk_mul_f32 v[238:239], v[238:239], s[100:101] op_sel_hi:[1,0]
	v_pk_mul_f32 v[240:241], v[240:241], s[100:101] op_sel_hi:[1,0]
	v_pk_mul_f32 v[242:243], v[242:243], s[100:101] op_sel_hi:[1,0]
	v_exp_f32_e32 v236, v236
	v_exp_f32_e32 v237, v237
	v_exp_f32_e32 v238, v238
	v_exp_f32_e32 v239, v239
	v_exp_f32_e32 v240, v240
	v_exp_f32_e32 v241, v241
	v_exp_f32_e32 v242, v242
	v_exp_f32_e32 v243, v243
	s_nop 0
	v_pk_add_f32 v[236:237], v[236:237], 1.0 op_sel_hi:[1,0]
	v_pk_add_f32 v[238:239], v[238:239], 1.0 op_sel_hi:[1,0]
	v_pk_add_f32 v[240:241], v[240:241], 1.0 op_sel_hi:[1,0]
	v_pk_add_f32 v[242:243], v[242:243], 1.0 op_sel_hi:[1,0]
	v_rcp_f32_e32 v244, v236
	v_rcp_f32_e32 v245, v237
	v_rcp_f32_e32 v250, v238
	v_rcp_f32_e32 v251, v239
	v_pk_fma_f32 v[246:247], v[236:237], v[244:245], 1.0 op_sel_hi:[1,1,0] neg_lo:[1,0,0] neg_hi:[1,0,0]
	v_pk_fma_f32 v[252:253], v[238:239], v[250:251], 1.0 op_sel_hi:[1,1,0] neg_lo:[1,0,0] neg_hi:[1,0,0]
	v_pk_fma_f32 v[244:245], v[246:247], v[244:245], v[244:245]
	v_pk_fma_f32 v[250:251], v[252:253], v[250:251], v[250:251]
	v_pk_fma_f32 v[246:247], v[236:237], v[244:245], 1.0 op_sel_hi:[1,1,0] neg_lo:[1,0,0] neg_hi:[1,0,0]
	v_pk_fma_f32 v[252:253], v[238:239], v[250:251], 1.0 op_sel_hi:[1,1,0] neg_lo:[1,0,0] neg_hi:[1,0,0]
	v_pk_fma_f32 v[248:249], v[246:247], v[244:245], v[244:245]
	v_pk_fma_f32 v[254:255], v[252:253], v[250:251], v[250:251]
	v_pk_fma_f32 v[246:247], v[236:237], v[248:249], 1.0 op_sel_hi:[1,1,0] neg_lo:[1,0,0] neg_hi:[1,0,0]
	v_pk_fma_f32 v[252:253], v[238:239], v[254:255], 1.0 op_sel_hi:[1,1,0] neg_lo:[1,0,0] neg_hi:[1,0,0]
	v_pk_fma_f32 v[248:249], v[246:247], v[244:245], v[248:249]
	v_pk_fma_f32 v[254:255], v[252:253], v[250:251], v[254:255]
	v_div_fixup_f32 v236, v248, v236, 1.0
	v_div_fixup_f32 v237, v249, v237, 1.0
	v_div_fixup_f32 v238, v254, v238, 1.0
	v_div_fixup_f32 v239, v255, v239, 1.0
	v_rcp_f32_e32 v244, v240
	v_rcp_f32_e32 v245, v241
	v_rcp_f32_e32 v250, v242
	v_rcp_f32_e32 v251, v243
	v_pk_fma_f32 v[246:247], v[240:241], v[244:245], 1.0 op_sel_hi:[1,1,0] neg_lo:[1,0,0] neg_hi:[1,0,0]
	v_pk_fma_f32 v[252:253], v[242:243], v[250:251], 1.0 op_sel_hi:[1,1,0] neg_lo:[1,0,0] neg_hi:[1,0,0]
	v_pk_fma_f32 v[244:245], v[246:247], v[244:245], v[244:245]
	v_pk_fma_f32 v[250:251], v[252:253], v[250:251], v[250:251]
	v_pk_fma_f32 v[246:247], v[240:241], v[244:245], 1.0 op_sel_hi:[1,1,0] neg_lo:[1,0,0] neg_hi:[1,0,0]
	v_pk_fma_f32 v[252:253], v[242:243], v[250:251], 1.0 op_sel_hi:[1,1,0] neg_lo:[1,0,0] neg_hi:[1,0,0]
	v_pk_fma_f32 v[248:249], v[246:247], v[244:245], v[244:245]
	v_pk_fma_f32 v[254:255], v[252:253], v[250:251], v[250:251]
	v_pk_fma_f32 v[246:247], v[240:241], v[248:249], 1.0 op_sel_hi:[1,1,0] neg_lo:[1,0,0] neg_hi:[1,0,0]
	v_pk_fma_f32 v[252:253], v[242:243], v[254:255], 1.0 op_sel_hi:[1,1,0] neg_lo:[1,0,0] neg_hi:[1,0,0]
	v_pk_fma_f32 v[248:249], v[246:247], v[244:245], v[248:249]
	v_pk_fma_f32 v[254:255], v[252:253], v[250:251], v[254:255]
	v_div_fixup_f32 v240, v248, v240, 1.0
	v_div_fixup_f32 v241, v249, v241, 1.0
	v_div_fixup_f32 v242, v254, v242, 1.0
	v_div_fixup_f32 v243, v255, v243, 1.0
	v_mul_f32_e32 v28, v28, v236
	v_mul_f32_e32 v34, v24, v238
	v_mul_f32_e32 v24, v29, v237
	v_mul_f32_e32 v29, v25, v239
	v_mul_f32_e32 v25, v30, v240
	v_mul_f32_e32 v30, v26, v242
	v_mul_f32_e32 v26, v31, v241
	v_mul_f32_e32 v27, v27, v243
	v_cvt_pk_bf16_f32 v24, v28, v24
	v_cvt_pk_bf16_f32 v25, v25, v26
	v_cvt_pk_bf16_f32 v26, v34, v29
	v_cvt_pk_bf16_f32 v27, v30, v27
	s_waitcnt vmcnt(8)
; __device__ __forceinline__ u32x4 pack8(const f32x4 v0, const f32x4 v1) { u32x4 w; w.x = pk2(v0[0], v0[1]); w.y = pk2(v0[2], v0[3]); w.z = pk2(v1[0], v1[1]); w.w = pk2(v1[2], v1[3]); return w; }
; __device__ __forceinline__ void unpack8(const u32x4 w, f32x4& v0, f32x4& v1) { v0 = (f32x4){bflo(w.x), bfhi(w.x), bflo(w.y), bfhi(w.y)}; v1 = (f32x4){bflo(w.z), bfhi(w.z), bflo(w.w), bfhi(w.w)}; }
; __device__ __forceinline__ float sigmoidf_(float x) { return 1.0f / (1.0f + __expf(-x)); }
;     __device__ __forceinline__ void operator()(const f32x4 (&acc)[2][2][4][2], const Unit& u, int wr, int wc, int fr, int fq) const {
;         const int row0 = u.pm * 256 + wr * 64 + fr, col0 = u.pn * 256 + wc * 32 + 8 * fq;
; #pragma unroll
;         for (int ai = 0; ai < 2; ++ai)
; #pragma unroll
;             for (int m = 0; m < 4; ++m) {
;                 bf16_t* rowp = z + (size_t)(row0 + ai * 128 + m * 16) * DIN + col0;
; #pragma unroll
;                 for (int bj = 0; bj < 2; ++bj) {
;                     const u32x4 gw = *(const u32x4*)(rowp + (MODE == 0 ? O_GB : O_GA) + bj * 128);
;                     f32x4 g0, g1; unpack8(gw, g0, g1);
;                     f32x4 v0, v1;
; #pragma unroll
;                     for (int j = 0; j < 4; ++j) { v0[j] = sigmoidf_(g0[j]) * acc[ai][bj][m][0][j]; v1[j] = sigmoidf_(g1[j]) * acc[ai][bj][m][1][j]; }
;                     if (MODE == 1) { const u32x4 mw = *(const u32x4*)(rowp + bj * 128); f32x4 m0, m1; unpack8(mw, m0, m1); v0 += m0; v1 += m1; }
;                     *(u32x4*)(rowp + bj * 128) = pack8(v0, v1); }
	v_mov_b32_e32 v28, v204
	v_mov_b32_e32 v29, v205
	v_mov_b32_e32 v30, v206
	v_mov_b32_e32 v31, v207
	s_mov_b32 s100, 0xbfb8aa3b
	v_lshlrev_b32_e32 v236, 16, v28
	v_and_b32_e32 v237, 0xffff0000, v28
	v_lshlrev_b32_e32 v238, 16, v30
	v_and_b32_e32 v239, 0xffff0000, v30
	v_lshlrev_b32_e32 v240, 16, v29
	v_and_b32_e32 v241, 0xffff0000, v29
	v_lshlrev_b32_e32 v242, 16, v31
	v_and_b32_e32 v243, 0xffff0000, v31
	v_pk_mul_f32 v[236:237], v[236:237], s[100:101] op_sel_hi:[1,0]
	v_pk_mul_f32 v[238:239], v[238:239], s[100:101] op_sel_hi:[1,0]
	v_pk_mul_f32 v[240:241], v[240:241], s[100:101] op_sel_hi:[1,0]
	v_pk_mul_f32 v[242:243], v[242:243], s[100:101] op_sel_hi:[1,0]
	v_exp_f32_e32 v236, v236
	v_exp_f32_e32 v237, v237
	v_exp_f32_e32 v238, v238
	v_exp_f32_e32 v239, v239
	v_exp_f32_e32 v240, v240
	v_exp_f32_e32 v241, v241
	v_exp_f32_e32 v242, v242
	v_exp_f32_e32 v243, v243
	s_nop 0
	v_pk_add_f32 v[236:237], v[236:237], 1.0 op_sel_hi:[1,0]
	v_pk_add_f32 v[238:239], v[238:239], 1.0 op_sel_hi:[1,0]
	v_pk_add_f32 v[240:241], v[240:241], 1.0 op_sel_hi:[1,0]
	v_pk_add_f32 v[242:243], v[242:243], 1.0 op_sel_hi:[1,0]
	v_rcp_f32_e32 v244, v236
	v_rcp_f32_e32 v245, v237
	v_rcp_f32_e32 v250, v238
	v_rcp_f32_e32 v251, v239
	v_pk_fma_f32 v[246:247], v[236:237], v[244:245], 1.0 op_sel_hi:[1,1,0] neg_lo:[1,0,0] neg_hi:[1,0,0]
	v_pk_fma_f32 v[252:253], v[238:239], v[250:251], 1.0 op_sel_hi:[1,1,0] neg_lo:[1,0,0] neg_hi:[1,0,0]
	v_pk_fma_f32 v[244:245], v[246:247], v[244:245], v[244:245]
	v_pk_fma_f32 v[250:251], v[252:253], v[250:251], v[250:251]
	v_pk_fma_f32 v[246:247], v[236:237], v[244:245], 1.0 op_sel_hi:[1,1,0] neg_lo:[1,0,0] neg_hi:[1,0,0]
	v_pk_fma_f32 v[252:253], v[238:239], v[250:251], 1.0 op_sel_hi:[1,1,0] neg_lo:[1,0,0] neg_hi:[1,0,0]
	v_pk_fma_f32 v[248:249], v[246:247], v[244:245], v[244:245]
	v_pk_fma_f32 v[254:255], v[252:253], v[250:251], v[250:251]
	v_pk_fma_f32 v[246:247], v[236:237], v[248:249], 1.0 op_sel_hi:[1,1,0] neg_lo:[1,0,0] neg_hi:[1,0,0]
	v_pk_fma_f32 v[252:253], v[238:239], v[254:255], 1.0 op_sel_hi:[1,1,0] neg_lo:[1,0,0] neg_hi:[1,0,0]
	v_pk_fma_f32 v[248:249], v[246:247], v[244:245], v[248:249]
	v_pk_fma_f32 v[254:255], v[252:253], v[250:251], v[254:255]
	v_div_fixup_f32 v236, v248, v236, 1.0
	v_div_fixup_f32 v237, v249, v237, 1.0
	v_div_fixup_f32 v238, v254, v238, 1.0
	v_div_fixup_f32 v239, v255, v239, 1.0
	v_rcp_f32_e32 v244, v240
	v_rcp_f32_e32 v245, v241
	v_rcp_f32_e32 v250, v242
	v_rcp_f32_e32 v251, v243
	v_pk_fma_f32 v[246:247], v[240:241], v[244:245], 1.0 op_sel_hi:[1,1,0] neg_lo:[1,0,0] neg_hi:[1,0,0]
	v_pk_fma_f32 v[252:253], v[242:243], v[250:251], 1.0 op_sel_hi:[1,1,0] neg_lo:[1,0,0] neg_hi:[1,0,0]
	v_pk_fma_f32 v[244:245], v[246:247], v[244:245], v[244:245]
	v_pk_fma_f32 v[250:251], v[252:253], v[250:251], v[250:251]
	v_pk_fma_f32 v[246:247], v[240:241], v[244:245], 1.0 op_sel_hi:[1,1,0] neg_lo:[1,0,0] neg_hi:[1,0,0]
	v_pk_fma_f32 v[252:253], v[242:243], v[250:251], 1.0 op_sel_hi:[1,1,0] neg_lo:[1,0,0] neg_hi:[1,0,0]
	v_pk_fma_f32 v[248:249], v[246:247], v[244:245], v[244:245]
	v_pk_fma_f32 v[254:255], v[252:253], v[250:251], v[250:251]
	v_pk_fma_f32 v[246:247], v[240:241], v[248:249], 1.0 op_sel_hi:[1,1,0] neg_lo:[1,0,0] neg_hi:[1,0,0]
	v_pk_fma_f32 v[252:253], v[242:243], v[254:255], 1.0 op_sel_hi:[1,1,0] neg_lo:[1,0,0] neg_hi:[1,0,0]
	v_pk_fma_f32 v[248:249], v[246:247], v[244:245], v[248:249]
	v_pk_fma_f32 v[254:255], v[252:253], v[250:251], v[254:255]
	v_div_fixup_f32 v240, v248, v240, 1.0
	v_div_fixup_f32 v241, v249, v241, 1.0
	v_div_fixup_f32 v242, v254, v242, 1.0
	v_div_fixup_f32 v243, v255, v243, 1.0
	global_store_dwordx4 v[32:33], v[24:27], off
	s_nop 0
	v_pk_mul_f32 v[20:21], v[20:21], v[236:237]
	v_pk_mul_f32 v[16:17], v[16:17], v[238:239]
	v_pk_mul_f32 v[22:23], v[22:23], v[240:241]
	v_pk_mul_f32 v[24:25], v[18:19], v[242:243]
	v_cvt_pk_bf16_f32 v18, v20, v21
	v_cvt_pk_bf16_f32 v19, v22, v23
	v_cvt_pk_bf16_f32 v20, v16, v17
	v_add_u32_e32 v16, 0xb0, v160
	v_mad_i64_i32 v[16:17], s[6:7], v16, s61, v[146:147]
	v_lshl_add_u64 v[16:17], v[16:17], 0, v[148:149]
	v_add_co_u32_e32 v26, vcc, s62, v16
	v_cvt_pk_bf16_f32 v21, v24, v25
	global_store_dwordx4 v[32:33], v[18:21], off offset:256
	s_nop 0
	v_addc_co_u32_e32 v27, vcc, 0, v17, vcc
	s_waitcnt vmcnt(7)
; __device__ __forceinline__ u32x4 pack8(const f32x4 v0, const f32x4 v1) { u32x4 w; w.x = pk2(v0[0], v0[1]); w.y = pk2(v0[2], v0[3]); w.z = pk2(v1[0], v1[1]); w.w = pk2(v1[2], v1[3]); return w; }
; __device__ __forceinline__ void unpack8(const u32x4 w, f32x4& v0, f32x4& v1) { v0 = (f32x4){bflo(w.x), bfhi(w.x), bflo(w.y), bfhi(w.y)}; v1 = (f32x4){bflo(w.z), bfhi(w.z), bflo(w.w), bfhi(w.w)}; }
; __device__ __forceinline__ float sigmoidf_(float x) { return 1.0f / (1.0f + __expf(-x)); }
;     __device__ __forceinline__ void operator()(const f32x4 (&acc)[2][2][4][2], const Unit& u, int wr, int wc, int fr, int fq) const {
;         const int row0 = u.pm * 256 + wr * 64 + fr, col0 = u.pn * 256 + wc * 32 + 8 * fq;
; #pragma unroll
;         for (int ai = 0; ai < 2; ++ai)
; #pragma unroll
;             for (int m = 0; m < 4; ++m) {
;                 bf16_t* rowp = z + (size_t)(row0 + ai * 128 + m * 16) * DIN + col0;
; #pragma unroll
;                 for (int bj = 0; bj < 2; ++bj) {
;                     const u32x4 gw = *(const u32x4*)(rowp + (MODE == 0 ? O_GB : O_GA) + bj * 128);
;                     f32x4 g0, g1; unpack8(gw, g0, g1);
;                     f32x4 v0, v1;
; #pragma unroll
;                     for (int j = 0; j < 4; ++j) { v0[j] = sigmoidf_(g0[j]) * acc[ai][bj][m][0][j]; v1[j] = sigmoidf_(g1[j]) * acc[ai][bj][m][1][j]; }
;                     if (MODE == 1) { const u32x4 mw = *(const u32x4*)(rowp + bj * 128); f32x4 m0, m1; unpack8(mw, m0, m1); v0 += m0; v1 += m1; }
;                     *(u32x4*)(rowp + bj * 128) = pack8(v0, v1); }
	v_mov_b32_e32 v22, v208
	v_mov_b32_e32 v23, v209
	v_mov_b32_e32 v24, v210
	v_mov_b32_e32 v25, v211
	s_mov_b32 s100, 0xbfb8aa3b
	v_lshlrev_b32_e32 v236, 16, v22
	v_and_b32_e32 v237, 0xffff0000, v22
	v_lshlrev_b32_e32 v238, 16, v24
	v_and_b32_e32 v239, 0xffff0000, v24
	v_lshlrev_b32_e32 v240, 16, v23
	v_and_b32_e32 v241, 0xffff0000, v23
	v_lshlrev_b32_e32 v242, 16, v25
	v_and_b32_e32 v243, 0xffff0000, v25
	v_pk_mul_f32 v[236:237], v[236:237], s[100:101] op_sel_hi:[1,0]
	v_pk_mul_f32 v[238:239], v[238:239], s[100:101] op_sel_hi:[1,0]
	v_pk_mul_f32 v[240:241], v[240:241], s[100:101] op_sel_hi:[1,0]
	v_pk_mul_f32 v[242:243], v[242:243], s[100:101] op_sel_hi:[1,0]
	v_exp_f32_e32 v236, v236
	v_exp_f32_e32 v237, v237
	v_exp_f32_e32 v238, v238
	v_exp_f32_e32 v239, v239
	v_exp_f32_e32 v240, v240
	v_exp_f32_e32 v241, v241
	v_exp_f32_e32 v242, v242
	v_exp_f32_e32 v243, v243
	s_nop 0
	v_pk_add_f32 v[236:237], v[236:237], 1.0 op_sel_hi:[1,0]
	v_pk_add_f32 v[238:239], v[238:239], 1.0 op_sel_hi:[1,0]
	v_pk_add_f32 v[240:241], v[240:241], 1.0 op_sel_hi:[1,0]
	v_pk_add_f32 v[242:243], v[242:243], 1.0 op_sel_hi:[1,0]
	v_rcp_f32_e32 v244, v236
	v_rcp_f32_e32 v245, v237
	v_rcp_f32_e32 v250, v238
	v_rcp_f32_e32 v251, v239
	v_pk_fma_f32 v[246:247], v[236:237], v[244:245], 1.0 op_sel_hi:[1,1,0] neg_lo:[1,0,0] neg_hi:[1,0,0]
	v_pk_fma_f32 v[252:253], v[238:239], v[250:251], 1.0 op_sel_hi:[1,1,0] neg_lo:[1,0,0] neg_hi:[1,0,0]
	v_pk_fma_f32 v[244:245], v[246:247], v[244:245], v[244:245]
	v_pk_fma_f32 v[250:251], v[252:253], v[250:251], v[250:251]
	v_pk_fma_f32 v[246:247], v[236:237], v[244:245], 1.0 op_sel_hi:[1,1,0] neg_lo:[1,0,0] neg_hi:[1,0,0]
	v_pk_fma_f32 v[252:253], v[238:239], v[250:251], 1.0 op_sel_hi:[1,1,0] neg_lo:[1,0,0] neg_hi:[1,0,0]
	v_pk_fma_f32 v[248:249], v[246:247], v[244:245], v[244:245]
	v_pk_fma_f32 v[254:255], v[252:253], v[250:251], v[250:251]
	v_pk_fma_f32 v[246:247], v[236:237], v[248:249], 1.0 op_sel_hi:[1,1,0] neg_lo:[1,0,0] neg_hi:[1,0,0]
	v_pk_fma_f32 v[252:253], v[238:239], v[254:255], 1.0 op_sel_hi:[1,1,0] neg_lo:[1,0,0] neg_hi:[1,0,0]
	v_pk_fma_f32 v[248:249], v[246:247], v[244:245], v[248:249]
	v_pk_fma_f32 v[254:255], v[252:253], v[250:251], v[254:255]
	v_div_fixup_f32 v236, v248, v236, 1.0
	v_div_fixup_f32 v237, v249, v237, 1.0
	v_div_fixup_f32 v238, v254, v238, 1.0
	v_div_fixup_f32 v239, v255, v239, 1.0
	v_rcp_f32_e32 v244, v240
	v_rcp_f32_e32 v245, v241
	v_rcp_f32_e32 v250, v242
	v_rcp_f32_e32 v251, v243
	v_pk_fma_f32 v[246:247], v[240:241], v[244:245], 1.0 op_sel_hi:[1,1,0] neg_lo:[1,0,0] neg_hi:[1,0,0]
	v_pk_fma_f32 v[252:253], v[242:243], v[250:251], 1.0 op_sel_hi:[1,1,0] neg_lo:[1,0,0] neg_hi:[1,0,0]
	v_pk_fma_f32 v[244:245], v[246:247], v[244:245], v[244:245]
	v_pk_fma_f32 v[250:251], v[252:253], v[250:251], v[250:251]
	v_pk_fma_f32 v[246:247], v[240:241], v[244:245], 1.0 op_sel_hi:[1,1,0] neg_lo:[1,0,0] neg_hi:[1,0,0]
	v_pk_fma_f32 v[252:253], v[242:243], v[250:251], 1.0 op_sel_hi:[1,1,0] neg_lo:[1,0,0] neg_hi:[1,0,0]
	v_pk_fma_f32 v[248:249], v[246:247], v[244:245], v[244:245]
	v_pk_fma_f32 v[254:255], v[252:253], v[250:251], v[250:251]
	v_pk_fma_f32 v[246:247], v[240:241], v[248:249], 1.0 op_sel_hi:[1,1,0] neg_lo:[1,0,0] neg_hi:[1,0,0]
	v_pk_fma_f32 v[252:253], v[242:243], v[254:255], 1.0 op_sel_hi:[1,1,0] neg_lo:[1,0,0] neg_hi:[1,0,0]
	v_pk_fma_f32 v[248:249], v[246:247], v[244:245], v[248:249]
	v_pk_fma_f32 v[254:255], v[252:253], v[250:251], v[254:255]
	v_div_fixup_f32 v240, v248, v240, 1.0
	v_div_fixup_f32 v241, v249, v241, 1.0
	v_div_fixup_f32 v242, v254, v242, 1.0
	v_div_fixup_f32 v243, v255, v243, 1.0
	v_mul_f32_e32 v12, v12, v236
	v_mul_f32_e32 v18, v8, v238
	v_mul_f32_e32 v8, v13, v237
	v_mul_f32_e32 v13, v9, v239
	v_mul_f32_e32 v9, v14, v240
	v_mul_f32_e32 v14, v10, v242
	v_mul_f32_e32 v10, v15, v241
	v_mul_f32_e32 v11, v11, v243
	v_cvt_pk_bf16_f32 v8, v12, v8
	v_cvt_pk_bf16_f32 v9, v9, v10
	v_cvt_pk_bf16_f32 v10, v18, v13
	v_cvt_pk_bf16_f32 v11, v14, v11
	s_waitcnt vmcnt(6)
; #define PG8_WAIT_V(n) asm volatile("s_waitcnt vmcnt(" #n ")" ::: "memory")
; #define PG8_BAR __builtin_amdgcn_s_barrier()
; __device__ __forceinline__ u32x4 pack8(const f32x4 v0, const f32x4 v1) { u32x4 w; w.x = pk2(v0[0], v0[1]); w.y = pk2(v0[2], v0[3]); w.z = pk2(v1[0], v1[1]); w.w = pk2(v1[2], v1[3]); return w; }
; __device__ __forceinline__ void unpack8(const u32x4 w, f32x4& v0, f32x4& v1) { v0 = (f32x4){bflo(w.x), bfhi(w.x), bflo(w.y), bfhi(w.y)}; v1 = (f32x4){bflo(w.z), bfhi(w.z), bflo(w.w), bfhi(w.w)}; }
; __device__ __forceinline__ float sigmoidf_(float x) { return 1.0f / (1.0f + __expf(-x)); }
;     ...
;         if (!has_next) break;
; #pragma unroll
;         for (int a = 0; a < 2; ++a)
; #pragma unroll
;             for (int b = 0; b < 2; ++b)
; #pragma unroll
;                 for (int m = 0; m < 4; ++m)
; #pragma unroll
;                     for (int n = 0; n < 2; ++n) acc[a][b][m][n] = (f32x4){0.f, 0.f, 0.f, 0.f};
;         cur = nxt; cA = nA; cB = nB; ++ui;
;     }
;     PG8_WAIT_V(0);
;     if (wr == 0) PG8_BAR;
;     PG8_BAR;
;     __device__ __forceinline__ void operator()(const f32x4 (&acc)[2][2][4][2], const Unit& u, int wr, int wc, int fr, int fq) const {
;         const int row0 = u.pm * 256 + wr * 64 + fr, col0 = u.pn * 256 + wc * 32 + 8 * fq;
; #pragma unroll
;         for (int ai = 0; ai < 2; ++ai)
; #pragma unroll
;             for (int m = 0; m < 4; ++m) {
;                 bf16_t* rowp = z + (size_t)(row0 + ai * 128 + m * 16) * DIN + col0;
; #pragma unroll
;                 for (int bj = 0; bj < 2; ++bj) {
;                     const u32x4 gw = *(const u32x4*)(rowp + (MODE == 0 ? O_GB : O_GA) + bj * 128);
;                     f32x4 g0, g1; unpack8(gw, g0, g1);
;                     f32x4 v0, v1;
; #pragma unroll
;                     for (int j = 0; j < 4; ++j) { v0[j] = sigmoidf_(g0[j]) * acc[ai][bj][m][0][j]; v1[j] = sigmoidf_(g1[j]) * acc[ai][bj][m][1][j]; }
;                     if (MODE == 1) { const u32x4 mw = *(const u32x4*)(rowp + bj * 128); f32x4 m0, m1; unpack8(mw, m0, m1); v0 += m0; v1 += m1; }
;                     *(u32x4*)(rowp + bj * 128) = pack8(v0, v1); }
	v_mov_b32_e32 v12, v212
	v_mov_b32_e32 v13, v213
	v_mov_b32_e32 v14, v214
	v_mov_b32_e32 v15, v215
	s_mov_b32 s100, 0xbfb8aa3b
	v_lshlrev_b32_e32 v236, 16, v12
	v_and_b32_e32 v237, 0xffff0000, v12
	v_lshlrev_b32_e32 v238, 16, v14
	v_and_b32_e32 v239, 0xffff0000, v14
	v_lshlrev_b32_e32 v240, 16, v13
	v_and_b32_e32 v241, 0xffff0000, v13
	v_lshlrev_b32_e32 v242, 16, v15
	v_and_b32_e32 v243, 0xffff0000, v15
	v_pk_mul_f32 v[236:237], v[236:237], s[100:101] op_sel_hi:[1,0]
	v_pk_mul_f32 v[238:239], v[238:239], s[100:101] op_sel_hi:[1,0]
	v_pk_mul_f32 v[240:241], v[240:241], s[100:101] op_sel_hi:[1,0]
	v_pk_mul_f32 v[242:243], v[242:243], s[100:101] op_sel_hi:[1,0]
	v_exp_f32_e32 v236, v236
	v_exp_f32_e32 v237, v237
	v_exp_f32_e32 v238, v238
	v_exp_f32_e32 v239, v239
	v_exp_f32_e32 v240, v240
	v_exp_f32_e32 v241, v241
	v_exp_f32_e32 v242, v242
	v_exp_f32_e32 v243, v243
	s_nop 0
	v_pk_add_f32 v[236:237], v[236:237], 1.0 op_sel_hi:[1,0]
	v_pk_add_f32 v[238:239], v[238:239], 1.0 op_sel_hi:[1,0]
	v_pk_add_f32 v[240:241], v[240:241], 1.0 op_sel_hi:[1,0]
	v_pk_add_f32 v[242:243], v[242:243], 1.0 op_sel_hi:[1,0]
	v_rcp_f32_e32 v244, v236
	v_rcp_f32_e32 v245, v237
	v_rcp_f32_e32 v250, v238
	v_rcp_f32_e32 v251, v239
	v_pk_fma_f32 v[246:247], v[236:237], v[244:245], 1.0 op_sel_hi:[1,1,0] neg_lo:[1,0,0] neg_hi:[1,0,0]
	v_pk_fma_f32 v[252:253], v[238:239], v[250:251], 1.0 op_sel_hi:[1,1,0] neg_lo:[1,0,0] neg_hi:[1,0,0]
	v_pk_fma_f32 v[244:245], v[246:247], v[244:245], v[244:245]
	v_pk_fma_f32 v[250:251], v[252:253], v[250:251], v[250:251]
	v_pk_fma_f32 v[246:247], v[236:237], v[244:245], 1.0 op_sel_hi:[1,1,0] neg_lo:[1,0,0] neg_hi:[1,0,0]
	v_pk_fma_f32 v[252:253], v[238:239], v[250:251], 1.0 op_sel_hi:[1,1,0] neg_lo:[1,0,0] neg_hi:[1,0,0]
	v_pk_fma_f32 v[248:249], v[246:247], v[244:245], v[244:245]
	v_pk_fma_f32 v[254:255], v[252:253], v[250:251], v[250:251]
	v_pk_fma_f32 v[246:247], v[236:237], v[248:249], 1.0 op_sel_hi:[1,1,0] neg_lo:[1,0,0] neg_hi:[1,0,0]
	v_pk_fma_f32 v[252:253], v[238:239], v[254:255], 1.0 op_sel_hi:[1,1,0] neg_lo:[1,0,0] neg_hi:[1,0,0]
	v_pk_fma_f32 v[248:249], v[246:247], v[244:245], v[248:249]
	v_pk_fma_f32 v[254:255], v[252:253], v[250:251], v[254:255]
	v_div_fixup_f32 v236, v248, v236, 1.0
	v_div_fixup_f32 v237, v249, v237, 1.0
	v_div_fixup_f32 v238, v254, v238, 1.0
	v_div_fixup_f32 v239, v255, v239, 1.0
	v_rcp_f32_e32 v244, v240
	v_rcp_f32_e32 v245, v241
	v_rcp_f32_e32 v250, v242
	v_rcp_f32_e32 v251, v243
	v_pk_fma_f32 v[246:247], v[240:241], v[244:245], 1.0 op_sel_hi:[1,1,0] neg_lo:[1,0,0] neg_hi:[1,0,0]
	v_pk_fma_f32 v[252:253], v[242:243], v[250:251], 1.0 op_sel_hi:[1,1,0] neg_lo:[1,0,0] neg_hi:[1,0,0]
	v_pk_fma_f32 v[244:245], v[246:247], v[244:245], v[244:245]
	v_pk_fma_f32 v[250:251], v[252:253], v[250:251], v[250:251]
	v_pk_fma_f32 v[246:247], v[240:241], v[244:245], 1.0 op_sel_hi:[1,1,0] neg_lo:[1,0,0] neg_hi:[1,0,0]
	v_pk_fma_f32 v[252:253], v[242:243], v[250:251], 1.0 op_sel_hi:[1,1,0] neg_lo:[1,0,0] neg_hi:[1,0,0]
	v_pk_fma_f32 v[248:249], v[246:247], v[244:245], v[244:245]
	v_pk_fma_f32 v[254:255], v[252:253], v[250:251], v[250:251]
	v_pk_fma_f32 v[246:247], v[240:241], v[248:249], 1.0 op_sel_hi:[1,1,0] neg_lo:[1,0,0] neg_hi:[1,0,0]
	v_pk_fma_f32 v[252:253], v[242:243], v[254:255], 1.0 op_sel_hi:[1,1,0] neg_lo:[1,0,0] neg_hi:[1,0,0]
	v_pk_fma_f32 v[248:249], v[246:247], v[244:245], v[248:249]
	v_pk_fma_f32 v[254:255], v[252:253], v[250:251], v[254:255]
	v_div_fixup_f32 v240, v248, v240, 1.0
	v_div_fixup_f32 v241, v249, v241, 1.0
	v_div_fixup_f32 v242, v254, v242, 1.0
	v_div_fixup_f32 v243, v255, v243, 1.0
	global_store_dwordx4 v[16:17], v[8:11], off
	s_nop 0
	v_mul_f32_e32 v4, v4, v236
	v_mul_f32_e32 v8, v0, v238
	v_mul_f32_e32 v0, v5, v237
	v_mul_f32_e32 v5, v1, v239
	v_mul_f32_e32 v1, v6, v240
	v_mul_f32_e32 v6, v2, v242
	v_mul_f32_e32 v2, v7, v241
	v_mul_f32_e32 v3, v3, v243
	s_and_b64 vcc, exec, s[10:11]
	s_mov_b32 s7, s28
	s_mov_b32 s6, s63
	v_cvt_pk_bf16_f32 v0, v4, v0
	v_cvt_pk_bf16_f32 v1, v1, v2
	v_cvt_pk_bf16_f32 v2, v8, v5
	v_cvt_pk_bf16_f32 v3, v6, v3
	global_store_dwordx4 v[16:17], v[0:3], off offset:256
	s_cbranch_vccz .LBB0_622
	s_waitcnt vmcnt(0)
	s_cmpk_gt_u32 s36, 0xff
	s_cbranch_scc1 .LBB0_631
	s_barrier

; #define PG8_STAGE(bufoff, gbase, voff) do { _Pragma("unroll") for (int _i = 0; _i < 2; ++_i) \
;         __builtin_amdgcn_global_load_lds((const unsigned*)((const char*)(gbase) + (voff)[_i]), (LAS unsigned*)(lds + (bufoff) + ldsw + _i * 8192), 16, 0, 0); } while (0)
; #define PG8_LDA(dst, b, h) do { _Pragma("unroll") for (int m = 0; m < 4; ++m) _Pragma("unroll") for (int k = 0; k < 2; ++k) dst[m][k] = *(const LAS bf16x8*)(lds + PG8_SA(b, h) + aoff + m * 2048 + k * 1024); } while (0)
; #define PG8_LDB(dst, b, h) do { _Pragma("unroll") for (int n = 0; n < 2; ++n) _Pragma("unroll") for (int k = 0; k < 2; ++k) dst[n][k] = *(const LAS bf16x8*)(lds + PG8_SB(b, h) + boff + n * 2048 + k * 1024); } while (0)
; #define PG8_MMA(ai, bj, At, Bt) do { __builtin_amdgcn_s_setprio(1); _Pragma("unroll") for (int m = 0; m < 4; ++m) _Pragma("unroll") for (int n = 0; n < 2; ++n) _Pragma("unroll") for (int k = 0; k < 2; ++k) \
;         acc[ai][bj][m][n] = __builtin_amdgcn_mfma_f32_16x16x32_bf16(Bt[n][k], At[m][k], acc[ai][bj][m][n], 0, 0, 0); __builtin_amdgcn_s_setprio(0); } while (0)
; #define PG8_WAIT_L(n) asm volatile("s_waitcnt lgkmcnt(" #n ")" ::: "memory")
; #define PG8_BAR __builtin_amdgcn_s_barrier()
; #define PG8_SCHED __builtin_amdgcn_sched_barrier(0)
;     ...
;             PG8_LDB(B0, 0, 0); PG8_SCHED; PG8_LDA(At, 0, 0); PG8_STAGE(PG8_SA(1, 1), a1 + hA, voffA);
;             PG8_WAIT_L(8); PG8_BAR; PG8_WAIT_L(0); PG8_MMA(0, 0, At, B0); PG8_BAR; PG8_SCHED;
;             PG8_LDB(B1, 0, 1); PG8_STAGE(PG8_SB(0, 0), b2, voffB);
;             PG8_BAR; PG8_WAIT_L(0); PG8_MMA(0, 1, At, B1); PG8_BAR;
;             PG8_LDA(At, 0, 1); PG8_STAGE(PG8_SA(0, 0), a2, voffA);
;             PG8_BAR; PG8_WAIT_L(0); PG8_MMA(1, 0, At, B0); PG8_BAR; PG8_SCHED;
.LBB0_1768:
	ds_read_b128 v[146:149], v157
	ds_read_b128 v[150:153], v157 offset:1024
	ds_read_b128 v[160:163], v157 offset:2048
	ds_read_b128 v[170:173], v157 offset:3072
	s_add_u32 s10, s12, 0x100
	s_addc_u32 s11, s13, 0
	s_cmp_eq_u32 s60, 4
	s_cselect_b32 s17, s29, s11
	s_cselect_b32 s16, s28, s10
	s_cselect_b32 s15, s27, s45
	s_cselect_b32 s14, s33, s44
	v_lshl_add_u64 v[164:165], s[12:13], 0, v[138:139]
	s_add_i32 m0, s37, 0xc000
	ds_read_b128 v[174:177], v158
	ds_read_b128 v[178:181], v158 offset:1024
	ds_read_b128 v[182:185], v158 offset:2048
	ds_read_b128 v[186:189], v158 offset:3072
	ds_read_b128 v[190:193], v158 offset:4096
	ds_read_b128 v[194:197], v158 offset:5120
	ds_read_b128 v[198:201], v158 offset:6144
	ds_read_b128 v[202:205], v158 offset:7168
	global_load_lds_dwordx4 v[164:165], off
	v_lshl_add_u64 v[164:165], s[12:13], 0, v[136:137]
	s_add_i32 m0, s37, 0xe000
	s_nop 0
	global_load_lds_dwordx4 v[164:165], off
	s_waitcnt lgkmcnt(8)
	s_barrier
	s_waitcnt lgkmcnt(0)
	s_setprio 1
	s_waitcnt lgkmcnt(0)
	v_mfma_f32_16x16x32_bf16 v[124:127], v[146:149], v[174:177], v[124:127]
	v_mfma_f32_16x16x32_bf16 v[120:123], v[160:163], v[174:177], v[120:123]
	v_mfma_f32_16x16x32_bf16 v[108:111], v[146:149], v[182:185], v[108:111]
	v_mfma_f32_16x16x32_bf16 v[104:107], v[160:163], v[182:185], v[104:107]
	v_mfma_f32_16x16x32_bf16 v[92:95], v[146:149], v[190:193], v[92:95]
	v_mfma_f32_16x16x32_bf16 v[88:91], v[160:163], v[190:193], v[88:91]
	v_mfma_f32_16x16x32_bf16 v[76:79], v[146:149], v[198:201], v[76:79]
	v_mfma_f32_16x16x32_bf16 v[72:75], v[160:163], v[198:201], v[72:75]
	v_mfma_f32_16x16x32_bf16 v[124:127], v[150:153], v[178:181], v[124:127]
	v_mfma_f32_16x16x32_bf16 v[120:123], v[170:173], v[178:181], v[120:123]
	v_mfma_f32_16x16x32_bf16 v[108:111], v[150:153], v[186:189], v[108:111]
	v_mfma_f32_16x16x32_bf16 v[104:107], v[170:173], v[186:189], v[104:107]
	v_mfma_f32_16x16x32_bf16 v[92:95], v[150:153], v[194:197], v[92:95]
	v_mfma_f32_16x16x32_bf16 v[88:91], v[170:173], v[194:197], v[88:91]
	v_mfma_f32_16x16x32_bf16 v[76:79], v[150:153], v[202:205], v[76:79]
	v_mfma_f32_16x16x32_bf16 v[72:75], v[170:173], v[202:205], v[72:75]
	s_setprio 0
	s_barrier
	s_add_i32 s12, s55, s35
	v_lshl_add_u64 v[164:165], s[14:15], 0, v[132:133]
	s_mov_b32 m0, s12
	ds_read_b128 v[206:209], v159
	ds_read_b128 v[210:213], v159 offset:1024
	ds_read_b128 v[214:217], v159 offset:2048
	ds_read_b128 v[218:221], v159 offset:3072
	global_load_lds_dwordx4 v[164:165], off
	v_lshl_add_u64 v[222:223], s[14:15], 0, v[128:129]
	s_add_i32 m0, s12, 0x2000
	s_nop 0
	global_load_lds_dwordx4 v[222:223], off
	s_barrier
	s_waitcnt lgkmcnt(0)
	s_setprio 1
	s_waitcnt lgkmcnt(0)
	v_mfma_f32_16x16x32_bf16 v[116:119], v[206:209], v[174:177], v[116:119]
	v_mfma_f32_16x16x32_bf16 v[112:115], v[214:217], v[174:177], v[112:115]
	v_mfma_f32_16x16x32_bf16 v[100:103], v[206:209], v[182:185], v[100:103]
	v_mfma_f32_16x16x32_bf16 v[96:99], v[214:217], v[182:185], v[96:99]
	v_mfma_f32_16x16x32_bf16 v[84:87], v[206:209], v[190:193], v[84:87]
	v_mfma_f32_16x16x32_bf16 v[80:83], v[214:217], v[190:193], v[80:83]
	v_mfma_f32_16x16x32_bf16 v[68:71], v[206:209], v[198:201], v[68:71]
	v_mfma_f32_16x16x32_bf16 v[64:67], v[214:217], v[198:201], v[64:67]
	v_mfma_f32_16x16x32_bf16 v[116:119], v[210:213], v[178:181], v[116:119]
	v_mfma_f32_16x16x32_bf16 v[112:115], v[218:221], v[178:181], v[112:115]
	v_mfma_f32_16x16x32_bf16 v[100:103], v[210:213], v[186:189], v[100:103]
	v_mfma_f32_16x16x32_bf16 v[96:99], v[218:221], v[186:189], v[96:99]
	v_mfma_f32_16x16x32_bf16 v[84:87], v[210:213], v[194:197], v[84:87]
	v_mfma_f32_16x16x32_bf16 v[80:83], v[218:221], v[194:197], v[80:83]
	v_mfma_f32_16x16x32_bf16 v[68:71], v[210:213], v[202:205], v[68:71]
	v_mfma_f32_16x16x32_bf16 v[64:67], v[218:221], v[202:205], v[64:67]
	s_setprio 0
	s_mov_b32 m0, s37
	v_lshl_add_u64 v[224:225], s[16:17], 0, v[134:135]
	s_barrier
	ds_read_b128 v[174:177], v158 offset:16384
	ds_read_b128 v[178:181], v158 offset:17408
	ds_read_b128 v[182:185], v158 offset:18432
	ds_read_b128 v[186:189], v158 offset:19456
	ds_read_b128 v[190:193], v158 offset:20480
	ds_read_b128 v[194:197], v158 offset:21504
	ds_read_b128 v[198:201], v158 offset:22528
	ds_read_b128 v[202:205], v158 offset:23552
	global_load_lds_dwordx4 v[224:225], off
	v_lshl_add_u64 v[226:227], s[16:17], 0, v[130:131]
	s_mov_b32 m0, s40
	s_nop 0
	global_load_lds_dwordx4 v[226:227], off
	s_barrier
	s_waitcnt lgkmcnt(0)
	s_setprio 1
	s_waitcnt lgkmcnt(0)
	v_mfma_f32_16x16x32_bf16 v[60:63], v[146:149], v[174:177], v[60:63]
	v_mfma_f32_16x16x32_bf16 v[56:59], v[160:163], v[174:177], v[56:59]
	v_mfma_f32_16x16x32_bf16 v[44:47], v[146:149], v[182:185], v[44:47]
	v_mfma_f32_16x16x32_bf16 v[40:43], v[160:163], v[182:185], v[40:43]
	v_mfma_f32_16x16x32_bf16 v[28:31], v[146:149], v[190:193], v[28:31]
	v_mfma_f32_16x16x32_bf16 v[24:27], v[160:163], v[190:193], v[24:27]
	v_mfma_f32_16x16x32_bf16 v[12:15], v[146:149], v[198:201], v[12:15]
	v_mfma_f32_16x16x32_bf16 v[8:11], v[160:163], v[198:201], v[8:11]
	v_mfma_f32_16x16x32_bf16 v[60:63], v[150:153], v[178:181], v[60:63]
	v_mfma_f32_16x16x32_bf16 v[56:59], v[170:173], v[178:181], v[56:59]
	v_mfma_f32_16x16x32_bf16 v[44:47], v[150:153], v[186:189], v[44:47]
	v_mfma_f32_16x16x32_bf16 v[40:43], v[170:173], v[186:189], v[40:43]
	v_mfma_f32_16x16x32_bf16 v[28:31], v[150:153], v[194:197], v[28:31]
	v_mfma_f32_16x16x32_bf16 v[24:27], v[170:173], v[194:197], v[24:27]
	v_mfma_f32_16x16x32_bf16 v[12:15], v[150:153], v[202:205], v[12:15]
	v_mfma_f32_16x16x32_bf16 v[8:11], v[170:173], v[202:205], v[8:11]
	s_setprio 0
	s_barrier
; #define PG8_STAGE(bufoff, gbase, voff) do { _Pragma("unroll") for (int _i = 0; _i < 2; ++_i) \
;         __builtin_amdgcn_global_load_lds((const unsigned*)((const char*)(gbase) + (voff)[_i]), (LAS unsigned*)(lds + (bufoff) + ldsw + _i * 8192), 16, 0, 0); } while (0)
; #define PG8_LDA(dst, b, h) do { _Pragma("unroll") for (int m = 0; m < 4; ++m) _Pragma("unroll") for (int k = 0; k < 2; ++k) dst[m][k] = *(const LAS bf16x8*)(lds + PG8_SA(b, h) + aoff + m * 2048 + k * 1024); } while (0)
; #define PG8_LDB(dst, b, h) do { _Pragma("unroll") for (int n = 0; n < 2; ++n) _Pragma("unroll") for (int k = 0; k < 2; ++k) dst[n][k] = *(const LAS bf16x8*)(lds + PG8_SB(b, h) + boff + n * 2048 + k * 1024); } while (0)
; #define PG8_MMA(ai, bj, At, Bt) do { __builtin_amdgcn_s_setprio(1); _Pragma("unroll") for (int m = 0; m < 4; ++m) _Pragma("unroll") for (int n = 0; n < 2; ++n) _Pragma("unroll") for (int k = 0; k < 2; ++k) \
;         acc[ai][bj][m][n] = __builtin_amdgcn_mfma_f32_16x16x32_bf16(Bt[n][k], At[m][k], acc[ai][bj][m][n], 0, 0, 0); __builtin_amdgcn_s_setprio(0); } while (0)
; #define PG8_WAIT_V(n) asm volatile("s_waitcnt vmcnt(" #n ")" ::: "memory")
; #define PG8_WAIT_L(n) asm volatile("s_waitcnt lgkmcnt(" #n ")" ::: "memory")
; #define PG8_BAR __builtin_amdgcn_s_barrier()
; #define PG8_SCHED __builtin_amdgcn_sched_barrier(0)
;     ...
;             PG8_STAGE(PG8_SB(0, 1), b2 + hB, voffB);
;             PG8_WAIT_V(6); PG8_BAR; PG8_MMA(1, 1, At, B1); PG8_BAR;
;             PG8_LDB(B0, 1, 0); PG8_SCHED; PG8_LDA(At, 1, 0); PG8_STAGE(PG8_SA(0, 1), a2 + hA, voffA);
;             PG8_WAIT_L(8); PG8_BAR; PG8_WAIT_L(0); PG8_MMA(0, 0, At, B0); PG8_BAR; PG8_SCHED;
;             PG8_LDB(B1, 1, 1); PG8_STAGE(PG8_SB(1, 0), b3, voffB);
;             PG8_BAR; PG8_WAIT_L(0); PG8_MMA(0, 1, At, B1); PG8_BAR;
;             PG8_LDA(At, 1, 1); PG8_STAGE(PG8_SA(1, 0), a3, voffA);
	s_add_u32 s12, s14, 0x20000
	s_addc_u32 s13, s15, 0
	s_add_i32 s61, s56, s35
	v_lshl_add_u64 v[146:147], s[12:13], 0, v[132:133]
	s_mov_b32 m0, s61
	s_nop 0
	global_load_lds_dwordx4 v[146:147], off
	v_lshl_add_u64 v[146:147], s[12:13], 0, v[128:129]
	s_add_i32 m0, s61, 0x2000
	s_nop 0
	global_load_lds_dwordx4 v[146:147], off
	s_waitcnt vmcnt(6)
	s_barrier
	s_setprio 1
	v_mfma_f32_16x16x32_bf16 v[52:55], v[206:209], v[174:177], v[52:55]
	v_mfma_f32_16x16x32_bf16 v[48:51], v[214:217], v[174:177], v[48:51]
	v_mfma_f32_16x16x32_bf16 v[36:39], v[206:209], v[182:185], v[36:39]
	v_mfma_f32_16x16x32_bf16 v[32:35], v[214:217], v[182:185], v[32:35]
	v_mfma_f32_16x16x32_bf16 v[20:23], v[206:209], v[190:193], v[20:23]
	v_mfma_f32_16x16x32_bf16 v[16:19], v[214:217], v[190:193], v[16:19]
	v_mfma_f32_16x16x32_bf16 v[4:7], v[206:209], v[198:201], v[4:7]
	v_mfma_f32_16x16x32_bf16 v[0:3], v[214:217], v[198:201], v[0:3]
	v_mfma_f32_16x16x32_bf16 v[52:55], v[210:213], v[178:181], v[52:55]
	v_mfma_f32_16x16x32_bf16 v[48:51], v[218:221], v[178:181], v[48:51]
	v_mfma_f32_16x16x32_bf16 v[36:39], v[210:213], v[186:189], v[36:39]
	v_mfma_f32_16x16x32_bf16 v[32:35], v[218:221], v[186:189], v[32:35]
	v_mfma_f32_16x16x32_bf16 v[20:23], v[210:213], v[194:197], v[20:23]
	v_mfma_f32_16x16x32_bf16 v[16:19], v[218:221], v[194:197], v[16:19]
	v_mfma_f32_16x16x32_bf16 v[4:7], v[210:213], v[202:205], v[4:7]
	v_mfma_f32_16x16x32_bf16 v[0:3], v[218:221], v[202:205], v[0:3]
	s_setprio 0
	s_add_i32 s61, 0, 0x18000
	v_add_u32_e32 v169, s61, v155
	s_barrier
	ds_read_b128 v[146:149], v169
	ds_read_b128 v[150:153], v169 offset:1024
	ds_read_b128 v[160:163], v169 offset:2048
	ds_read_b128 v[170:173], v169 offset:3072
	s_add_u32 s12, s16, 0x110000
	s_addc_u32 s13, s17, 0
	s_mov_b32 m0, s41
	v_lshl_add_u64 v[206:207], s[12:13], 0, v[134:135]
	ds_read_b128 v[174:177], v158 offset:32768
	ds_read_b128 v[178:181], v158 offset:33792
	ds_read_b128 v[182:185], v158 offset:34816
	ds_read_b128 v[186:189], v158 offset:35840
	ds_read_b128 v[190:193], v158 offset:36864
	ds_read_b128 v[194:197], v158 offset:37888
	ds_read_b128 v[198:201], v158 offset:38912
	ds_read_b128 v[202:205], v158 offset:39936
	global_load_lds_dwordx4 v[206:207], off
	v_lshl_add_u64 v[206:207], s[12:13], 0, v[130:131]
	s_mov_b32 m0, s42
	s_nop 0
	global_load_lds_dwordx4 v[206:207], off
	s_waitcnt lgkmcnt(8)
	s_barrier
	s_waitcnt lgkmcnt(0)
	s_setprio 1
	s_waitcnt lgkmcnt(0)
	v_mfma_f32_16x16x32_bf16 v[124:127], v[146:149], v[174:177], v[124:127]
	v_mfma_f32_16x16x32_bf16 v[120:123], v[160:163], v[174:177], v[120:123]
	v_mfma_f32_16x16x32_bf16 v[108:111], v[146:149], v[182:185], v[108:111]
	v_mfma_f32_16x16x32_bf16 v[104:107], v[160:163], v[182:185], v[104:107]
	v_mfma_f32_16x16x32_bf16 v[92:95], v[146:149], v[190:193], v[92:95]
	v_mfma_f32_16x16x32_bf16 v[88:91], v[160:163], v[190:193], v[88:91]
	v_mfma_f32_16x16x32_bf16 v[76:79], v[146:149], v[198:201], v[76:79]
	v_mfma_f32_16x16x32_bf16 v[72:75], v[160:163], v[198:201], v[72:75]
	v_mfma_f32_16x16x32_bf16 v[124:127], v[150:153], v[178:181], v[124:127]
	v_mfma_f32_16x16x32_bf16 v[120:123], v[170:173], v[178:181], v[120:123]
	v_mfma_f32_16x16x32_bf16 v[108:111], v[150:153], v[186:189], v[108:111]
	v_mfma_f32_16x16x32_bf16 v[104:107], v[170:173], v[186:189], v[104:107]
	v_mfma_f32_16x16x32_bf16 v[92:95], v[150:153], v[194:197], v[92:95]
	v_mfma_f32_16x16x32_bf16 v[88:91], v[170:173], v[194:197], v[88:91]
	v_mfma_f32_16x16x32_bf16 v[76:79], v[150:153], v[202:205], v[76:79]
	v_mfma_f32_16x16x32_bf16 v[72:75], v[170:173], v[202:205], v[72:75]
	s_setprio 0
	s_barrier
	s_add_i32 s16, 0, 0x1c000
	s_add_i32 s12, s61, s35
	v_add_u32_e32 v169, s16, v155
	v_lshl_add_u64 v[164:165], v[164:165], 0, s[24:25]
	s_mov_b32 m0, s12
	ds_read_b128 v[206:209], v169
	ds_read_b128 v[210:213], v169 offset:1024
	ds_read_b128 v[214:217], v169 offset:2048
	ds_read_b128 v[218:221], v169 offset:3072
	global_load_lds_dwordx4 v[164:165], off
	v_lshl_add_u64 v[164:165], v[222:223], 0, s[24:25]
	s_add_i32 m0, s12, 0x2000
	s_nop 0
	global_load_lds_dwordx4 v[164:165], off
	s_barrier
	s_waitcnt lgkmcnt(0)
	s_setprio 1
	s_waitcnt lgkmcnt(0)
	v_mfma_f32_16x16x32_bf16 v[116:119], v[206:209], v[174:177], v[116:119]
	v_mfma_f32_16x16x32_bf16 v[112:115], v[214:217], v[174:177], v[112:115]
	v_mfma_f32_16x16x32_bf16 v[100:103], v[206:209], v[182:185], v[100:103]
	v_mfma_f32_16x16x32_bf16 v[96:99], v[214:217], v[182:185], v[96:99]
	v_mfma_f32_16x16x32_bf16 v[84:87], v[206:209], v[190:193], v[84:87]
	v_mfma_f32_16x16x32_bf16 v[80:83], v[214:217], v[190:193], v[80:83]
	v_mfma_f32_16x16x32_bf16 v[68:71], v[206:209], v[198:201], v[68:71]
	v_mfma_f32_16x16x32_bf16 v[64:67], v[214:217], v[198:201], v[64:67]
	v_mfma_f32_16x16x32_bf16 v[116:119], v[210:213], v[178:181], v[116:119]
	v_mfma_f32_16x16x32_bf16 v[112:115], v[218:221], v[178:181], v[112:115]
	v_mfma_f32_16x16x32_bf16 v[100:103], v[210:213], v[186:189], v[100:103]
	v_mfma_f32_16x16x32_bf16 v[96:99], v[218:221], v[186:189], v[96:99]
	v_mfma_f32_16x16x32_bf16 v[84:87], v[210:213], v[194:197], v[84:87]
	v_mfma_f32_16x16x32_bf16 v[80:83], v[218:221], v[194:197], v[80:83]
	v_mfma_f32_16x16x32_bf16 v[68:71], v[210:213], v[202:205], v[68:71]
	v_mfma_f32_16x16x32_bf16 v[64:67], v[218:221], v[202:205], v[64:67]
	s_setprio 0
	s_mov_b32 m0, s52
	v_lshl_add_u64 v[164:165], v[224:225], 0, s[24:25]
	s_barrier
	ds_read_b128 v[174:177], v158 offset:49152
	ds_read_b128 v[178:181], v158 offset:50176
	ds_read_b128 v[182:185], v158 offset:51200
	ds_read_b128 v[186:189], v158 offset:52224
	ds_read_b128 v[190:193], v158 offset:53248
	ds_read_b128 v[194:197], v158 offset:54272
	ds_read_b128 v[198:201], v158 offset:55296
	ds_read_b128 v[202:205], v158 offset:56320
	global_load_lds_dwordx4 v[164:165], off
	v_lshl_add_u64 v[164:165], v[226:227], 0, s[24:25]
	s_mov_b32 m0, s53
	s_nop 0
	global_load_lds_dwordx4 v[164:165], off
	s_barrier
; __device__ __forceinline__ float sigmoidf_(float x) { return 1.0f / (1.0f + __expf(-x)); }
; #define PG8_STAGE(bufoff, gbase, voff) do { _Pragma("unroll") for (int _i = 0; _i < 2; ++_i) \
;         __builtin_amdgcn_global_load_lds((const unsigned*)((const char*)(gbase) + (voff)[_i]), (LAS unsigned*)(lds + (bufoff) + ldsw + _i * 8192), 16, 0, 0); } while (0)
; #define PG8_MMA(ai, bj, At, Bt) do { __builtin_amdgcn_s_setprio(1); _Pragma("unroll") for (int m = 0; m < 4; ++m) _Pragma("unroll") for (int n = 0; n < 2; ++n) _Pragma("unroll") for (int k = 0; k < 2; ++k) \
;         acc[ai][bj][m][n] = __builtin_amdgcn_mfma_f32_16x16x32_bf16(Bt[n][k], At[m][k], acc[ai][bj][m][n], 0, 0, 0); __builtin_amdgcn_s_setprio(0); } while (0)
; #define PG8_WAIT_V(n) asm volatile("s_waitcnt vmcnt(" #n ")" ::: "memory")
; #define PG8_WAIT_L(n) asm volatile("s_waitcnt lgkmcnt(" #n ")" ::: "memory")
; #define PG8_BAR __builtin_amdgcn_s_barrier()
; #define PG8_SCHED __builtin_amdgcn_sched_barrier(0)
; __device__ __forceinline__ void unpack8(const u32x4 w, f32x4& v0, f32x4& v1) { v0 = (f32x4){bflo(w.x), bfhi(w.x), bflo(w.y), bfhi(w.y)}; v1 = (f32x4){bflo(w.z), bfhi(w.z), bflo(w.w), bfhi(w.w)}; }
;     ...
;             PG8_BAR; PG8_WAIT_L(0); PG8_MMA(1, 0, At, B0); PG8_BAR; PG8_SCHED;
;             PG8_STAGE(PG8_SB(1, 1), b3 + hB, voffB);
;             PG8_WAIT_V(6); PG8_BAR; PG8_MMA(1, 1, At, B1); PG8_BAR;
;     __device__ __forceinline__ void operator()(const f32x4 (&acc)[2][2][4][2], const Unit& u, int wr, int wc, int fr, int fq) const {
;         const int row0 = u.pm * 256 + wr * 64 + fr, col0 = u.pn * 256 + wc * 32 + 8 * fq;
; #pragma unroll
;         for (int ai = 0; ai < 2; ++ai)
; #pragma unroll
;             for (int m = 0; m < 4; ++m) {
;                 bf16_t* rowp = z + (size_t)(row0 + ai * 128 + m * 16) * DIN + col0;
; #pragma unroll
;                 for (int bj = 0; bj < 2; ++bj) {
;                     const u32x4 gw = *(const u32x4*)(rowp + (MODE == 0 ? O_GB : O_GA) + bj * 128);
;                     f32x4 g0, g1; unpack8(gw, g0, g1);
;                     f32x4 v0, v1;
; #pragma unroll
;                     for (int j = 0; j < 4; ++j) { v0[j] = sigmoidf_(g0[j]) * acc[ai][bj][m][0][j]; v1[j] = sigmoidf_(g1[j]) * acc[ai][bj][m][1][j]; }
	s_waitcnt lgkmcnt(0)
	s_setprio 1
	s_waitcnt lgkmcnt(0)
	v_mfma_f32_16x16x32_bf16 v[60:63], v[146:149], v[174:177], v[60:63]
	v_mfma_f32_16x16x32_bf16 v[56:59], v[160:163], v[174:177], v[56:59]
	v_mfma_f32_16x16x32_bf16 v[44:47], v[146:149], v[182:185], v[44:47]
	v_mfma_f32_16x16x32_bf16 v[40:43], v[160:163], v[182:185], v[40:43]
	v_mfma_f32_16x16x32_bf16 v[28:31], v[146:149], v[190:193], v[28:31]
	v_mfma_f32_16x16x32_bf16 v[24:27], v[160:163], v[190:193], v[24:27]
	v_mfma_f32_16x16x32_bf16 v[12:15], v[146:149], v[198:201], v[12:15]
	v_mfma_f32_16x16x32_bf16 v[8:11], v[160:163], v[198:201], v[8:11]
	v_mfma_f32_16x16x32_bf16 v[60:63], v[150:153], v[178:181], v[60:63]
	v_mfma_f32_16x16x32_bf16 v[56:59], v[170:173], v[178:181], v[56:59]
	v_mfma_f32_16x16x32_bf16 v[44:47], v[150:153], v[186:189], v[44:47]
	v_mfma_f32_16x16x32_bf16 v[40:43], v[170:173], v[186:189], v[40:43]
	v_mfma_f32_16x16x32_bf16 v[28:31], v[150:153], v[194:197], v[28:31]
	v_mfma_f32_16x16x32_bf16 v[24:27], v[170:173], v[194:197], v[24:27]
	v_mfma_f32_16x16x32_bf16 v[12:15], v[150:153], v[202:205], v[12:15]
	v_mfma_f32_16x16x32_bf16 v[8:11], v[170:173], v[202:205], v[8:11]
	s_setprio 0
	s_barrier
	s_add_u32 s12, s14, 0x20080
	s_addc_u32 s13, s15, 0
	s_add_i32 s14, s16, s35
	v_lshl_add_u64 v[146:147], s[12:13], 0, v[132:133]
	s_mov_b32 m0, s14
	s_nop 0
	global_load_lds_dwordx4 v[146:147], off
	v_lshl_add_u64 v[146:147], s[12:13], 0, v[128:129]
	s_add_i32 m0, s14, 0x2000
	s_nop 0
	global_load_lds_dwordx4 v[146:147], off
	s_waitcnt vmcnt(6)
	s_barrier
	s_setprio 1
	v_mfma_f32_16x16x32_bf16 v[52:55], v[206:209], v[174:177], v[52:55]
	v_mfma_f32_16x16x32_bf16 v[48:51], v[214:217], v[174:177], v[48:51]
	v_mfma_f32_16x16x32_bf16 v[36:39], v[206:209], v[182:185], v[36:39]
	v_mfma_f32_16x16x32_bf16 v[32:35], v[214:217], v[182:185], v[32:35]
	v_mfma_f32_16x16x32_bf16 v[20:23], v[206:209], v[190:193], v[20:23]
	v_mfma_f32_16x16x32_bf16 v[16:19], v[214:217], v[190:193], v[16:19]
	v_mfma_f32_16x16x32_bf16 v[4:7], v[206:209], v[198:201], v[4:7]
	v_mfma_f32_16x16x32_bf16 v[0:3], v[214:217], v[198:201], v[0:3]
	v_mfma_f32_16x16x32_bf16 v[52:55], v[210:213], v[178:181], v[52:55]
	v_mfma_f32_16x16x32_bf16 v[48:51], v[218:221], v[178:181], v[48:51]
	v_mfma_f32_16x16x32_bf16 v[36:39], v[210:213], v[186:189], v[36:39]
	v_mfma_f32_16x16x32_bf16 v[32:35], v[218:221], v[186:189], v[32:35]
	v_mfma_f32_16x16x32_bf16 v[20:23], v[210:213], v[194:197], v[20:23]
	v_mfma_f32_16x16x32_bf16 v[16:19], v[218:221], v[194:197], v[16:19]
	v_mfma_f32_16x16x32_bf16 v[4:7], v[210:213], v[202:205], v[4:7]
	v_mfma_f32_16x16x32_bf16 v[0:3], v[218:221], v[202:205], v[0:3]
	s_setprio 0
	s_add_i32 s60, s60, 2
	s_add_u32 s44, s44, 0x100
	s_addc_u32 s45, s45, 0
	s_cmp_gt_u32 s60, 5
	s_mov_b64 s[12:13], s[10:11]
	s_barrier
	s_cbranch_scc0 .LBB0_1768
	v_lshl_or_b32 v148, s7, 8, v156
	v_lshl_add_u32 v160, s6, 8, v154
	v_ashrrev_i32_e32 v149, 31, v148
	v_mov_b64_e32 v[146:147], s[22:23]
	v_mad_i64_i32 v[150:151], s[6:7], v160, s57, v[146:147]
	v_lshlrev_b64 v[148:149], 1, v[148:149]
	v_lshl_add_u64 v[150:151], v[150:151], 0, v[148:149]
	v_add_co_u32_e32 v152, vcc, 0x1000, v150
	s_nop 1
	v_addc_co_u32_e32 v153, vcc, 0, v151, vcc
	v_subrev_u32_e32 v197, s22, v150
	v_add_u32_e32 v198, 0x1a00, v197
	global_load_dwordx4 v[200:203], v198, s[22:23]
	v_add_u32_e32 v198, 0x1b00, v197
	global_load_dwordx4 v[204:207], v198, s[22:23]
	v_add_u32_e32 v198, 0x23a00, v197
	global_load_dwordx4 v[208:211], v198, s[22:23]
	v_add_u32_e32 v198, 0x23b00, v197
	global_load_dwordx4 v[212:215], v198, s[22:23]
	v_add_u32_e32 v198, 0x45a00, v197
	global_load_dwordx4 v[216:219], v198, s[22:23]
	v_add_u32_e32 v198, 0x45b00, v197
	global_load_dwordx4 v[232:235], v198, s[22:23]
	s_waitcnt vmcnt(5)
	v_mov_b32_e32 v162, v200
	v_mov_b32_e32 v163, v201
	v_mov_b32_e32 v164, v202
	v_mov_b32_e32 v165, v203
	v_add_u32_e32 v198, 0x67a00, v197
	global_load_dwordx4 v[200:203], v198, s[22:23]
	s_mov_b32 s100, 0xbfb8aa3b
	v_lshlrev_b32_e32 v236, 16, v162
	v_and_b32_e32 v237, 0xffff0000, v162
	v_lshlrev_b32_e32 v238, 16, v164
	v_and_b32_e32 v239, 0xffff0000, v164
	v_lshlrev_b32_e32 v240, 16, v163
	v_and_b32_e32 v241, 0xffff0000, v163
	v_lshlrev_b32_e32 v242, 16, v165
	v_and_b32_e32 v243, 0xffff0000, v165
	v_pk_mul_f32 v[236:237], v[236:237], s[100:101] op_sel_hi:[1,0]
	v_pk_mul_f32 v[238:239], v[238:239], s[100:101] op_sel_hi:[1,0]
	v_pk_mul_f32 v[240:241], v[240:241], s[100:101] op_sel_hi:[1,0]
	v_pk_mul_f32 v[242:243], v[242:243], s[100:101] op_sel_hi:[1,0]
	v_exp_f32_e32 v236, v236
	v_exp_f32_e32 v237, v237
	v_exp_f32_e32 v238, v238
	v_exp_f32_e32 v239, v239
	v_exp_f32_e32 v240, v240
	v_exp_f32_e32 v241, v241
	v_exp_f32_e32 v242, v242
	v_exp_f32_e32 v243, v243
	s_nop 0
	v_pk_add_f32 v[236:237], v[236:237], 1.0 op_sel_hi:[1,0]
	v_pk_add_f32 v[238:239], v[238:239], 1.0 op_sel_hi:[1,0]
	v_pk_add_f32 v[240:241], v[240:241], 1.0 op_sel_hi:[1,0]
	v_pk_add_f32 v[242:243], v[242:243], 1.0 op_sel_hi:[1,0]
	v_rcp_f32_e32 v244, v236
	v_rcp_f32_e32 v245, v237
	v_rcp_f32_e32 v250, v238
	v_rcp_f32_e32 v251, v239
	v_pk_fma_f32 v[246:247], v[236:237], v[244:245], 1.0 op_sel_hi:[1,1,0] neg_lo:[1,0,0] neg_hi:[1,0,0]
	v_pk_fma_f32 v[252:253], v[238:239], v[250:251], 1.0 op_sel_hi:[1,1,0] neg_lo:[1,0,0] neg_hi:[1,0,0]
	v_pk_fma_f32 v[244:245], v[246:247], v[244:245], v[244:245]
	v_pk_fma_f32 v[250:251], v[252:253], v[250:251], v[250:251]
	v_pk_fma_f32 v[246:247], v[236:237], v[244:245], 1.0 op_sel_hi:[1,1,0] neg_lo:[1,0,0] neg_hi:[1,0,0]
	v_pk_fma_f32 v[252:253], v[238:239], v[250:251], 1.0 op_sel_hi:[1,1,0] neg_lo:[1,0,0] neg_hi:[1,0,0]
	v_pk_fma_f32 v[248:249], v[246:247], v[244:245], v[244:245]
; __device__ __forceinline__ float sigmoidf_(float x) { return 1.0f / (1.0f + __expf(-x)); }
; __device__ __forceinline__ u32x4 pack8(const f32x4 v0, const f32x4 v1) { u32x4 w; w.x = pk2(v0[0], v0[1]); w.y = pk2(v0[2], v0[3]); w.z = pk2(v1[0], v1[1]); w.w = pk2(v1[2], v1[3]); return w; }
; __device__ __forceinline__ void unpack8(const u32x4 w, f32x4& v0, f32x4& v1) { v0 = (f32x4){bflo(w.x), bfhi(w.x), bflo(w.y), bfhi(w.y)}; v1 = (f32x4){bflo(w.z), bfhi(w.z), bflo(w.w), bfhi(w.w)}; }
;     __device__ __forceinline__ void operator()(const f32x4 (&acc)[2][2][4][2], const Unit& u, int wr, int wc, int fr, int fq) const {
;     ...
;         for (int ai = 0; ai < 2; ++ai)
; #pragma unroll
;             for (int m = 0; m < 4; ++m) {
;                 bf16_t* rowp = z + (size_t)(row0 + ai * 128 + m * 16) * DIN + col0;
; #pragma unroll
;                 for (int bj = 0; bj < 2; ++bj) {
;                     const u32x4 gw = *(const u32x4*)(rowp + (MODE == 0 ? O_GB : O_GA) + bj * 128);
;                     f32x4 g0, g1; unpack8(gw, g0, g1);
;                     f32x4 v0, v1;
; #pragma unroll
;                     for (int j = 0; j < 4; ++j) { v0[j] = sigmoidf_(g0[j]) * acc[ai][bj][m][0][j]; v1[j] = sigmoidf_(g1[j]) * acc[ai][bj][m][1][j]; }
;                     if (MODE == 1) { const u32x4 mw = *(const u32x4*)(rowp + bj * 128); f32x4 m0, m1; unpack8(mw, m0, m1); v0 += m0; v1 += m1; }
;                     *(u32x4*)(rowp + bj * 128) = pack8(v0, v1); }
	v_pk_fma_f32 v[254:255], v[252:253], v[250:251], v[250:251]
	v_pk_fma_f32 v[246:247], v[236:237], v[248:249], 1.0 op_sel_hi:[1,1,0] neg_lo:[1,0,0] neg_hi:[1,0,0]
	v_pk_fma_f32 v[252:253], v[238:239], v[254:255], 1.0 op_sel_hi:[1,1,0] neg_lo:[1,0,0] neg_hi:[1,0,0]
	v_pk_fma_f32 v[248:249], v[246:247], v[244:245], v[248:249]
	v_pk_fma_f32 v[254:255], v[252:253], v[250:251], v[254:255]
	v_div_fixup_f32 v236, v248, v236, 1.0
	v_div_fixup_f32 v237, v249, v237, 1.0
	v_div_fixup_f32 v238, v254, v238, 1.0
	v_div_fixup_f32 v239, v255, v239, 1.0
	v_rcp_f32_e32 v244, v240
	v_rcp_f32_e32 v245, v241
	v_rcp_f32_e32 v250, v242
	v_rcp_f32_e32 v251, v243
	v_pk_fma_f32 v[246:247], v[240:241], v[244:245], 1.0 op_sel_hi:[1,1,0] neg_lo:[1,0,0] neg_hi:[1,0,0]
	v_pk_fma_f32 v[252:253], v[242:243], v[250:251], 1.0 op_sel_hi:[1,1,0] neg_lo:[1,0,0] neg_hi:[1,0,0]
	v_pk_fma_f32 v[244:245], v[246:247], v[244:245], v[244:245]
	v_pk_fma_f32 v[250:251], v[252:253], v[250:251], v[250:251]
	v_pk_fma_f32 v[246:247], v[240:241], v[244:245], 1.0 op_sel_hi:[1,1,0] neg_lo:[1,0,0] neg_hi:[1,0,0]
	v_pk_fma_f32 v[252:253], v[242:243], v[250:251], 1.0 op_sel_hi:[1,1,0] neg_lo:[1,0,0] neg_hi:[1,0,0]
	v_pk_fma_f32 v[248:249], v[246:247], v[244:245], v[244:245]
	v_pk_fma_f32 v[254:255], v[252:253], v[250:251], v[250:251]
	v_pk_fma_f32 v[246:247], v[240:241], v[248:249], 1.0 op_sel_hi:[1,1,0] neg_lo:[1,0,0] neg_hi:[1,0,0]
	v_pk_fma_f32 v[252:253], v[242:243], v[254:255], 1.0 op_sel_hi:[1,1,0] neg_lo:[1,0,0] neg_hi:[1,0,0]
	v_pk_fma_f32 v[248:249], v[246:247], v[244:245], v[248:249]
	v_pk_fma_f32 v[254:255], v[252:253], v[250:251], v[254:255]
	v_div_fixup_f32 v240, v248, v240, 1.0
	v_div_fixup_f32 v241, v249, v241, 1.0
	v_div_fixup_f32 v242, v254, v242, 1.0
	v_div_fixup_f32 v243, v255, v243, 1.0
	s_mov_b64 vcc, s[10:11]
	s_mov_b64 vcc, s[12:13]
	v_mul_f32_e32 v124, v124, v236
	s_mov_b64 vcc, s[14:15]
	v_mul_f32_e32 v161, v120, v238
	v_mul_f32_e32 v120, v125, v237
	v_mul_f32_e32 v125, v121, v239
	s_mov_b64 vcc, s[16:17]
	v_mul_f32_e32 v126, v126, v240
	v_mul_f32_e32 v162, v122, v242
	v_mul_f32_e32 v121, v127, v241
	v_mul_f32_e32 v123, v123, v243
	v_cvt_pk_bf16_f32 v120, v124, v120
	v_cvt_pk_bf16_f32 v121, v126, v121
	v_cvt_pk_bf16_f32 v122, v161, v125
	v_cvt_pk_bf16_f32 v123, v162, v123
	s_mov_b64 s[14:15], s[30:31]
	global_store_dwordx4 v[150:151], v[120:123], off
	s_mov_b64 s[12:13], s[28:29]
	s_waitcnt vmcnt(6)
	v_mov_b32_e32 v124, v204
	v_mov_b32_e32 v125, v205
	v_mov_b32_e32 v126, v206
	v_mov_b32_e32 v127, v207
	v_add_u32_e32 v198, 0x67b00, v197
	global_load_dwordx4 v[204:207], v198, s[22:23]
	s_mov_b32 s100, 0xbfb8aa3b
	v_lshlrev_b32_e32 v236, 16, v124
	v_and_b32_e32 v237, 0xffff0000, v124
	v_lshlrev_b32_e32 v238, 16, v126
	v_and_b32_e32 v239, 0xffff0000, v126
	v_lshlrev_b32_e32 v240, 16, v125
	v_and_b32_e32 v241, 0xffff0000, v125
	v_lshlrev_b32_e32 v242, 16, v127
	v_and_b32_e32 v243, 0xffff0000, v127
	v_pk_mul_f32 v[236:237], v[236:237], s[100:101] op_sel_hi:[1,0]
	v_pk_mul_f32 v[238:239], v[238:239], s[100:101] op_sel_hi:[1,0]
	v_pk_mul_f32 v[240:241], v[240:241], s[100:101] op_sel_hi:[1,0]
	v_pk_mul_f32 v[242:243], v[242:243], s[100:101] op_sel_hi:[1,0]
	v_exp_f32_e32 v236, v236
	v_exp_f32_e32 v237, v237
	v_exp_f32_e32 v238, v238
	v_exp_f32_e32 v239, v239
	v_exp_f32_e32 v240, v240
	v_exp_f32_e32 v241, v241
	v_exp_f32_e32 v242, v242
	v_exp_f32_e32 v243, v243
	s_nop 0
	v_pk_add_f32 v[236:237], v[236:237], 1.0 op_sel_hi:[1,0]
	v_pk_add_f32 v[238:239], v[238:239], 1.0 op_sel_hi:[1,0]
	v_pk_add_f32 v[240:241], v[240:241], 1.0 op_sel_hi:[1,0]
	v_pk_add_f32 v[242:243], v[242:243], 1.0 op_sel_hi:[1,0]
	v_rcp_f32_e32 v244, v236
	v_rcp_f32_e32 v245, v237
	v_rcp_f32_e32 v250, v238
	v_rcp_f32_e32 v251, v239
	v_pk_fma_f32 v[246:247], v[236:237], v[244:245], 1.0 op_sel_hi:[1,1,0] neg_lo:[1,0,0] neg_hi:[1,0,0]
	v_pk_fma_f32 v[252:253], v[238:239], v[250:251], 1.0 op_sel_hi:[1,1,0] neg_lo:[1,0,0] neg_hi:[1,0,0]
	v_pk_fma_f32 v[244:245], v[246:247], v[244:245], v[244:245]
	v_pk_fma_f32 v[250:251], v[252:253], v[250:251], v[250:251]
	v_pk_fma_f32 v[246:247], v[236:237], v[244:245], 1.0 op_sel_hi:[1,1,0] neg_lo:[1,0,0] neg_hi:[1,0,0]
	v_pk_fma_f32 v[252:253], v[238:239], v[250:251], 1.0 op_sel_hi:[1,1,0] neg_lo:[1,0,0] neg_hi:[1,0,0]
	v_pk_fma_f32 v[248:249], v[246:247], v[244:245], v[244:245]
	v_pk_fma_f32 v[254:255], v[252:253], v[250:251], v[250:251]
	v_pk_fma_f32 v[246:247], v[236:237], v[248:249], 1.0 op_sel_hi:[1,1,0] neg_lo:[1,0,0] neg_hi:[1,0,0]
	v_pk_fma_f32 v[252:253], v[238:239], v[254:255], 1.0 op_sel_hi:[1,1,0] neg_lo:[1,0,0] neg_hi:[1,0,0]
	v_pk_fma_f32 v[248:249], v[246:247], v[244:245], v[248:249]
	v_pk_fma_f32 v[254:255], v[252:253], v[250:251], v[254:255]
	v_div_fixup_f32 v236, v248, v236, 1.0
	v_div_fixup_f32 v237, v249, v237, 1.0
	v_div_fixup_f32 v238, v254, v238, 1.0
	v_div_fixup_f32 v239, v255, v239, 1.0
	v_rcp_f32_e32 v244, v240
	v_rcp_f32_e32 v245, v241
	v_rcp_f32_e32 v250, v242
	v_rcp_f32_e32 v251, v243
	v_pk_fma_f32 v[246:247], v[240:241], v[244:245], 1.0 op_sel_hi:[1,1,0] neg_lo:[1,0,0] neg_hi:[1,0,0]
	v_pk_fma_f32 v[252:253], v[242:243], v[250:251], 1.0 op_sel_hi:[1,1,0] neg_lo:[1,0,0] neg_hi:[1,0,0]
	v_pk_fma_f32 v[244:245], v[246:247], v[244:245], v[244:245]
	v_pk_fma_f32 v[250:251], v[252:253], v[250:251], v[250:251]
	v_pk_fma_f32 v[246:247], v[240:241], v[244:245], 1.0 op_sel_hi:[1,1,0] neg_lo:[1,0,0] neg_hi:[1,0,0]
	v_pk_fma_f32 v[252:253], v[242:243], v[250:251], 1.0 op_sel_hi:[1,1,0] neg_lo:[1,0,0] neg_hi:[1,0,0]
	v_pk_fma_f32 v[248:249], v[246:247], v[244:245], v[244:245]
	v_pk_fma_f32 v[254:255], v[252:253], v[250:251], v[250:251]
	v_pk_fma_f32 v[246:247], v[240:241], v[248:249], 1.0 op_sel_hi:[1,1,0] neg_lo:[1,0,0] neg_hi:[1,0,0]
	v_pk_fma_f32 v[252:253], v[242:243], v[254:255], 1.0 op_sel_hi:[1,1,0] neg_lo:[1,0,0] neg_hi:[1,0,0]
	v_pk_fma_f32 v[248:249], v[246:247], v[244:245], v[248:249]
	v_pk_fma_f32 v[254:255], v[252:253], v[250:251], v[254:255]
	v_div_fixup_f32 v240, v248, v240, 1.0
	v_div_fixup_f32 v241, v249, v241, 1.0
	v_div_fixup_f32 v242, v254, v242, 1.0
	v_div_fixup_f32 v243, v255, v243, 1.0
	s_mov_b64 vcc, s[10:11]
	v_pk_mul_f32 v[116:117], v[116:117], v[236:237]
	v_pk_mul_f32 v[112:113], v[112:113], v[238:239]
	v_pk_mul_f32 v[118:119], v[118:119], v[240:241]
	v_pk_mul_f32 v[120:121], v[114:115], v[242:243]
	v_cvt_pk_bf16_f32 v114, v116, v117
	v_cvt_pk_bf16_f32 v115, v118, v119
	v_cvt_pk_bf16_f32 v116, v112, v113
	v_or_b32_e32 v112, 16, v160
	v_mad_i64_i32 v[112:113], s[6:7], v112, s57, v[146:147]
	v_lshl_add_u64 v[112:113], v[112:113], 0, v[148:149]
	v_add_co_u32_e32 v122, vcc, s58, v112
	v_cvt_pk_bf16_f32 v117, v120, v121
	global_store_dwordx4 v[150:151], v[114:117], off offset:256
	s_nop 0
	v_addc_co_u32_e32 v123, vcc, 0, v113, vcc
	s_waitcnt vmcnt(7)
; __device__ __forceinline__ float sigmoidf_(float x) { return 1.0f / (1.0f + __expf(-x)); }
; __device__ __forceinline__ u32x4 pack8(const f32x4 v0, const f32x4 v1) { u32x4 w; w.x = pk2(v0[0], v0[1]); w.y = pk2(v0[2], v0[3]); w.z = pk2(v1[0], v1[1]); w.w = pk2(v1[2], v1[3]); return w; }
; __device__ __forceinline__ void unpack8(const u32x4 w, f32x4& v0, f32x4& v1) { v0 = (f32x4){bflo(w.x), bfhi(w.x), bflo(w.y), bfhi(w.y)}; v1 = (f32x4){bflo(w.z), bfhi(w.z), bflo(w.w), bfhi(w.w)}; }
;     __device__ __forceinline__ void operator()(const f32x4 (&acc)[2][2][4][2], const Unit& u, int wr, int wc, int fr, int fq) const {
;     ...
;         for (int ai = 0; ai < 2; ++ai)
; #pragma unroll
;             for (int m = 0; m < 4; ++m) {
;                 bf16_t* rowp = z + (size_t)(row0 + ai * 128 + m * 16) * DIN + col0;
; #pragma unroll
;                 for (int bj = 0; bj < 2; ++bj) {
;                     const u32x4 gw = *(const u32x4*)(rowp + (MODE == 0 ? O_GB : O_GA) + bj * 128);
;                     f32x4 g0, g1; unpack8(gw, g0, g1);
;                     f32x4 v0, v1;
; #pragma unroll
;                     for (int j = 0; j < 4; ++j) { v0[j] = sigmoidf_(g0[j]) * acc[ai][bj][m][0][j]; v1[j] = sigmoidf_(g1[j]) * acc[ai][bj][m][1][j]; }
;                     if (MODE == 1) { const u32x4 mw = *(const u32x4*)(rowp + bj * 128); f32x4 m0, m1; unpack8(mw, m0, m1); v0 += m0; v1 += m1; }
;                     *(u32x4*)(rowp + bj * 128) = pack8(v0, v1); }
	v_mov_b32_e32 v118, v208
	v_mov_b32_e32 v119, v209
	v_mov_b32_e32 v120, v210
	v_mov_b32_e32 v121, v211
	v_add_u32_e32 v198, 0x111a00, v197
	global_load_dwordx4 v[208:211], v198, s[22:23]
	s_mov_b32 s100, 0xbfb8aa3b
	v_lshlrev_b32_e32 v236, 16, v118
	v_and_b32_e32 v237, 0xffff0000, v118
	v_lshlrev_b32_e32 v238, 16, v120
	v_and_b32_e32 v239, 0xffff0000, v120
	v_lshlrev_b32_e32 v240, 16, v119
	v_and_b32_e32 v241, 0xffff0000, v119
	v_lshlrev_b32_e32 v242, 16, v121
	v_and_b32_e32 v243, 0xffff0000, v121
	v_pk_mul_f32 v[236:237], v[236:237], s[100:101] op_sel_hi:[1,0]
	v_pk_mul_f32 v[238:239], v[238:239], s[100:101] op_sel_hi:[1,0]
	v_pk_mul_f32 v[240:241], v[240:241], s[100:101] op_sel_hi:[1,0]
	v_pk_mul_f32 v[242:243], v[242:243], s[100:101] op_sel_hi:[1,0]
	v_exp_f32_e32 v236, v236
	v_exp_f32_e32 v237, v237
	v_exp_f32_e32 v238, v238
	v_exp_f32_e32 v239, v239
	v_exp_f32_e32 v240, v240
	v_exp_f32_e32 v241, v241
	v_exp_f32_e32 v242, v242
	v_exp_f32_e32 v243, v243
	s_nop 0
	v_pk_add_f32 v[236:237], v[236:237], 1.0 op_sel_hi:[1,0]
	v_pk_add_f32 v[238:239], v[238:239], 1.0 op_sel_hi:[1,0]
	v_pk_add_f32 v[240:241], v[240:241], 1.0 op_sel_hi:[1,0]
	v_pk_add_f32 v[242:243], v[242:243], 1.0 op_sel_hi:[1,0]
	v_rcp_f32_e32 v244, v236
	v_rcp_f32_e32 v245, v237
	v_rcp_f32_e32 v250, v238
	v_rcp_f32_e32 v251, v239
	v_pk_fma_f32 v[246:247], v[236:237], v[244:245], 1.0 op_sel_hi:[1,1,0] neg_lo:[1,0,0] neg_hi:[1,0,0]
	v_pk_fma_f32 v[252:253], v[238:239], v[250:251], 1.0 op_sel_hi:[1,1,0] neg_lo:[1,0,0] neg_hi:[1,0,0]
	v_pk_fma_f32 v[244:245], v[246:247], v[244:245], v[244:245]
	v_pk_fma_f32 v[250:251], v[252:253], v[250:251], v[250:251]
	v_pk_fma_f32 v[246:247], v[236:237], v[244:245], 1.0 op_sel_hi:[1,1,0] neg_lo:[1,0,0] neg_hi:[1,0,0]
	v_pk_fma_f32 v[252:253], v[238:239], v[250:251], 1.0 op_sel_hi:[1,1,0] neg_lo:[1,0,0] neg_hi:[1,0,0]
	v_pk_fma_f32 v[248:249], v[246:247], v[244:245], v[244:245]
	v_pk_fma_f32 v[254:255], v[252:253], v[250:251], v[250:251]
	v_pk_fma_f32 v[246:247], v[236:237], v[248:249], 1.0 op_sel_hi:[1,1,0] neg_lo:[1,0,0] neg_hi:[1,0,0]
	v_pk_fma_f32 v[252:253], v[238:239], v[254:255], 1.0 op_sel_hi:[1,1,0] neg_lo:[1,0,0] neg_hi:[1,0,0]
	v_pk_fma_f32 v[248:249], v[246:247], v[244:245], v[248:249]
	v_pk_fma_f32 v[254:255], v[252:253], v[250:251], v[254:255]
	v_div_fixup_f32 v236, v248, v236, 1.0
	v_div_fixup_f32 v237, v249, v237, 1.0
	v_div_fixup_f32 v238, v254, v238, 1.0
	v_div_fixup_f32 v239, v255, v239, 1.0
	v_rcp_f32_e32 v244, v240
	v_rcp_f32_e32 v245, v241
	v_rcp_f32_e32 v250, v242
	v_rcp_f32_e32 v251, v243
	v_pk_fma_f32 v[246:247], v[240:241], v[244:245], 1.0 op_sel_hi:[1,1,0] neg_lo:[1,0,0] neg_hi:[1,0,0]
	v_pk_fma_f32 v[252:253], v[242:243], v[250:251], 1.0 op_sel_hi:[1,1,0] neg_lo:[1,0,0] neg_hi:[1,0,0]
	v_pk_fma_f32 v[244:245], v[246:247], v[244:245], v[244:245]
	v_pk_fma_f32 v[250:251], v[252:253], v[250:251], v[250:251]
	v_pk_fma_f32 v[246:247], v[240:241], v[244:245], 1.0 op_sel_hi:[1,1,0] neg_lo:[1,0,0] neg_hi:[1,0,0]
	v_pk_fma_f32 v[252:253], v[242:243], v[250:251], 1.0 op_sel_hi:[1,1,0] neg_lo:[1,0,0] neg_hi:[1,0,0]
	v_pk_fma_f32 v[248:249], v[246:247], v[244:245], v[244:245]
	v_pk_fma_f32 v[254:255], v[252:253], v[250:251], v[250:251]
	v_pk_fma_f32 v[246:247], v[240:241], v[248:249], 1.0 op_sel_hi:[1,1,0] neg_lo:[1,0,0] neg_hi:[1,0,0]
	v_pk_fma_f32 v[252:253], v[242:243], v[254:255], 1.0 op_sel_hi:[1,1,0] neg_lo:[1,0,0] neg_hi:[1,0,0]
	v_pk_fma_f32 v[248:249], v[246:247], v[244:245], v[248:249]
	v_pk_fma_f32 v[254:255], v[252:253], v[250:251], v[254:255]
	v_div_fixup_f32 v240, v248, v240, 1.0
	v_div_fixup_f32 v241, v249, v241, 1.0
	v_div_fixup_f32 v242, v254, v242, 1.0
	v_div_fixup_f32 v243, v255, v243, 1.0
	v_mul_f32_e32 v108, v108, v236
	v_mul_f32_e32 v114, v104, v238
	v_mul_f32_e32 v104, v109, v237
	v_mul_f32_e32 v109, v105, v239
	v_mul_f32_e32 v105, v110, v240
	v_mul_f32_e32 v110, v106, v242
	v_mul_f32_e32 v106, v111, v241
	v_mul_f32_e32 v107, v107, v243
	v_cvt_pk_bf16_f32 v104, v108, v104
	v_cvt_pk_bf16_f32 v105, v105, v106
	v_cvt_pk_bf16_f32 v106, v114, v109
	v_cvt_pk_bf16_f32 v107, v110, v107
	s_waitcnt vmcnt(7)
	v_mov_b32_e32 v108, v212
	v_mov_b32_e32 v109, v213
	v_mov_b32_e32 v110, v214
	v_mov_b32_e32 v111, v215
	v_add_u32_e32 v198, 0x111b00, v197
	global_load_dwordx4 v[212:215], v198, s[22:23]
	s_mov_b32 s100, 0xbfb8aa3b
	v_lshlrev_b32_e32 v236, 16, v108
	v_and_b32_e32 v237, 0xffff0000, v108
	v_lshlrev_b32_e32 v238, 16, v110
	v_and_b32_e32 v239, 0xffff0000, v110
	v_lshlrev_b32_e32 v240, 16, v109
	v_and_b32_e32 v241, 0xffff0000, v109
	v_lshlrev_b32_e32 v242, 16, v111
	v_and_b32_e32 v243, 0xffff0000, v111
	v_pk_mul_f32 v[236:237], v[236:237], s[100:101] op_sel_hi:[1,0]
	v_pk_mul_f32 v[238:239], v[238:239], s[100:101] op_sel_hi:[1,0]
	v_pk_mul_f32 v[240:241], v[240:241], s[100:101] op_sel_hi:[1,0]
	v_pk_mul_f32 v[242:243], v[242:243], s[100:101] op_sel_hi:[1,0]
	v_exp_f32_e32 v236, v236
	v_exp_f32_e32 v237, v237
	v_exp_f32_e32 v238, v238
	v_exp_f32_e32 v239, v239
	v_exp_f32_e32 v240, v240
	v_exp_f32_e32 v241, v241
	v_exp_f32_e32 v242, v242
	v_exp_f32_e32 v243, v243
	s_nop 0
	v_pk_add_f32 v[236:237], v[236:237], 1.0 op_sel_hi:[1,0]
	v_pk_add_f32 v[238:239], v[238:239], 1.0 op_sel_hi:[1,0]
	v_pk_add_f32 v[240:241], v[240:241], 1.0 op_sel_hi:[1,0]
	v_pk_add_f32 v[242:243], v[242:243], 1.0 op_sel_hi:[1,0]
	v_rcp_f32_e32 v244, v236
	v_rcp_f32_e32 v245, v237
	v_rcp_f32_e32 v250, v238
	v_rcp_f32_e32 v251, v239
	v_pk_fma_f32 v[246:247], v[236:237], v[244:245], 1.0 op_sel_hi:[1,1,0] neg_lo:[1,0,0] neg_hi:[1,0,0]
	v_pk_fma_f32 v[252:253], v[238:239], v[250:251], 1.0 op_sel_hi:[1,1,0] neg_lo:[1,0,0] neg_hi:[1,0,0]
; __device__ __forceinline__ float sigmoidf_(float x) { return 1.0f / (1.0f + __expf(-x)); }
; __device__ __forceinline__ u32x4 pack8(const f32x4 v0, const f32x4 v1) { u32x4 w; w.x = pk2(v0[0], v0[1]); w.y = pk2(v0[2], v0[3]); w.z = pk2(v1[0], v1[1]); w.w = pk2(v1[2], v1[3]); return w; }
; __device__ __forceinline__ void unpack8(const u32x4 w, f32x4& v0, f32x4& v1) { v0 = (f32x4){bflo(w.x), bfhi(w.x), bflo(w.y), bfhi(w.y)}; v1 = (f32x4){bflo(w.z), bfhi(w.z), bflo(w.w), bfhi(w.w)}; }
;     __device__ __forceinline__ void operator()(const f32x4 (&acc)[2][2][4][2], const Unit& u, int wr, int wc, int fr, int fq) const {
;     ...
;         for (int ai = 0; ai < 2; ++ai)
; #pragma unroll
;             for (int m = 0; m < 4; ++m) {
;                 bf16_t* rowp = z + (size_t)(row0 + ai * 128 + m * 16) * DIN + col0;
; #pragma unroll
;                 for (int bj = 0; bj < 2; ++bj) {
;                     const u32x4 gw = *(const u32x4*)(rowp + (MODE == 0 ? O_GB : O_GA) + bj * 128);
;                     f32x4 g0, g1; unpack8(gw, g0, g1);
;                     f32x4 v0, v1;
; #pragma unroll
;                     for (int j = 0; j < 4; ++j) { v0[j] = sigmoidf_(g0[j]) * acc[ai][bj][m][0][j]; v1[j] = sigmoidf_(g1[j]) * acc[ai][bj][m][1][j]; }
;                     if (MODE == 1) { const u32x4 mw = *(const u32x4*)(rowp + bj * 128); f32x4 m0, m1; unpack8(mw, m0, m1); v0 += m0; v1 += m1; }
;                     *(u32x4*)(rowp + bj * 128) = pack8(v0, v1); }
	v_pk_fma_f32 v[244:245], v[246:247], v[244:245], v[244:245]
	v_pk_fma_f32 v[250:251], v[252:253], v[250:251], v[250:251]
	v_pk_fma_f32 v[246:247], v[236:237], v[244:245], 1.0 op_sel_hi:[1,1,0] neg_lo:[1,0,0] neg_hi:[1,0,0]
	v_pk_fma_f32 v[252:253], v[238:239], v[250:251], 1.0 op_sel_hi:[1,1,0] neg_lo:[1,0,0] neg_hi:[1,0,0]
	v_pk_fma_f32 v[248:249], v[246:247], v[244:245], v[244:245]
	v_pk_fma_f32 v[254:255], v[252:253], v[250:251], v[250:251]
	v_pk_fma_f32 v[246:247], v[236:237], v[248:249], 1.0 op_sel_hi:[1,1,0] neg_lo:[1,0,0] neg_hi:[1,0,0]
	v_pk_fma_f32 v[252:253], v[238:239], v[254:255], 1.0 op_sel_hi:[1,1,0] neg_lo:[1,0,0] neg_hi:[1,0,0]
	v_pk_fma_f32 v[248:249], v[246:247], v[244:245], v[248:249]
	v_pk_fma_f32 v[254:255], v[252:253], v[250:251], v[254:255]
	v_div_fixup_f32 v236, v248, v236, 1.0
	v_div_fixup_f32 v237, v249, v237, 1.0
	v_div_fixup_f32 v238, v254, v238, 1.0
	v_div_fixup_f32 v239, v255, v239, 1.0
	v_rcp_f32_e32 v244, v240
	v_rcp_f32_e32 v245, v241
	v_rcp_f32_e32 v250, v242
	v_rcp_f32_e32 v251, v243
	v_pk_fma_f32 v[246:247], v[240:241], v[244:245], 1.0 op_sel_hi:[1,1,0] neg_lo:[1,0,0] neg_hi:[1,0,0]
	v_pk_fma_f32 v[252:253], v[242:243], v[250:251], 1.0 op_sel_hi:[1,1,0] neg_lo:[1,0,0] neg_hi:[1,0,0]
	v_pk_fma_f32 v[244:245], v[246:247], v[244:245], v[244:245]
	v_pk_fma_f32 v[250:251], v[252:253], v[250:251], v[250:251]
	v_pk_fma_f32 v[246:247], v[240:241], v[244:245], 1.0 op_sel_hi:[1,1,0] neg_lo:[1,0,0] neg_hi:[1,0,0]
	v_pk_fma_f32 v[252:253], v[242:243], v[250:251], 1.0 op_sel_hi:[1,1,0] neg_lo:[1,0,0] neg_hi:[1,0,0]
	v_pk_fma_f32 v[248:249], v[246:247], v[244:245], v[244:245]
	v_pk_fma_f32 v[254:255], v[252:253], v[250:251], v[250:251]
	v_pk_fma_f32 v[246:247], v[240:241], v[248:249], 1.0 op_sel_hi:[1,1,0] neg_lo:[1,0,0] neg_hi:[1,0,0]
	v_pk_fma_f32 v[252:253], v[242:243], v[254:255], 1.0 op_sel_hi:[1,1,0] neg_lo:[1,0,0] neg_hi:[1,0,0]
	v_pk_fma_f32 v[248:249], v[246:247], v[244:245], v[248:249]
	v_pk_fma_f32 v[254:255], v[252:253], v[250:251], v[254:255]
	v_div_fixup_f32 v240, v248, v240, 1.0
	v_div_fixup_f32 v241, v249, v241, 1.0
	v_div_fixup_f32 v242, v254, v242, 1.0
	v_div_fixup_f32 v243, v255, v243, 1.0
	global_store_dwordx4 v[112:113], v[104:107], off
	s_nop 0
	v_pk_mul_f32 v[100:101], v[100:101], v[236:237]
	v_pk_mul_f32 v[96:97], v[96:97], v[238:239]
	v_pk_mul_f32 v[102:103], v[102:103], v[240:241]
	v_pk_mul_f32 v[104:105], v[98:99], v[242:243]
	v_cvt_pk_bf16_f32 v98, v100, v101
	v_cvt_pk_bf16_f32 v99, v102, v103
	v_cvt_pk_bf16_f32 v100, v96, v97
	v_or_b32_e32 v96, 32, v160
	v_mad_i64_i32 v[96:97], s[6:7], v96, s57, v[146:147]
	v_lshl_add_u64 v[96:97], v[96:97], 0, v[148:149]
	v_add_co_u32_e32 v106, vcc, s58, v96
	v_cvt_pk_bf16_f32 v101, v104, v105
	global_store_dwordx4 v[112:113], v[98:101], off offset:256
	s_nop 0
	v_addc_co_u32_e32 v107, vcc, 0, v97, vcc
	s_waitcnt vmcnt(9)
	v_mov_b32_e32 v102, v216
	v_mov_b32_e32 v103, v217
	v_mov_b32_e32 v104, v218
	v_mov_b32_e32 v105, v219
	v_add_u32_e32 v198, 0x133a00, v197
	global_load_dwordx4 v[216:219], v198, s[22:23]
	s_mov_b32 s100, 0xbfb8aa3b
	v_lshlrev_b32_e32 v236, 16, v102
	v_and_b32_e32 v237, 0xffff0000, v102
	v_lshlrev_b32_e32 v238, 16, v104
	v_and_b32_e32 v239, 0xffff0000, v104
	v_lshlrev_b32_e32 v240, 16, v103
	v_and_b32_e32 v241, 0xffff0000, v103
	v_lshlrev_b32_e32 v242, 16, v105
	v_and_b32_e32 v243, 0xffff0000, v105
	v_pk_mul_f32 v[236:237], v[236:237], s[100:101] op_sel_hi:[1,0]
	v_pk_mul_f32 v[238:239], v[238:239], s[100:101] op_sel_hi:[1,0]
	v_pk_mul_f32 v[240:241], v[240:241], s[100:101] op_sel_hi:[1,0]
	v_pk_mul_f32 v[242:243], v[242:243], s[100:101] op_sel_hi:[1,0]
	v_exp_f32_e32 v236, v236
	v_exp_f32_e32 v237, v237
	v_exp_f32_e32 v238, v238
	v_exp_f32_e32 v239, v239
	v_exp_f32_e32 v240, v240
	v_exp_f32_e32 v241, v241
	v_exp_f32_e32 v242, v242
	v_exp_f32_e32 v243, v243
	s_nop 0
	v_pk_add_f32 v[236:237], v[236:237], 1.0 op_sel_hi:[1,0]
	v_pk_add_f32 v[238:239], v[238:239], 1.0 op_sel_hi:[1,0]
	v_pk_add_f32 v[240:241], v[240:241], 1.0 op_sel_hi:[1,0]
	v_pk_add_f32 v[242:243], v[242:243], 1.0 op_sel_hi:[1,0]
	v_rcp_f32_e32 v244, v236
	v_rcp_f32_e32 v245, v237
	v_rcp_f32_e32 v250, v238
	v_rcp_f32_e32 v251, v239
	v_pk_fma_f32 v[246:247], v[236:237], v[244:245], 1.0 op_sel_hi:[1,1,0] neg_lo:[1,0,0] neg_hi:[1,0,0]
	v_pk_fma_f32 v[252:253], v[238:239], v[250:251], 1.0 op_sel_hi:[1,1,0] neg_lo:[1,0,0] neg_hi:[1,0,0]
	v_pk_fma_f32 v[244:245], v[246:247], v[244:245], v[244:245]
	v_pk_fma_f32 v[250:251], v[252:253], v[250:251], v[250:251]
	v_pk_fma_f32 v[246:247], v[236:237], v[244:245], 1.0 op_sel_hi:[1,1,0] neg_lo:[1,0,0] neg_hi:[1,0,0]
	v_pk_fma_f32 v[252:253], v[238:239], v[250:251], 1.0 op_sel_hi:[1,1,0] neg_lo:[1,0,0] neg_hi:[1,0,0]
	v_pk_fma_f32 v[248:249], v[246:247], v[244:245], v[244:245]
	v_pk_fma_f32 v[254:255], v[252:253], v[250:251], v[250:251]
	v_pk_fma_f32 v[246:247], v[236:237], v[248:249], 1.0 op_sel_hi:[1,1,0] neg_lo:[1,0,0] neg_hi:[1,0,0]
	v_pk_fma_f32 v[252:253], v[238:239], v[254:255], 1.0 op_sel_hi:[1,1,0] neg_lo:[1,0,0] neg_hi:[1,0,0]
	v_pk_fma_f32 v[248:249], v[246:247], v[244:245], v[248:249]
	v_pk_fma_f32 v[254:255], v[252:253], v[250:251], v[254:255]
	v_div_fixup_f32 v236, v248, v236, 1.0
	v_div_fixup_f32 v237, v249, v237, 1.0
	v_div_fixup_f32 v238, v254, v238, 1.0
	v_div_fixup_f32 v239, v255, v239, 1.0
	v_rcp_f32_e32 v244, v240
	v_rcp_f32_e32 v245, v241
	v_rcp_f32_e32 v250, v242
	v_rcp_f32_e32 v251, v243
	v_pk_fma_f32 v[246:247], v[240:241], v[244:245], 1.0 op_sel_hi:[1,1,0] neg_lo:[1,0,0] neg_hi:[1,0,0]
	v_pk_fma_f32 v[252:253], v[242:243], v[250:251], 1.0 op_sel_hi:[1,1,0] neg_lo:[1,0,0] neg_hi:[1,0,0]
	v_pk_fma_f32 v[244:245], v[246:247], v[244:245], v[244:245]
	v_pk_fma_f32 v[250:251], v[252:253], v[250:251], v[250:251]
	v_pk_fma_f32 v[246:247], v[240:241], v[244:245], 1.0 op_sel_hi:[1,1,0] neg_lo:[1,0,0] neg_hi:[1,0,0]
	v_pk_fma_f32 v[252:253], v[242:243], v[250:251], 1.0 op_sel_hi:[1,1,0] neg_lo:[1,0,0] neg_hi:[1,0,0]
	v_pk_fma_f32 v[248:249], v[246:247], v[244:245], v[244:245]
	v_pk_fma_f32 v[254:255], v[252:253], v[250:251], v[250:251]
	v_pk_fma_f32 v[246:247], v[240:241], v[248:249], 1.0 op_sel_hi:[1,1,0] neg_lo:[1,0,0] neg_hi:[1,0,0]
	v_pk_fma_f32 v[252:253], v[242:243], v[254:255], 1.0 op_sel_hi:[1,1,0] neg_lo:[1,0,0] neg_hi:[1,0,0]
	v_pk_fma_f32 v[248:249], v[246:247], v[244:245], v[248:249]
	v_pk_fma_f32 v[254:255], v[252:253], v[250:251], v[254:255]
	v_div_fixup_f32 v240, v248, v240, 1.0
	v_div_fixup_f32 v241, v249, v241, 1.0
	v_div_fixup_f32 v242, v254, v242, 1.0
	v_div_fixup_f32 v243, v255, v243, 1.0
	v_mul_f32_e32 v92, v92, v236
	v_mul_f32_e32 v98, v88, v238
	v_mul_f32_e32 v88, v93, v237
	v_mul_f32_e32 v93, v89, v239
	v_mul_f32_e32 v89, v94, v240
	v_mul_f32_e32 v94, v90, v242
	v_mul_f32_e32 v90, v95, v241
	v_mul_f32_e32 v91, v91, v243
	v_cvt_pk_bf16_f32 v88, v92, v88
	v_cvt_pk_bf16_f32 v89, v89, v90
	v_cvt_pk_bf16_f32 v90, v98, v93
	v_cvt_pk_bf16_f32 v91, v94, v91
	s_waitcnt vmcnt(9)
; __device__ __forceinline__ float sigmoidf_(float x) { return 1.0f / (1.0f + __expf(-x)); }
; __device__ __forceinline__ u32x4 pack8(const f32x4 v0, const f32x4 v1) { u32x4 w; w.x = pk2(v0[0], v0[1]); w.y = pk2(v0[2], v0[3]); w.z = pk2(v1[0], v1[1]); w.w = pk2(v1[2], v1[3]); return w; }
; __device__ __forceinline__ void unpack8(const u32x4 w, f32x4& v0, f32x4& v1) { v0 = (f32x4){bflo(w.x), bfhi(w.x), bflo(w.y), bfhi(w.y)}; v1 = (f32x4){bflo(w.z), bfhi(w.z), bflo(w.w), bfhi(w.w)}; }
;     __device__ __forceinline__ void operator()(const f32x4 (&acc)[2][2][4][2], const Unit& u, int wr, int wc, int fr, int fq) const {
;     ...
;         for (int ai = 0; ai < 2; ++ai)
; #pragma unroll
;             for (int m = 0; m < 4; ++m) {
;                 bf16_t* rowp = z + (size_t)(row0 + ai * 128 + m * 16) * DIN + col0;
; #pragma unroll
;                 for (int bj = 0; bj < 2; ++bj) {
;                     const u32x4 gw = *(const u32x4*)(rowp + (MODE == 0 ? O_GB : O_GA) + bj * 128);
;                     f32x4 g0, g1; unpack8(gw, g0, g1);
;                     f32x4 v0, v1;
; #pragma unroll
;                     for (int j = 0; j < 4; ++j) { v0[j] = sigmoidf_(g0[j]) * acc[ai][bj][m][0][j]; v1[j] = sigmoidf_(g1[j]) * acc[ai][bj][m][1][j]; }
;                     if (MODE == 1) { const u32x4 mw = *(const u32x4*)(rowp + bj * 128); f32x4 m0, m1; unpack8(mw, m0, m1); v0 += m0; v1 += m1; }
;                     *(u32x4*)(rowp + bj * 128) = pack8(v0, v1); }
	v_mov_b32_e32 v92, v232
	v_mov_b32_e32 v93, v233
	v_mov_b32_e32 v94, v234
	v_mov_b32_e32 v95, v235
	v_add_u32_e32 v198, 0x133b00, v197
	global_load_dwordx4 v[232:235], v198, s[22:23]
	s_mov_b32 s100, 0xbfb8aa3b
	v_lshlrev_b32_e32 v236, 16, v92
	v_and_b32_e32 v237, 0xffff0000, v92
	v_lshlrev_b32_e32 v238, 16, v94
	v_and_b32_e32 v239, 0xffff0000, v94
	v_lshlrev_b32_e32 v240, 16, v93
	v_and_b32_e32 v241, 0xffff0000, v93
	v_lshlrev_b32_e32 v242, 16, v95
	v_and_b32_e32 v243, 0xffff0000, v95
	v_pk_mul_f32 v[236:237], v[236:237], s[100:101] op_sel_hi:[1,0]
	v_pk_mul_f32 v[238:239], v[238:239], s[100:101] op_sel_hi:[1,0]
	v_pk_mul_f32 v[240:241], v[240:241], s[100:101] op_sel_hi:[1,0]
	v_pk_mul_f32 v[242:243], v[242:243], s[100:101] op_sel_hi:[1,0]
	v_exp_f32_e32 v236, v236
	v_exp_f32_e32 v237, v237
	v_exp_f32_e32 v238, v238
	v_exp_f32_e32 v239, v239
	v_exp_f32_e32 v240, v240
	v_exp_f32_e32 v241, v241
	v_exp_f32_e32 v242, v242
	v_exp_f32_e32 v243, v243
	s_nop 0
	v_pk_add_f32 v[236:237], v[236:237], 1.0 op_sel_hi:[1,0]
	v_pk_add_f32 v[238:239], v[238:239], 1.0 op_sel_hi:[1,0]
	v_pk_add_f32 v[240:241], v[240:241], 1.0 op_sel_hi:[1,0]
	v_pk_add_f32 v[242:243], v[242:243], 1.0 op_sel_hi:[1,0]
	v_rcp_f32_e32 v244, v236
	v_rcp_f32_e32 v245, v237
	v_rcp_f32_e32 v250, v238
	v_rcp_f32_e32 v251, v239
	v_pk_fma_f32 v[246:247], v[236:237], v[244:245], 1.0 op_sel_hi:[1,1,0] neg_lo:[1,0,0] neg_hi:[1,0,0]
	v_pk_fma_f32 v[252:253], v[238:239], v[250:251], 1.0 op_sel_hi:[1,1,0] neg_lo:[1,0,0] neg_hi:[1,0,0]
	v_pk_fma_f32 v[244:245], v[246:247], v[244:245], v[244:245]
	v_pk_fma_f32 v[250:251], v[252:253], v[250:251], v[250:251]
	v_pk_fma_f32 v[246:247], v[236:237], v[244:245], 1.0 op_sel_hi:[1,1,0] neg_lo:[1,0,0] neg_hi:[1,0,0]
	v_pk_fma_f32 v[252:253], v[238:239], v[250:251], 1.0 op_sel_hi:[1,1,0] neg_lo:[1,0,0] neg_hi:[1,0,0]
	v_pk_fma_f32 v[248:249], v[246:247], v[244:245], v[244:245]
	v_pk_fma_f32 v[254:255], v[252:253], v[250:251], v[250:251]
	v_pk_fma_f32 v[246:247], v[236:237], v[248:249], 1.0 op_sel_hi:[1,1,0] neg_lo:[1,0,0] neg_hi:[1,0,0]
	v_pk_fma_f32 v[252:253], v[238:239], v[254:255], 1.0 op_sel_hi:[1,1,0] neg_lo:[1,0,0] neg_hi:[1,0,0]
	v_pk_fma_f32 v[248:249], v[246:247], v[244:245], v[248:249]
	v_pk_fma_f32 v[254:255], v[252:253], v[250:251], v[254:255]
	v_div_fixup_f32 v236, v248, v236, 1.0
	v_div_fixup_f32 v237, v249, v237, 1.0
	v_div_fixup_f32 v238, v254, v238, 1.0
	v_div_fixup_f32 v239, v255, v239, 1.0
	v_rcp_f32_e32 v244, v240
	v_rcp_f32_e32 v245, v241
	v_rcp_f32_e32 v250, v242
	v_rcp_f32_e32 v251, v243
	v_pk_fma_f32 v[246:247], v[240:241], v[244:245], 1.0 op_sel_hi:[1,1,0] neg_lo:[1,0,0] neg_hi:[1,0,0]
	v_pk_fma_f32 v[252:253], v[242:243], v[250:251], 1.0 op_sel_hi:[1,1,0] neg_lo:[1,0,0] neg_hi:[1,0,0]
	v_pk_fma_f32 v[244:245], v[246:247], v[244:245], v[244:245]
	v_pk_fma_f32 v[250:251], v[252:253], v[250:251], v[250:251]
	v_pk_fma_f32 v[246:247], v[240:241], v[244:245], 1.0 op_sel_hi:[1,1,0] neg_lo:[1,0,0] neg_hi:[1,0,0]
	v_pk_fma_f32 v[252:253], v[242:243], v[250:251], 1.0 op_sel_hi:[1,1,0] neg_lo:[1,0,0] neg_hi:[1,0,0]
	v_pk_fma_f32 v[248:249], v[246:247], v[244:245], v[244:245]
	v_pk_fma_f32 v[254:255], v[252:253], v[250:251], v[250:251]
	v_pk_fma_f32 v[246:247], v[240:241], v[248:249], 1.0 op_sel_hi:[1,1,0] neg_lo:[1,0,0] neg_hi:[1,0,0]
	v_pk_fma_f32 v[252:253], v[242:243], v[254:255], 1.0 op_sel_hi:[1,1,0] neg_lo:[1,0,0] neg_hi:[1,0,0]
	v_pk_fma_f32 v[248:249], v[246:247], v[244:245], v[248:249]
	v_pk_fma_f32 v[254:255], v[252:253], v[250:251], v[254:255]
	v_div_fixup_f32 v240, v248, v240, 1.0
	v_div_fixup_f32 v241, v249, v241, 1.0
	v_div_fixup_f32 v242, v254, v242, 1.0
	v_div_fixup_f32 v243, v255, v243, 1.0
	global_store_dwordx4 v[96:97], v[88:91], off
	s_nop 0
	v_pk_mul_f32 v[84:85], v[84:85], v[236:237]
	v_pk_mul_f32 v[80:81], v[80:81], v[238:239]
	v_pk_mul_f32 v[86:87], v[86:87], v[240:241]
	v_pk_mul_f32 v[88:89], v[82:83], v[242:243]
	v_cvt_pk_bf16_f32 v82, v84, v85
	v_cvt_pk_bf16_f32 v83, v86, v87
	v_cvt_pk_bf16_f32 v84, v80, v81
	v_or_b32_e32 v80, 48, v160
	v_mad_i64_i32 v[80:81], s[6:7], v80, s57, v[146:147]
	v_lshl_add_u64 v[80:81], v[80:81], 0, v[148:149]
	v_add_co_u32_e32 v90, vcc, s58, v80
	v_cvt_pk_bf16_f32 v85, v88, v89
	global_store_dwordx4 v[96:97], v[82:85], off offset:256
	s_nop 0
	v_addc_co_u32_e32 v91, vcc, 0, v81, vcc
	s_waitcnt vmcnt(11)
; __device__ __forceinline__ float sigmoidf_(float x) { return 1.0f / (1.0f + __expf(-x)); }
; __device__ __forceinline__ u32x4 pack8(const f32x4 v0, const f32x4 v1) { u32x4 w; w.x = pk2(v0[0], v0[1]); w.y = pk2(v0[2], v0[3]); w.z = pk2(v1[0], v1[1]); w.w = pk2(v1[2], v1[3]); return w; }
; __device__ __forceinline__ void unpack8(const u32x4 w, f32x4& v0, f32x4& v1) { v0 = (f32x4){bflo(w.x), bfhi(w.x), bflo(w.y), bfhi(w.y)}; v1 = (f32x4){bflo(w.z), bfhi(w.z), bflo(w.w), bfhi(w.w)}; }
;     __device__ __forceinline__ void operator()(const f32x4 (&acc)[2][2][4][2], const Unit& u, int wr, int wc, int fr, int fq) const {
;     ...
;         for (int ai = 0; ai < 2; ++ai)
; #pragma unroll
;             for (int m = 0; m < 4; ++m) {
;                 bf16_t* rowp = z + (size_t)(row0 + ai * 128 + m * 16) * DIN + col0;
; #pragma unroll
;                 for (int bj = 0; bj < 2; ++bj) {
;                     const u32x4 gw = *(const u32x4*)(rowp + (MODE == 0 ? O_GB : O_GA) + bj * 128);
;                     f32x4 g0, g1; unpack8(gw, g0, g1);
;                     f32x4 v0, v1;
; #pragma unroll
;                     for (int j = 0; j < 4; ++j) { v0[j] = sigmoidf_(g0[j]) * acc[ai][bj][m][0][j]; v1[j] = sigmoidf_(g1[j]) * acc[ai][bj][m][1][j]; }
;                     if (MODE == 1) { const u32x4 mw = *(const u32x4*)(rowp + bj * 128); f32x4 m0, m1; unpack8(mw, m0, m1); v0 += m0; v1 += m1; }
;                     *(u32x4*)(rowp + bj * 128) = pack8(v0, v1); }
	v_mov_b32_e32 v86, v200
	v_mov_b32_e32 v87, v201
	v_mov_b32_e32 v88, v202
	v_mov_b32_e32 v89, v203
	v_add_u32_e32 v198, 0x155a00, v197
	global_load_dwordx4 v[200:203], v198, s[22:23]
	s_mov_b32 s100, 0xbfb8aa3b
	v_lshlrev_b32_e32 v236, 16, v86
	v_and_b32_e32 v237, 0xffff0000, v86
	v_lshlrev_b32_e32 v238, 16, v88
	v_and_b32_e32 v239, 0xffff0000, v88
	v_lshlrev_b32_e32 v240, 16, v87
	v_and_b32_e32 v241, 0xffff0000, v87
	v_lshlrev_b32_e32 v242, 16, v89
	v_and_b32_e32 v243, 0xffff0000, v89
	v_pk_mul_f32 v[236:237], v[236:237], s[100:101] op_sel_hi:[1,0]
	v_pk_mul_f32 v[238:239], v[238:239], s[100:101] op_sel_hi:[1,0]
	v_pk_mul_f32 v[240:241], v[240:241], s[100:101] op_sel_hi:[1,0]
	v_pk_mul_f32 v[242:243], v[242:243], s[100:101] op_sel_hi:[1,0]
	v_exp_f32_e32 v236, v236
	v_exp_f32_e32 v237, v237
	v_exp_f32_e32 v238, v238
	v_exp_f32_e32 v239, v239
	v_exp_f32_e32 v240, v240
	v_exp_f32_e32 v241, v241
	v_exp_f32_e32 v242, v242
	v_exp_f32_e32 v243, v243
	s_nop 0
	v_pk_add_f32 v[236:237], v[236:237], 1.0 op_sel_hi:[1,0]
	v_pk_add_f32 v[238:239], v[238:239], 1.0 op_sel_hi:[1,0]
	v_pk_add_f32 v[240:241], v[240:241], 1.0 op_sel_hi:[1,0]
	v_pk_add_f32 v[242:243], v[242:243], 1.0 op_sel_hi:[1,0]
	v_rcp_f32_e32 v244, v236
	v_rcp_f32_e32 v245, v237
	v_rcp_f32_e32 v250, v238
	v_rcp_f32_e32 v251, v239
	v_pk_fma_f32 v[246:247], v[236:237], v[244:245], 1.0 op_sel_hi:[1,1,0] neg_lo:[1,0,0] neg_hi:[1,0,0]
	v_pk_fma_f32 v[252:253], v[238:239], v[250:251], 1.0 op_sel_hi:[1,1,0] neg_lo:[1,0,0] neg_hi:[1,0,0]
	v_pk_fma_f32 v[244:245], v[246:247], v[244:245], v[244:245]
	v_pk_fma_f32 v[250:251], v[252:253], v[250:251], v[250:251]
	v_pk_fma_f32 v[246:247], v[236:237], v[244:245], 1.0 op_sel_hi:[1,1,0] neg_lo:[1,0,0] neg_hi:[1,0,0]
	v_pk_fma_f32 v[252:253], v[238:239], v[250:251], 1.0 op_sel_hi:[1,1,0] neg_lo:[1,0,0] neg_hi:[1,0,0]
	v_pk_fma_f32 v[248:249], v[246:247], v[244:245], v[244:245]
	v_pk_fma_f32 v[254:255], v[252:253], v[250:251], v[250:251]
	v_pk_fma_f32 v[246:247], v[236:237], v[248:249], 1.0 op_sel_hi:[1,1,0] neg_lo:[1,0,0] neg_hi:[1,0,0]
	v_pk_fma_f32 v[252:253], v[238:239], v[254:255], 1.0 op_sel_hi:[1,1,0] neg_lo:[1,0,0] neg_hi:[1,0,0]
	v_pk_fma_f32 v[248:249], v[246:247], v[244:245], v[248:249]
	v_pk_fma_f32 v[254:255], v[252:253], v[250:251], v[254:255]
	v_div_fixup_f32 v236, v248, v236, 1.0
	v_div_fixup_f32 v237, v249, v237, 1.0
	v_div_fixup_f32 v238, v254, v238, 1.0
	v_div_fixup_f32 v239, v255, v239, 1.0
	v_rcp_f32_e32 v244, v240
	v_rcp_f32_e32 v245, v241
	v_rcp_f32_e32 v250, v242
	v_rcp_f32_e32 v251, v243
	v_pk_fma_f32 v[246:247], v[240:241], v[244:245], 1.0 op_sel_hi:[1,1,0] neg_lo:[1,0,0] neg_hi:[1,0,0]
	v_pk_fma_f32 v[252:253], v[242:243], v[250:251], 1.0 op_sel_hi:[1,1,0] neg_lo:[1,0,0] neg_hi:[1,0,0]
	v_pk_fma_f32 v[244:245], v[246:247], v[244:245], v[244:245]
	v_pk_fma_f32 v[250:251], v[252:253], v[250:251], v[250:251]
	v_pk_fma_f32 v[246:247], v[240:241], v[244:245], 1.0 op_sel_hi:[1,1,0] neg_lo:[1,0,0] neg_hi:[1,0,0]
	v_pk_fma_f32 v[252:253], v[242:243], v[250:251], 1.0 op_sel_hi:[1,1,0] neg_lo:[1,0,0] neg_hi:[1,0,0]
	v_pk_fma_f32 v[248:249], v[246:247], v[244:245], v[244:245]
	v_pk_fma_f32 v[254:255], v[252:253], v[250:251], v[250:251]
	v_pk_fma_f32 v[246:247], v[240:241], v[248:249], 1.0 op_sel_hi:[1,1,0] neg_lo:[1,0,0] neg_hi:[1,0,0]
	v_pk_fma_f32 v[252:253], v[242:243], v[254:255], 1.0 op_sel_hi:[1,1,0] neg_lo:[1,0,0] neg_hi:[1,0,0]
	v_pk_fma_f32 v[248:249], v[246:247], v[244:245], v[248:249]
	v_pk_fma_f32 v[254:255], v[252:253], v[250:251], v[254:255]
	v_div_fixup_f32 v240, v248, v240, 1.0
	v_div_fixup_f32 v241, v249, v241, 1.0
	v_div_fixup_f32 v242, v254, v242, 1.0
	v_div_fixup_f32 v243, v255, v243, 1.0
	v_mul_f32_e32 v76, v76, v236
	v_mul_f32_e32 v82, v72, v238
	v_mul_f32_e32 v72, v77, v237
	v_mul_f32_e32 v77, v73, v239
	v_mul_f32_e32 v73, v78, v240
	v_mul_f32_e32 v78, v74, v242
	v_mul_f32_e32 v74, v79, v241
	v_mul_f32_e32 v75, v75, v243
	v_cvt_pk_bf16_f32 v72, v76, v72
	v_cvt_pk_bf16_f32 v73, v73, v74
	v_cvt_pk_bf16_f32 v74, v82, v77
	v_cvt_pk_bf16_f32 v75, v78, v75
	s_waitcnt vmcnt(10)
	v_mov_b32_e32 v76, v204
	v_mov_b32_e32 v77, v205
	v_mov_b32_e32 v78, v206
	v_mov_b32_e32 v79, v207
	v_add_u32_e32 v198, 0x155b00, v197
	global_load_dwordx4 v[204:207], v198, s[22:23]
	s_mov_b32 s100, 0xbfb8aa3b
	v_lshlrev_b32_e32 v236, 16, v76
	v_and_b32_e32 v237, 0xffff0000, v76
	v_lshlrev_b32_e32 v238, 16, v78
	v_and_b32_e32 v239, 0xffff0000, v78
	v_lshlrev_b32_e32 v240, 16, v77
	v_and_b32_e32 v241, 0xffff0000, v77
	v_lshlrev_b32_e32 v242, 16, v79
	v_and_b32_e32 v243, 0xffff0000, v79
	v_pk_mul_f32 v[236:237], v[236:237], s[100:101] op_sel_hi:[1,0]
	v_pk_mul_f32 v[238:239], v[238:239], s[100:101] op_sel_hi:[1,0]
	v_pk_mul_f32 v[240:241], v[240:241], s[100:101] op_sel_hi:[1,0]
	v_pk_mul_f32 v[242:243], v[242:243], s[100:101] op_sel_hi:[1,0]
	v_exp_f32_e32 v236, v236
	v_exp_f32_e32 v237, v237
	v_exp_f32_e32 v238, v238
	v_exp_f32_e32 v239, v239
	v_exp_f32_e32 v240, v240
	v_exp_f32_e32 v241, v241
	v_exp_f32_e32 v242, v242
	v_exp_f32_e32 v243, v243
	s_nop 0
	v_pk_add_f32 v[236:237], v[236:237], 1.0 op_sel_hi:[1,0]
	v_pk_add_f32 v[238:239], v[238:239], 1.0 op_sel_hi:[1,0]
	v_pk_add_f32 v[240:241], v[240:241], 1.0 op_sel_hi:[1,0]
	v_pk_add_f32 v[242:243], v[242:243], 1.0 op_sel_hi:[1,0]
	v_rcp_f32_e32 v244, v236
	v_rcp_f32_e32 v245, v237
	v_rcp_f32_e32 v250, v238
	v_rcp_f32_e32 v251, v239
	v_pk_fma_f32 v[246:247], v[236:237], v[244:245], 1.0 op_sel_hi:[1,1,0] neg_lo:[1,0,0] neg_hi:[1,0,0]
	v_pk_fma_f32 v[252:253], v[238:239], v[250:251], 1.0 op_sel_hi:[1,1,0] neg_lo:[1,0,0] neg_hi:[1,0,0]
	v_pk_fma_f32 v[244:245], v[246:247], v[244:245], v[244:245]
; __device__ __forceinline__ float sigmoidf_(float x) { return 1.0f / (1.0f + __expf(-x)); }
; __device__ __forceinline__ u32x4 pack8(const f32x4 v0, const f32x4 v1) { u32x4 w; w.x = pk2(v0[0], v0[1]); w.y = pk2(v0[2], v0[3]); w.z = pk2(v1[0], v1[1]); w.w = pk2(v1[2], v1[3]); return w; }
; __device__ __forceinline__ void unpack8(const u32x4 w, f32x4& v0, f32x4& v1) { v0 = (f32x4){bflo(w.x), bfhi(w.x), bflo(w.y), bfhi(w.y)}; v1 = (f32x4){bflo(w.z), bfhi(w.z), bflo(w.w), bfhi(w.w)}; }
;     __device__ __forceinline__ void operator()(const f32x4 (&acc)[2][2][4][2], const Unit& u, int wr, int wc, int fr, int fq) const {
;     ...
;         for (int ai = 0; ai < 2; ++ai)
; #pragma unroll
;             for (int m = 0; m < 4; ++m) {
;                 bf16_t* rowp = z + (size_t)(row0 + ai * 128 + m * 16) * DIN + col0;
; #pragma unroll
;                 for (int bj = 0; bj < 2; ++bj) {
;                     const u32x4 gw = *(const u32x4*)(rowp + (MODE == 0 ? O_GB : O_GA) + bj * 128);
;                     f32x4 g0, g1; unpack8(gw, g0, g1);
;                     f32x4 v0, v1;
; #pragma unroll
;                     for (int j = 0; j < 4; ++j) { v0[j] = sigmoidf_(g0[j]) * acc[ai][bj][m][0][j]; v1[j] = sigmoidf_(g1[j]) * acc[ai][bj][m][1][j]; }
;                     if (MODE == 1) { const u32x4 mw = *(const u32x4*)(rowp + bj * 128); f32x4 m0, m1; unpack8(mw, m0, m1); v0 += m0; v1 += m1; }
;                     *(u32x4*)(rowp + bj * 128) = pack8(v0, v1); }
	v_pk_fma_f32 v[250:251], v[252:253], v[250:251], v[250:251]
	v_pk_fma_f32 v[246:247], v[236:237], v[244:245], 1.0 op_sel_hi:[1,1,0] neg_lo:[1,0,0] neg_hi:[1,0,0]
	v_pk_fma_f32 v[252:253], v[238:239], v[250:251], 1.0 op_sel_hi:[1,1,0] neg_lo:[1,0,0] neg_hi:[1,0,0]
	v_pk_fma_f32 v[248:249], v[246:247], v[244:245], v[244:245]
	v_pk_fma_f32 v[254:255], v[252:253], v[250:251], v[250:251]
	v_pk_fma_f32 v[246:247], v[236:237], v[248:249], 1.0 op_sel_hi:[1,1,0] neg_lo:[1,0,0] neg_hi:[1,0,0]
	v_pk_fma_f32 v[252:253], v[238:239], v[254:255], 1.0 op_sel_hi:[1,1,0] neg_lo:[1,0,0] neg_hi:[1,0,0]
	v_pk_fma_f32 v[248:249], v[246:247], v[244:245], v[248:249]
	v_pk_fma_f32 v[254:255], v[252:253], v[250:251], v[254:255]
	v_div_fixup_f32 v236, v248, v236, 1.0
	v_div_fixup_f32 v237, v249, v237, 1.0
	v_div_fixup_f32 v238, v254, v238, 1.0
	v_div_fixup_f32 v239, v255, v239, 1.0
	v_rcp_f32_e32 v244, v240
	v_rcp_f32_e32 v245, v241
	v_rcp_f32_e32 v250, v242
	v_rcp_f32_e32 v251, v243
	v_pk_fma_f32 v[246:247], v[240:241], v[244:245], 1.0 op_sel_hi:[1,1,0] neg_lo:[1,0,0] neg_hi:[1,0,0]
	v_pk_fma_f32 v[252:253], v[242:243], v[250:251], 1.0 op_sel_hi:[1,1,0] neg_lo:[1,0,0] neg_hi:[1,0,0]
	v_pk_fma_f32 v[244:245], v[246:247], v[244:245], v[244:245]
	v_pk_fma_f32 v[250:251], v[252:253], v[250:251], v[250:251]
	v_pk_fma_f32 v[246:247], v[240:241], v[244:245], 1.0 op_sel_hi:[1,1,0] neg_lo:[1,0,0] neg_hi:[1,0,0]
	v_pk_fma_f32 v[252:253], v[242:243], v[250:251], 1.0 op_sel_hi:[1,1,0] neg_lo:[1,0,0] neg_hi:[1,0,0]
	v_pk_fma_f32 v[248:249], v[246:247], v[244:245], v[244:245]
	v_pk_fma_f32 v[254:255], v[252:253], v[250:251], v[250:251]
	v_pk_fma_f32 v[246:247], v[240:241], v[248:249], 1.0 op_sel_hi:[1,1,0] neg_lo:[1,0,0] neg_hi:[1,0,0]
	v_pk_fma_f32 v[252:253], v[242:243], v[254:255], 1.0 op_sel_hi:[1,1,0] neg_lo:[1,0,0] neg_hi:[1,0,0]
	v_pk_fma_f32 v[248:249], v[246:247], v[244:245], v[248:249]
	v_pk_fma_f32 v[254:255], v[252:253], v[250:251], v[254:255]
	v_div_fixup_f32 v240, v248, v240, 1.0
	v_div_fixup_f32 v241, v249, v241, 1.0
	v_div_fixup_f32 v242, v254, v242, 1.0
	v_div_fixup_f32 v243, v255, v243, 1.0
	global_store_dwordx4 v[80:81], v[72:75], off
	s_nop 0
	v_pk_mul_f32 v[68:69], v[68:69], v[236:237]
	v_pk_mul_f32 v[64:65], v[64:65], v[238:239]
	v_pk_mul_f32 v[70:71], v[70:71], v[240:241]
	v_pk_mul_f32 v[72:73], v[66:67], v[242:243]
	v_cvt_pk_bf16_f32 v66, v68, v69
	v_cvt_pk_bf16_f32 v67, v70, v71
	v_cvt_pk_bf16_f32 v68, v64, v65
	v_add_u32_e32 v64, 0x80, v160
	v_mad_i64_i32 v[64:65], s[6:7], v64, s57, v[146:147]
	v_lshl_add_u64 v[64:65], v[64:65], 0, v[148:149]
	v_add_co_u32_e32 v74, vcc, s58, v64
	v_cvt_pk_bf16_f32 v69, v72, v73
	global_store_dwordx4 v[80:81], v[66:69], off offset:256
	s_nop 0
	v_addc_co_u32_e32 v75, vcc, 0, v65, vcc
	s_waitcnt vmcnt(11)
	v_mov_b32_e32 v70, v208
	v_mov_b32_e32 v71, v209
	v_mov_b32_e32 v72, v210
	v_mov_b32_e32 v73, v211
	v_add_u32_e32 v198, 0x177a00, v197
	global_load_dwordx4 v[208:211], v198, s[22:23]
	s_mov_b32 s100, 0xbfb8aa3b
	v_lshlrev_b32_e32 v236, 16, v70
	v_and_b32_e32 v237, 0xffff0000, v70
	v_lshlrev_b32_e32 v238, 16, v72
	v_and_b32_e32 v239, 0xffff0000, v72
	v_lshlrev_b32_e32 v240, 16, v71
	v_and_b32_e32 v241, 0xffff0000, v71
	v_lshlrev_b32_e32 v242, 16, v73
	v_and_b32_e32 v243, 0xffff0000, v73
	v_pk_mul_f32 v[236:237], v[236:237], s[100:101] op_sel_hi:[1,0]
	v_pk_mul_f32 v[238:239], v[238:239], s[100:101] op_sel_hi:[1,0]
	v_pk_mul_f32 v[240:241], v[240:241], s[100:101] op_sel_hi:[1,0]
	v_pk_mul_f32 v[242:243], v[242:243], s[100:101] op_sel_hi:[1,0]
	v_exp_f32_e32 v236, v236
	v_exp_f32_e32 v237, v237
	v_exp_f32_e32 v238, v238
	v_exp_f32_e32 v239, v239
	v_exp_f32_e32 v240, v240
	v_exp_f32_e32 v241, v241
	v_exp_f32_e32 v242, v242
	v_exp_f32_e32 v243, v243
	s_nop 0
	v_pk_add_f32 v[236:237], v[236:237], 1.0 op_sel_hi:[1,0]
	v_pk_add_f32 v[238:239], v[238:239], 1.0 op_sel_hi:[1,0]
	v_pk_add_f32 v[240:241], v[240:241], 1.0 op_sel_hi:[1,0]
	v_pk_add_f32 v[242:243], v[242:243], 1.0 op_sel_hi:[1,0]
	v_rcp_f32_e32 v244, v236
	v_rcp_f32_e32 v245, v237
	v_rcp_f32_e32 v250, v238
	v_rcp_f32_e32 v251, v239
	v_pk_fma_f32 v[246:247], v[236:237], v[244:245], 1.0 op_sel_hi:[1,1,0] neg_lo:[1,0,0] neg_hi:[1,0,0]
	v_pk_fma_f32 v[252:253], v[238:239], v[250:251], 1.0 op_sel_hi:[1,1,0] neg_lo:[1,0,0] neg_hi:[1,0,0]
	v_pk_fma_f32 v[244:245], v[246:247], v[244:245], v[244:245]
	v_pk_fma_f32 v[250:251], v[252:253], v[250:251], v[250:251]
	v_pk_fma_f32 v[246:247], v[236:237], v[244:245], 1.0 op_sel_hi:[1,1,0] neg_lo:[1,0,0] neg_hi:[1,0,0]
	v_pk_fma_f32 v[252:253], v[238:239], v[250:251], 1.0 op_sel_hi:[1,1,0] neg_lo:[1,0,0] neg_hi:[1,0,0]
	v_pk_fma_f32 v[248:249], v[246:247], v[244:245], v[244:245]
	v_pk_fma_f32 v[254:255], v[252:253], v[250:251], v[250:251]
	v_pk_fma_f32 v[246:247], v[236:237], v[248:249], 1.0 op_sel_hi:[1,1,0] neg_lo:[1,0,0] neg_hi:[1,0,0]
	v_pk_fma_f32 v[252:253], v[238:239], v[254:255], 1.0 op_sel_hi:[1,1,0] neg_lo:[1,0,0] neg_hi:[1,0,0]
	v_pk_fma_f32 v[248:249], v[246:247], v[244:245], v[248:249]
	v_pk_fma_f32 v[254:255], v[252:253], v[250:251], v[254:255]
	v_div_fixup_f32 v236, v248, v236, 1.0
	v_div_fixup_f32 v237, v249, v237, 1.0
	v_div_fixup_f32 v238, v254, v238, 1.0
	v_div_fixup_f32 v239, v255, v239, 1.0
	v_rcp_f32_e32 v244, v240
	v_rcp_f32_e32 v245, v241
	v_rcp_f32_e32 v250, v242
	v_rcp_f32_e32 v251, v243
	v_pk_fma_f32 v[246:247], v[240:241], v[244:245], 1.0 op_sel_hi:[1,1,0] neg_lo:[1,0,0] neg_hi:[1,0,0]
	v_pk_fma_f32 v[252:253], v[242:243], v[250:251], 1.0 op_sel_hi:[1,1,0] neg_lo:[1,0,0] neg_hi:[1,0,0]
	v_pk_fma_f32 v[244:245], v[246:247], v[244:245], v[244:245]
	v_pk_fma_f32 v[250:251], v[252:253], v[250:251], v[250:251]
	v_pk_fma_f32 v[246:247], v[240:241], v[244:245], 1.0 op_sel_hi:[1,1,0] neg_lo:[1,0,0] neg_hi:[1,0,0]
	v_pk_fma_f32 v[252:253], v[242:243], v[250:251], 1.0 op_sel_hi:[1,1,0] neg_lo:[1,0,0] neg_hi:[1,0,0]
	v_pk_fma_f32 v[248:249], v[246:247], v[244:245], v[244:245]
	v_pk_fma_f32 v[254:255], v[252:253], v[250:251], v[250:251]
	v_pk_fma_f32 v[246:247], v[240:241], v[248:249], 1.0 op_sel_hi:[1,1,0] neg_lo:[1,0,0] neg_hi:[1,0,0]
	v_pk_fma_f32 v[252:253], v[242:243], v[254:255], 1.0 op_sel_hi:[1,1,0] neg_lo:[1,0,0] neg_hi:[1,0,0]
	v_pk_fma_f32 v[248:249], v[246:247], v[244:245], v[248:249]
	v_pk_fma_f32 v[254:255], v[252:253], v[250:251], v[254:255]
	v_div_fixup_f32 v240, v248, v240, 1.0
	v_div_fixup_f32 v241, v249, v241, 1.0
	v_div_fixup_f32 v242, v254, v242, 1.0
	v_div_fixup_f32 v243, v255, v243, 1.0
	v_mul_f32_e32 v60, v60, v236
	v_mul_f32_e32 v66, v56, v238
	v_mul_f32_e32 v56, v61, v237
	v_mul_f32_e32 v61, v57, v239
	v_mul_f32_e32 v57, v62, v240
	v_mul_f32_e32 v62, v58, v242
	v_mul_f32_e32 v58, v63, v241
	v_mul_f32_e32 v59, v59, v243
	v_cvt_pk_bf16_f32 v56, v60, v56
	v_cvt_pk_bf16_f32 v57, v57, v58
	v_cvt_pk_bf16_f32 v58, v66, v61
	v_cvt_pk_bf16_f32 v59, v62, v59
	s_waitcnt vmcnt(11)
; __device__ __forceinline__ float sigmoidf_(float x) { return 1.0f / (1.0f + __expf(-x)); }
; __device__ __forceinline__ u32x4 pack8(const f32x4 v0, const f32x4 v1) { u32x4 w; w.x = pk2(v0[0], v0[1]); w.y = pk2(v0[2], v0[3]); w.z = pk2(v1[0], v1[1]); w.w = pk2(v1[2], v1[3]); return w; }
; __device__ __forceinline__ void unpack8(const u32x4 w, f32x4& v0, f32x4& v1) { v0 = (f32x4){bflo(w.x), bfhi(w.x), bflo(w.y), bfhi(w.y)}; v1 = (f32x4){bflo(w.z), bfhi(w.z), bflo(w.w), bfhi(w.w)}; }
;     __device__ __forceinline__ void operator()(const f32x4 (&acc)[2][2][4][2], const Unit& u, int wr, int wc, int fr, int fq) const {
;     ...
;         for (int ai = 0; ai < 2; ++ai)
; #pragma unroll
;             for (int m = 0; m < 4; ++m) {
;                 bf16_t* rowp = z + (size_t)(row0 + ai * 128 + m * 16) * DIN + col0;
; #pragma unroll
;                 for (int bj = 0; bj < 2; ++bj) {
;                     const u32x4 gw = *(const u32x4*)(rowp + (MODE == 0 ? O_GB : O_GA) + bj * 128);
;                     f32x4 g0, g1; unpack8(gw, g0, g1);
;                     f32x4 v0, v1;
; #pragma unroll
;                     for (int j = 0; j < 4; ++j) { v0[j] = sigmoidf_(g0[j]) * acc[ai][bj][m][0][j]; v1[j] = sigmoidf_(g1[j]) * acc[ai][bj][m][1][j]; }
;                     if (MODE == 1) { const u32x4 mw = *(const u32x4*)(rowp + bj * 128); f32x4 m0, m1; unpack8(mw, m0, m1); v0 += m0; v1 += m1; }
;                     *(u32x4*)(rowp + bj * 128) = pack8(v0, v1); }
	v_mov_b32_e32 v60, v212
	v_mov_b32_e32 v61, v213
	v_mov_b32_e32 v62, v214
	v_mov_b32_e32 v63, v215
	v_add_u32_e32 v198, 0x177b00, v197
	global_load_dwordx4 v[212:215], v198, s[22:23]
	s_mov_b32 s100, 0xbfb8aa3b
	v_lshlrev_b32_e32 v236, 16, v60
	v_and_b32_e32 v237, 0xffff0000, v60
	v_lshlrev_b32_e32 v238, 16, v62
	v_and_b32_e32 v239, 0xffff0000, v62
	v_lshlrev_b32_e32 v240, 16, v61
	v_and_b32_e32 v241, 0xffff0000, v61
	v_lshlrev_b32_e32 v242, 16, v63
	v_and_b32_e32 v243, 0xffff0000, v63
	v_pk_mul_f32 v[236:237], v[236:237], s[100:101] op_sel_hi:[1,0]
	v_pk_mul_f32 v[238:239], v[238:239], s[100:101] op_sel_hi:[1,0]
	v_pk_mul_f32 v[240:241], v[240:241], s[100:101] op_sel_hi:[1,0]
	v_pk_mul_f32 v[242:243], v[242:243], s[100:101] op_sel_hi:[1,0]
	v_exp_f32_e32 v236, v236
	v_exp_f32_e32 v237, v237
	v_exp_f32_e32 v238, v238
	v_exp_f32_e32 v239, v239
	v_exp_f32_e32 v240, v240
	v_exp_f32_e32 v241, v241
	v_exp_f32_e32 v242, v242
	v_exp_f32_e32 v243, v243
	s_nop 0
	v_pk_add_f32 v[236:237], v[236:237], 1.0 op_sel_hi:[1,0]
	v_pk_add_f32 v[238:239], v[238:239], 1.0 op_sel_hi:[1,0]
	v_pk_add_f32 v[240:241], v[240:241], 1.0 op_sel_hi:[1,0]
	v_pk_add_f32 v[242:243], v[242:243], 1.0 op_sel_hi:[1,0]
	v_rcp_f32_e32 v244, v236
	v_rcp_f32_e32 v245, v237
	v_rcp_f32_e32 v250, v238
	v_rcp_f32_e32 v251, v239
	v_pk_fma_f32 v[246:247], v[236:237], v[244:245], 1.0 op_sel_hi:[1,1,0] neg_lo:[1,0,0] neg_hi:[1,0,0]
	v_pk_fma_f32 v[252:253], v[238:239], v[250:251], 1.0 op_sel_hi:[1,1,0] neg_lo:[1,0,0] neg_hi:[1,0,0]
	v_pk_fma_f32 v[244:245], v[246:247], v[244:245], v[244:245]
	v_pk_fma_f32 v[250:251], v[252:253], v[250:251], v[250:251]
	v_pk_fma_f32 v[246:247], v[236:237], v[244:245], 1.0 op_sel_hi:[1,1,0] neg_lo:[1,0,0] neg_hi:[1,0,0]
	v_pk_fma_f32 v[252:253], v[238:239], v[250:251], 1.0 op_sel_hi:[1,1,0] neg_lo:[1,0,0] neg_hi:[1,0,0]
	v_pk_fma_f32 v[248:249], v[246:247], v[244:245], v[244:245]
	v_pk_fma_f32 v[254:255], v[252:253], v[250:251], v[250:251]
	v_pk_fma_f32 v[246:247], v[236:237], v[248:249], 1.0 op_sel_hi:[1,1,0] neg_lo:[1,0,0] neg_hi:[1,0,0]
	v_pk_fma_f32 v[252:253], v[238:239], v[254:255], 1.0 op_sel_hi:[1,1,0] neg_lo:[1,0,0] neg_hi:[1,0,0]
	v_pk_fma_f32 v[248:249], v[246:247], v[244:245], v[248:249]
	v_pk_fma_f32 v[254:255], v[252:253], v[250:251], v[254:255]
	v_div_fixup_f32 v236, v248, v236, 1.0
	v_div_fixup_f32 v237, v249, v237, 1.0
	v_div_fixup_f32 v238, v254, v238, 1.0
	v_div_fixup_f32 v239, v255, v239, 1.0
	v_rcp_f32_e32 v244, v240
	v_rcp_f32_e32 v245, v241
	v_rcp_f32_e32 v250, v242
	v_rcp_f32_e32 v251, v243
	v_pk_fma_f32 v[246:247], v[240:241], v[244:245], 1.0 op_sel_hi:[1,1,0] neg_lo:[1,0,0] neg_hi:[1,0,0]
	v_pk_fma_f32 v[252:253], v[242:243], v[250:251], 1.0 op_sel_hi:[1,1,0] neg_lo:[1,0,0] neg_hi:[1,0,0]
	v_pk_fma_f32 v[244:245], v[246:247], v[244:245], v[244:245]
	v_pk_fma_f32 v[250:251], v[252:253], v[250:251], v[250:251]
	v_pk_fma_f32 v[246:247], v[240:241], v[244:245], 1.0 op_sel_hi:[1,1,0] neg_lo:[1,0,0] neg_hi:[1,0,0]
	v_pk_fma_f32 v[252:253], v[242:243], v[250:251], 1.0 op_sel_hi:[1,1,0] neg_lo:[1,0,0] neg_hi:[1,0,0]
	v_pk_fma_f32 v[248:249], v[246:247], v[244:245], v[244:245]
	v_pk_fma_f32 v[254:255], v[252:253], v[250:251], v[250:251]
	v_pk_fma_f32 v[246:247], v[240:241], v[248:249], 1.0 op_sel_hi:[1,1,0] neg_lo:[1,0,0] neg_hi:[1,0,0]
	v_pk_fma_f32 v[252:253], v[242:243], v[254:255], 1.0 op_sel_hi:[1,1,0] neg_lo:[1,0,0] neg_hi:[1,0,0]
	v_pk_fma_f32 v[248:249], v[246:247], v[244:245], v[248:249]
	v_pk_fma_f32 v[254:255], v[252:253], v[250:251], v[254:255]
	v_div_fixup_f32 v240, v248, v240, 1.0
	v_div_fixup_f32 v241, v249, v241, 1.0
	v_div_fixup_f32 v242, v254, v242, 1.0
	v_div_fixup_f32 v243, v255, v243, 1.0
	global_store_dwordx4 v[64:65], v[56:59], off
	s_nop 0
	v_pk_mul_f32 v[52:53], v[52:53], v[236:237]
	v_pk_mul_f32 v[48:49], v[48:49], v[238:239]
	v_pk_mul_f32 v[54:55], v[54:55], v[240:241]
	v_pk_mul_f32 v[56:57], v[50:51], v[242:243]
	v_cvt_pk_bf16_f32 v50, v52, v53
	v_cvt_pk_bf16_f32 v51, v54, v55
	v_cvt_pk_bf16_f32 v52, v48, v49
	v_add_u32_e32 v48, 0x90, v160
	v_mad_i64_i32 v[48:49], s[6:7], v48, s57, v[146:147]
	v_lshl_add_u64 v[48:49], v[48:49], 0, v[148:149]
	v_add_co_u32_e32 v58, vcc, s58, v48
	v_cvt_pk_bf16_f32 v53, v56, v57
	global_store_dwordx4 v[64:65], v[50:53], off offset:256
	s_nop 0
	v_addc_co_u32_e32 v59, vcc, 0, v49, vcc
	s_waitcnt vmcnt(11)
; __device__ __forceinline__ float sigmoidf_(float x) { return 1.0f / (1.0f + __expf(-x)); }
; __device__ __forceinline__ u32x4 pack8(const f32x4 v0, const f32x4 v1) { u32x4 w; w.x = pk2(v0[0], v0[1]); w.y = pk2(v0[2], v0[3]); w.z = pk2(v1[0], v1[1]); w.w = pk2(v1[2], v1[3]); return w; }
; __device__ __forceinline__ void unpack8(const u32x4 w, f32x4& v0, f32x4& v1) { v0 = (f32x4){bflo(w.x), bfhi(w.x), bflo(w.y), bfhi(w.y)}; v1 = (f32x4){bflo(w.z), bfhi(w.z), bflo(w.w), bfhi(w.w)}; }
;     __device__ __forceinline__ void operator()(const f32x4 (&acc)[2][2][4][2], const Unit& u, int wr, int wc, int fr, int fq) const {
;     ...
;         for (int ai = 0; ai < 2; ++ai)
; #pragma unroll
;             for (int m = 0; m < 4; ++m) {
;                 bf16_t* rowp = z + (size_t)(row0 + ai * 128 + m * 16) * DIN + col0;
; #pragma unroll
;                 for (int bj = 0; bj < 2; ++bj) {
;                     const u32x4 gw = *(const u32x4*)(rowp + (MODE == 0 ? O_GB : O_GA) + bj * 128);
;                     f32x4 g0, g1; unpack8(gw, g0, g1);
;                     f32x4 v0, v1;
; #pragma unroll
;                     for (int j = 0; j < 4; ++j) { v0[j] = sigmoidf_(g0[j]) * acc[ai][bj][m][0][j]; v1[j] = sigmoidf_(g1[j]) * acc[ai][bj][m][1][j]; }
;                     if (MODE == 1) { const u32x4 mw = *(const u32x4*)(rowp + bj * 128); f32x4 m0, m1; unpack8(mw, m0, m1); v0 += m0; v1 += m1; }
;                     *(u32x4*)(rowp + bj * 128) = pack8(v0, v1); }
	v_mov_b32_e32 v54, v216
	v_mov_b32_e32 v55, v217
	v_mov_b32_e32 v56, v218
	v_mov_b32_e32 v57, v219
	s_mov_b32 s100, 0xbfb8aa3b
	v_lshlrev_b32_e32 v236, 16, v54
	v_and_b32_e32 v237, 0xffff0000, v54
	v_lshlrev_b32_e32 v238, 16, v56
	v_and_b32_e32 v239, 0xffff0000, v56
	v_lshlrev_b32_e32 v240, 16, v55
	v_and_b32_e32 v241, 0xffff0000, v55
	v_lshlrev_b32_e32 v242, 16, v57
	v_and_b32_e32 v243, 0xffff0000, v57
	v_pk_mul_f32 v[236:237], v[236:237], s[100:101] op_sel_hi:[1,0]
	v_pk_mul_f32 v[238:239], v[238:239], s[100:101] op_sel_hi:[1,0]
	v_pk_mul_f32 v[240:241], v[240:241], s[100:101] op_sel_hi:[1,0]
	v_pk_mul_f32 v[242:243], v[242:243], s[100:101] op_sel_hi:[1,0]
	v_exp_f32_e32 v236, v236
	v_exp_f32_e32 v237, v237
	v_exp_f32_e32 v238, v238
	v_exp_f32_e32 v239, v239
	v_exp_f32_e32 v240, v240
	v_exp_f32_e32 v241, v241
	v_exp_f32_e32 v242, v242
	v_exp_f32_e32 v243, v243
	s_nop 0
	v_pk_add_f32 v[236:237], v[236:237], 1.0 op_sel_hi:[1,0]
	v_pk_add_f32 v[238:239], v[238:239], 1.0 op_sel_hi:[1,0]
	v_pk_add_f32 v[240:241], v[240:241], 1.0 op_sel_hi:[1,0]
	v_pk_add_f32 v[242:243], v[242:243], 1.0 op_sel_hi:[1,0]
	v_rcp_f32_e32 v244, v236
	v_rcp_f32_e32 v245, v237
	v_rcp_f32_e32 v250, v238
	v_rcp_f32_e32 v251, v239
	v_pk_fma_f32 v[246:247], v[236:237], v[244:245], 1.0 op_sel_hi:[1,1,0] neg_lo:[1,0,0] neg_hi:[1,0,0]
	v_pk_fma_f32 v[252:253], v[238:239], v[250:251], 1.0 op_sel_hi:[1,1,0] neg_lo:[1,0,0] neg_hi:[1,0,0]
	v_pk_fma_f32 v[244:245], v[246:247], v[244:245], v[244:245]
	v_pk_fma_f32 v[250:251], v[252:253], v[250:251], v[250:251]
	v_pk_fma_f32 v[246:247], v[236:237], v[244:245], 1.0 op_sel_hi:[1,1,0] neg_lo:[1,0,0] neg_hi:[1,0,0]
	v_pk_fma_f32 v[252:253], v[238:239], v[250:251], 1.0 op_sel_hi:[1,1,0] neg_lo:[1,0,0] neg_hi:[1,0,0]
	v_pk_fma_f32 v[248:249], v[246:247], v[244:245], v[244:245]
	v_pk_fma_f32 v[254:255], v[252:253], v[250:251], v[250:251]
	v_pk_fma_f32 v[246:247], v[236:237], v[248:249], 1.0 op_sel_hi:[1,1,0] neg_lo:[1,0,0] neg_hi:[1,0,0]
	v_pk_fma_f32 v[252:253], v[238:239], v[254:255], 1.0 op_sel_hi:[1,1,0] neg_lo:[1,0,0] neg_hi:[1,0,0]
	v_pk_fma_f32 v[248:249], v[246:247], v[244:245], v[248:249]
	v_pk_fma_f32 v[254:255], v[252:253], v[250:251], v[254:255]
	v_div_fixup_f32 v236, v248, v236, 1.0
	v_div_fixup_f32 v237, v249, v237, 1.0
	v_div_fixup_f32 v238, v254, v238, 1.0
	v_div_fixup_f32 v239, v255, v239, 1.0
	v_rcp_f32_e32 v244, v240
	v_rcp_f32_e32 v245, v241
	v_rcp_f32_e32 v250, v242
	v_rcp_f32_e32 v251, v243
	v_pk_fma_f32 v[246:247], v[240:241], v[244:245], 1.0 op_sel_hi:[1,1,0] neg_lo:[1,0,0] neg_hi:[1,0,0]
	v_pk_fma_f32 v[252:253], v[242:243], v[250:251], 1.0 op_sel_hi:[1,1,0] neg_lo:[1,0,0] neg_hi:[1,0,0]
	v_pk_fma_f32 v[244:245], v[246:247], v[244:245], v[244:245]
	v_pk_fma_f32 v[250:251], v[252:253], v[250:251], v[250:251]
	v_pk_fma_f32 v[246:247], v[240:241], v[244:245], 1.0 op_sel_hi:[1,1,0] neg_lo:[1,0,0] neg_hi:[1,0,0]
	v_pk_fma_f32 v[252:253], v[242:243], v[250:251], 1.0 op_sel_hi:[1,1,0] neg_lo:[1,0,0] neg_hi:[1,0,0]
	v_pk_fma_f32 v[248:249], v[246:247], v[244:245], v[244:245]
	v_pk_fma_f32 v[254:255], v[252:253], v[250:251], v[250:251]
	v_pk_fma_f32 v[246:247], v[240:241], v[248:249], 1.0 op_sel_hi:[1,1,0] neg_lo:[1,0,0] neg_hi:[1,0,0]
	v_pk_fma_f32 v[252:253], v[242:243], v[254:255], 1.0 op_sel_hi:[1,1,0] neg_lo:[1,0,0] neg_hi:[1,0,0]
	v_pk_fma_f32 v[248:249], v[246:247], v[244:245], v[248:249]
	v_pk_fma_f32 v[254:255], v[252:253], v[250:251], v[254:255]
	v_div_fixup_f32 v240, v248, v240, 1.0
	v_div_fixup_f32 v241, v249, v241, 1.0
	v_div_fixup_f32 v242, v254, v242, 1.0
	v_div_fixup_f32 v243, v255, v243, 1.0
	v_mul_f32_e32 v44, v44, v236
	v_mul_f32_e32 v50, v40, v238
	v_mul_f32_e32 v40, v45, v237
	v_mul_f32_e32 v45, v41, v239
	v_mul_f32_e32 v41, v46, v240
	v_mul_f32_e32 v46, v42, v242
	v_mul_f32_e32 v42, v47, v241
	v_mul_f32_e32 v43, v43, v243
	v_cvt_pk_bf16_f32 v40, v44, v40
	v_cvt_pk_bf16_f32 v41, v41, v42
	v_cvt_pk_bf16_f32 v42, v50, v45
	v_cvt_pk_bf16_f32 v43, v46, v43
	s_waitcnt vmcnt(10)
	v_mov_b32_e32 v44, v232
	v_mov_b32_e32 v45, v233
	v_mov_b32_e32 v46, v234
	v_mov_b32_e32 v47, v235
	s_mov_b32 s100, 0xbfb8aa3b
	v_lshlrev_b32_e32 v236, 16, v44
	v_and_b32_e32 v237, 0xffff0000, v44
	v_lshlrev_b32_e32 v238, 16, v46
	v_and_b32_e32 v239, 0xffff0000, v46
	v_lshlrev_b32_e32 v240, 16, v45
	v_and_b32_e32 v241, 0xffff0000, v45
	v_lshlrev_b32_e32 v242, 16, v47
	v_and_b32_e32 v243, 0xffff0000, v47
	v_pk_mul_f32 v[236:237], v[236:237], s[100:101] op_sel_hi:[1,0]
	v_pk_mul_f32 v[238:239], v[238:239], s[100:101] op_sel_hi:[1,0]
	v_pk_mul_f32 v[240:241], v[240:241], s[100:101] op_sel_hi:[1,0]
	v_pk_mul_f32 v[242:243], v[242:243], s[100:101] op_sel_hi:[1,0]
	v_exp_f32_e32 v236, v236
	v_exp_f32_e32 v237, v237
	v_exp_f32_e32 v238, v238
	v_exp_f32_e32 v239, v239
	v_exp_f32_e32 v240, v240
	v_exp_f32_e32 v241, v241
	v_exp_f32_e32 v242, v242
	v_exp_f32_e32 v243, v243
	s_nop 0
	v_pk_add_f32 v[236:237], v[236:237], 1.0 op_sel_hi:[1,0]
	v_pk_add_f32 v[238:239], v[238:239], 1.0 op_sel_hi:[1,0]
	v_pk_add_f32 v[240:241], v[240:241], 1.0 op_sel_hi:[1,0]
	v_pk_add_f32 v[242:243], v[242:243], 1.0 op_sel_hi:[1,0]
	v_rcp_f32_e32 v244, v236
	v_rcp_f32_e32 v245, v237
	v_rcp_f32_e32 v250, v238
	v_rcp_f32_e32 v251, v239
	v_pk_fma_f32 v[246:247], v[236:237], v[244:245], 1.0 op_sel_hi:[1,1,0] neg_lo:[1,0,0] neg_hi:[1,0,0]
	v_pk_fma_f32 v[252:253], v[238:239], v[250:251], 1.0 op_sel_hi:[1,1,0] neg_lo:[1,0,0] neg_hi:[1,0,0]
	v_pk_fma_f32 v[244:245], v[246:247], v[244:245], v[244:245]
	v_pk_fma_f32 v[250:251], v[252:253], v[250:251], v[250:251]
	v_pk_fma_f32 v[246:247], v[236:237], v[244:245], 1.0 op_sel_hi:[1,1,0] neg_lo:[1,0,0] neg_hi:[1,0,0]
; __device__ __forceinline__ float sigmoidf_(float x) { return 1.0f / (1.0f + __expf(-x)); }
; __device__ __forceinline__ u32x4 pack8(const f32x4 v0, const f32x4 v1) { u32x4 w; w.x = pk2(v0[0], v0[1]); w.y = pk2(v0[2], v0[3]); w.z = pk2(v1[0], v1[1]); w.w = pk2(v1[2], v1[3]); return w; }
; __device__ __forceinline__ void unpack8(const u32x4 w, f32x4& v0, f32x4& v1) { v0 = (f32x4){bflo(w.x), bfhi(w.x), bflo(w.y), bfhi(w.y)}; v1 = (f32x4){bflo(w.z), bfhi(w.z), bflo(w.w), bfhi(w.w)}; }
;     __device__ __forceinline__ void operator()(const f32x4 (&acc)[2][2][4][2], const Unit& u, int wr, int wc, int fr, int fq) const {
;     ...
;         for (int ai = 0; ai < 2; ++ai)
; #pragma unroll
;             for (int m = 0; m < 4; ++m) {
;                 bf16_t* rowp = z + (size_t)(row0 + ai * 128 + m * 16) * DIN + col0;
; #pragma unroll
;                 for (int bj = 0; bj < 2; ++bj) {
;                     const u32x4 gw = *(const u32x4*)(rowp + (MODE == 0 ? O_GB : O_GA) + bj * 128);
;                     f32x4 g0, g1; unpack8(gw, g0, g1);
;                     f32x4 v0, v1;
; #pragma unroll
;                     for (int j = 0; j < 4; ++j) { v0[j] = sigmoidf_(g0[j]) * acc[ai][bj][m][0][j]; v1[j] = sigmoidf_(g1[j]) * acc[ai][bj][m][1][j]; }
;                     if (MODE == 1) { const u32x4 mw = *(const u32x4*)(rowp + bj * 128); f32x4 m0, m1; unpack8(mw, m0, m1); v0 += m0; v1 += m1; }
;                     *(u32x4*)(rowp + bj * 128) = pack8(v0, v1); }
	v_pk_fma_f32 v[252:253], v[238:239], v[250:251], 1.0 op_sel_hi:[1,1,0] neg_lo:[1,0,0] neg_hi:[1,0,0]
	v_pk_fma_f32 v[248:249], v[246:247], v[244:245], v[244:245]
	v_pk_fma_f32 v[254:255], v[252:253], v[250:251], v[250:251]
	v_pk_fma_f32 v[246:247], v[236:237], v[248:249], 1.0 op_sel_hi:[1,1,0] neg_lo:[1,0,0] neg_hi:[1,0,0]
	v_pk_fma_f32 v[252:253], v[238:239], v[254:255], 1.0 op_sel_hi:[1,1,0] neg_lo:[1,0,0] neg_hi:[1,0,0]
	v_pk_fma_f32 v[248:249], v[246:247], v[244:245], v[248:249]
	v_pk_fma_f32 v[254:255], v[252:253], v[250:251], v[254:255]
	v_div_fixup_f32 v236, v248, v236, 1.0
	v_div_fixup_f32 v237, v249, v237, 1.0
	v_div_fixup_f32 v238, v254, v238, 1.0
	v_div_fixup_f32 v239, v255, v239, 1.0
	v_rcp_f32_e32 v244, v240
	v_rcp_f32_e32 v245, v241
	v_rcp_f32_e32 v250, v242
	v_rcp_f32_e32 v251, v243
	v_pk_fma_f32 v[246:247], v[240:241], v[244:245], 1.0 op_sel_hi:[1,1,0] neg_lo:[1,0,0] neg_hi:[1,0,0]
	v_pk_fma_f32 v[252:253], v[242:243], v[250:251], 1.0 op_sel_hi:[1,1,0] neg_lo:[1,0,0] neg_hi:[1,0,0]
	v_pk_fma_f32 v[244:245], v[246:247], v[244:245], v[244:245]
	v_pk_fma_f32 v[250:251], v[252:253], v[250:251], v[250:251]
	v_pk_fma_f32 v[246:247], v[240:241], v[244:245], 1.0 op_sel_hi:[1,1,0] neg_lo:[1,0,0] neg_hi:[1,0,0]
	v_pk_fma_f32 v[252:253], v[242:243], v[250:251], 1.0 op_sel_hi:[1,1,0] neg_lo:[1,0,0] neg_hi:[1,0,0]
	v_pk_fma_f32 v[248:249], v[246:247], v[244:245], v[244:245]
	v_pk_fma_f32 v[254:255], v[252:253], v[250:251], v[250:251]
	v_pk_fma_f32 v[246:247], v[240:241], v[248:249], 1.0 op_sel_hi:[1,1,0] neg_lo:[1,0,0] neg_hi:[1,0,0]
	v_pk_fma_f32 v[252:253], v[242:243], v[254:255], 1.0 op_sel_hi:[1,1,0] neg_lo:[1,0,0] neg_hi:[1,0,0]
	v_pk_fma_f32 v[248:249], v[246:247], v[244:245], v[248:249]
	v_pk_fma_f32 v[254:255], v[252:253], v[250:251], v[254:255]
	v_div_fixup_f32 v240, v248, v240, 1.0
	v_div_fixup_f32 v241, v249, v241, 1.0
	v_div_fixup_f32 v242, v254, v242, 1.0
	v_div_fixup_f32 v243, v255, v243, 1.0
	global_store_dwordx4 v[48:49], v[40:43], off
	s_nop 0
	v_pk_mul_f32 v[36:37], v[36:37], v[236:237]
	v_pk_mul_f32 v[32:33], v[32:33], v[238:239]
	v_pk_mul_f32 v[38:39], v[38:39], v[240:241]
	v_pk_mul_f32 v[40:41], v[34:35], v[242:243]
	v_cvt_pk_bf16_f32 v34, v36, v37
	v_cvt_pk_bf16_f32 v35, v38, v39
	v_cvt_pk_bf16_f32 v36, v32, v33
	v_add_u32_e32 v32, 0xa0, v160
	v_mad_i64_i32 v[32:33], s[6:7], v32, s57, v[146:147]
	v_lshl_add_u64 v[32:33], v[32:33], 0, v[148:149]
	v_add_co_u32_e32 v42, vcc, s58, v32
	v_cvt_pk_bf16_f32 v37, v40, v41
	global_store_dwordx4 v[48:49], v[34:37], off offset:256
	s_nop 0
	v_addc_co_u32_e32 v43, vcc, 0, v33, vcc
	s_waitcnt vmcnt(9)
	v_mov_b32_e32 v38, v200
	v_mov_b32_e32 v39, v201
	v_mov_b32_e32 v40, v202
	v_mov_b32_e32 v41, v203
	s_mov_b32 s100, 0xbfb8aa3b
	v_lshlrev_b32_e32 v236, 16, v38
	v_and_b32_e32 v237, 0xffff0000, v38
	v_lshlrev_b32_e32 v238, 16, v40
	v_and_b32_e32 v239, 0xffff0000, v40
	v_lshlrev_b32_e32 v240, 16, v39
	v_and_b32_e32 v241, 0xffff0000, v39
	v_lshlrev_b32_e32 v242, 16, v41
	v_and_b32_e32 v243, 0xffff0000, v41
	v_pk_mul_f32 v[236:237], v[236:237], s[100:101] op_sel_hi:[1,0]
	v_pk_mul_f32 v[238:239], v[238:239], s[100:101] op_sel_hi:[1,0]
	v_pk_mul_f32 v[240:241], v[240:241], s[100:101] op_sel_hi:[1,0]
	v_pk_mul_f32 v[242:243], v[242:243], s[100:101] op_sel_hi:[1,0]
	v_exp_f32_e32 v236, v236
	v_exp_f32_e32 v237, v237
	v_exp_f32_e32 v238, v238
	v_exp_f32_e32 v239, v239
	v_exp_f32_e32 v240, v240
	v_exp_f32_e32 v241, v241
	v_exp_f32_e32 v242, v242
	v_exp_f32_e32 v243, v243
	s_nop 0
	v_pk_add_f32 v[236:237], v[236:237], 1.0 op_sel_hi:[1,0]
	v_pk_add_f32 v[238:239], v[238:239], 1.0 op_sel_hi:[1,0]
	v_pk_add_f32 v[240:241], v[240:241], 1.0 op_sel_hi:[1,0]
	v_pk_add_f32 v[242:243], v[242:243], 1.0 op_sel_hi:[1,0]
	v_rcp_f32_e32 v244, v236
	v_rcp_f32_e32 v245, v237
	v_rcp_f32_e32 v250, v238
	v_rcp_f32_e32 v251, v239
	v_pk_fma_f32 v[246:247], v[236:237], v[244:245], 1.0 op_sel_hi:[1,1,0] neg_lo:[1,0,0] neg_hi:[1,0,0]
	v_pk_fma_f32 v[252:253], v[238:239], v[250:251], 1.0 op_sel_hi:[1,1,0] neg_lo:[1,0,0] neg_hi:[1,0,0]
	v_pk_fma_f32 v[244:245], v[246:247], v[244:245], v[244:245]
	v_pk_fma_f32 v[250:251], v[252:253], v[250:251], v[250:251]
	v_pk_fma_f32 v[246:247], v[236:237], v[244:245], 1.0 op_sel_hi:[1,1,0] neg_lo:[1,0,0] neg_hi:[1,0,0]
	v_pk_fma_f32 v[252:253], v[238:239], v[250:251], 1.0 op_sel_hi:[1,1,0] neg_lo:[1,0,0] neg_hi:[1,0,0]
	v_pk_fma_f32 v[248:249], v[246:247], v[244:245], v[244:245]
	v_pk_fma_f32 v[254:255], v[252:253], v[250:251], v[250:251]
	v_pk_fma_f32 v[246:247], v[236:237], v[248:249], 1.0 op_sel_hi:[1,1,0] neg_lo:[1,0,0] neg_hi:[1,0,0]
	v_pk_fma_f32 v[252:253], v[238:239], v[254:255], 1.0 op_sel_hi:[1,1,0] neg_lo:[1,0,0] neg_hi:[1,0,0]
	v_pk_fma_f32 v[248:249], v[246:247], v[244:245], v[248:249]
	v_pk_fma_f32 v[254:255], v[252:253], v[250:251], v[254:255]
	v_div_fixup_f32 v236, v248, v236, 1.0
	v_div_fixup_f32 v237, v249, v237, 1.0
	v_div_fixup_f32 v238, v254, v238, 1.0
	v_div_fixup_f32 v239, v255, v239, 1.0
	v_rcp_f32_e32 v244, v240
	v_rcp_f32_e32 v245, v241
	v_rcp_f32_e32 v250, v242
	v_rcp_f32_e32 v251, v243
	v_pk_fma_f32 v[246:247], v[240:241], v[244:245], 1.0 op_sel_hi:[1,1,0] neg_lo:[1,0,0] neg_hi:[1,0,0]
	v_pk_fma_f32 v[252:253], v[242:243], v[250:251], 1.0 op_sel_hi:[1,1,0] neg_lo:[1,0,0] neg_hi:[1,0,0]
	v_pk_fma_f32 v[244:245], v[246:247], v[244:245], v[244:245]
	v_pk_fma_f32 v[250:251], v[252:253], v[250:251], v[250:251]
	v_pk_fma_f32 v[246:247], v[240:241], v[244:245], 1.0 op_sel_hi:[1,1,0] neg_lo:[1,0,0] neg_hi:[1,0,0]
	v_pk_fma_f32 v[252:253], v[242:243], v[250:251], 1.0 op_sel_hi:[1,1,0] neg_lo:[1,0,0] neg_hi:[1,0,0]
	v_pk_fma_f32 v[248:249], v[246:247], v[244:245], v[244:245]
	v_pk_fma_f32 v[254:255], v[252:253], v[250:251], v[250:251]
	v_pk_fma_f32 v[246:247], v[240:241], v[248:249], 1.0 op_sel_hi:[1,1,0] neg_lo:[1,0,0] neg_hi:[1,0,0]
	v_pk_fma_f32 v[252:253], v[242:243], v[254:255], 1.0 op_sel_hi:[1,1,0] neg_lo:[1,0,0] neg_hi:[1,0,0]
	v_pk_fma_f32 v[248:249], v[246:247], v[244:245], v[248:249]
	v_pk_fma_f32 v[254:255], v[252:253], v[250:251], v[254:255]
	v_div_fixup_f32 v240, v248, v240, 1.0
	v_div_fixup_f32 v241, v249, v241, 1.0
	v_div_fixup_f32 v242, v254, v242, 1.0
	v_div_fixup_f32 v243, v255, v243, 1.0
	v_mul_f32_e32 v28, v28, v236
	v_mul_f32_e32 v34, v24, v238
	v_mul_f32_e32 v24, v29, v237
	v_mul_f32_e32 v29, v25, v239
	v_mul_f32_e32 v25, v30, v240
	v_mul_f32_e32 v30, v26, v242
	v_mul_f32_e32 v26, v31, v241
	v_mul_f32_e32 v27, v27, v243
	v_cvt_pk_bf16_f32 v24, v28, v24
	v_cvt_pk_bf16_f32 v25, v25, v26
	v_cvt_pk_bf16_f32 v26, v34, v29
	v_cvt_pk_bf16_f32 v27, v30, v27
	s_waitcnt vmcnt(8)
; __device__ __forceinline__ float sigmoidf_(float x) { return 1.0f / (1.0f + __expf(-x)); }
; __device__ __forceinline__ u32x4 pack8(const f32x4 v0, const f32x4 v1) { u32x4 w; w.x = pk2(v0[0], v0[1]); w.y = pk2(v0[2], v0[3]); w.z = pk2(v1[0], v1[1]); w.w = pk2(v1[2], v1[3]); return w; }
; __device__ __forceinline__ void unpack8(const u32x4 w, f32x4& v0, f32x4& v1) { v0 = (f32x4){bflo(w.x), bfhi(w.x), bflo(w.y), bfhi(w.y)}; v1 = (f32x4){bflo(w.z), bfhi(w.z), bflo(w.w), bfhi(w.w)}; }
;     __device__ __forceinline__ void operator()(const f32x4 (&acc)[2][2][4][2], const Unit& u, int wr, int wc, int fr, int fq) const {
;     ...
;         for (int ai = 0; ai < 2; ++ai)
; #pragma unroll
;             for (int m = 0; m < 4; ++m) {
;                 bf16_t* rowp = z + (size_t)(row0 + ai * 128 + m * 16) * DIN + col0;
; #pragma unroll
;                 for (int bj = 0; bj < 2; ++bj) {
;                     const u32x4 gw = *(const u32x4*)(rowp + (MODE == 0 ? O_GB : O_GA) + bj * 128);
;                     f32x4 g0, g1; unpack8(gw, g0, g1);
;                     f32x4 v0, v1;
; #pragma unroll
;                     for (int j = 0; j < 4; ++j) { v0[j] = sigmoidf_(g0[j]) * acc[ai][bj][m][0][j]; v1[j] = sigmoidf_(g1[j]) * acc[ai][bj][m][1][j]; }
;                     if (MODE == 1) { const u32x4 mw = *(const u32x4*)(rowp + bj * 128); f32x4 m0, m1; unpack8(mw, m0, m1); v0 += m0; v1 += m1; }
;                     *(u32x4*)(rowp + bj * 128) = pack8(v0, v1); }
	v_mov_b32_e32 v28, v204
	v_mov_b32_e32 v29, v205
	v_mov_b32_e32 v30, v206
	v_mov_b32_e32 v31, v207
	s_mov_b32 s100, 0xbfb8aa3b
	v_lshlrev_b32_e32 v236, 16, v28
	v_and_b32_e32 v237, 0xffff0000, v28
	v_lshlrev_b32_e32 v238, 16, v30
	v_and_b32_e32 v239, 0xffff0000, v30
	v_lshlrev_b32_e32 v240, 16, v29
	v_and_b32_e32 v241, 0xffff0000, v29
	v_lshlrev_b32_e32 v242, 16, v31
	v_and_b32_e32 v243, 0xffff0000, v31
	v_pk_mul_f32 v[236:237], v[236:237], s[100:101] op_sel_hi:[1,0]
	v_pk_mul_f32 v[238:239], v[238:239], s[100:101] op_sel_hi:[1,0]
	v_pk_mul_f32 v[240:241], v[240:241], s[100:101] op_sel_hi:[1,0]
	v_pk_mul_f32 v[242:243], v[242:243], s[100:101] op_sel_hi:[1,0]
	v_exp_f32_e32 v236, v236
	v_exp_f32_e32 v237, v237
	v_exp_f32_e32 v238, v238
	v_exp_f32_e32 v239, v239
	v_exp_f32_e32 v240, v240
	v_exp_f32_e32 v241, v241
	v_exp_f32_e32 v242, v242
	v_exp_f32_e32 v243, v243
	s_nop 0
	v_pk_add_f32 v[236:237], v[236:237], 1.0 op_sel_hi:[1,0]
	v_pk_add_f32 v[238:239], v[238:239], 1.0 op_sel_hi:[1,0]
	v_pk_add_f32 v[240:241], v[240:241], 1.0 op_sel_hi:[1,0]
	v_pk_add_f32 v[242:243], v[242:243], 1.0 op_sel_hi:[1,0]
	v_rcp_f32_e32 v244, v236
	v_rcp_f32_e32 v245, v237
	v_rcp_f32_e32 v250, v238
	v_rcp_f32_e32 v251, v239
	v_pk_fma_f32 v[246:247], v[236:237], v[244:245], 1.0 op_sel_hi:[1,1,0] neg_lo:[1,0,0] neg_hi:[1,0,0]
	v_pk_fma_f32 v[252:253], v[238:239], v[250:251], 1.0 op_sel_hi:[1,1,0] neg_lo:[1,0,0] neg_hi:[1,0,0]
	v_pk_fma_f32 v[244:245], v[246:247], v[244:245], v[244:245]
	v_pk_fma_f32 v[250:251], v[252:253], v[250:251], v[250:251]
	v_pk_fma_f32 v[246:247], v[236:237], v[244:245], 1.0 op_sel_hi:[1,1,0] neg_lo:[1,0,0] neg_hi:[1,0,0]
	v_pk_fma_f32 v[252:253], v[238:239], v[250:251], 1.0 op_sel_hi:[1,1,0] neg_lo:[1,0,0] neg_hi:[1,0,0]
	v_pk_fma_f32 v[248:249], v[246:247], v[244:245], v[244:245]
	v_pk_fma_f32 v[254:255], v[252:253], v[250:251], v[250:251]
	v_pk_fma_f32 v[246:247], v[236:237], v[248:249], 1.0 op_sel_hi:[1,1,0] neg_lo:[1,0,0] neg_hi:[1,0,0]
	v_pk_fma_f32 v[252:253], v[238:239], v[254:255], 1.0 op_sel_hi:[1,1,0] neg_lo:[1,0,0] neg_hi:[1,0,0]
	v_pk_fma_f32 v[248:249], v[246:247], v[244:245], v[248:249]
	v_pk_fma_f32 v[254:255], v[252:253], v[250:251], v[254:255]
	v_div_fixup_f32 v236, v248, v236, 1.0
	v_div_fixup_f32 v237, v249, v237, 1.0
	v_div_fixup_f32 v238, v254, v238, 1.0
	v_div_fixup_f32 v239, v255, v239, 1.0
	v_rcp_f32_e32 v244, v240
	v_rcp_f32_e32 v245, v241
	v_rcp_f32_e32 v250, v242
	v_rcp_f32_e32 v251, v243
	v_pk_fma_f32 v[246:247], v[240:241], v[244:245], 1.0 op_sel_hi:[1,1,0] neg_lo:[1,0,0] neg_hi:[1,0,0]
	v_pk_fma_f32 v[252:253], v[242:243], v[250:251], 1.0 op_sel_hi:[1,1,0] neg_lo:[1,0,0] neg_hi:[1,0,0]
	v_pk_fma_f32 v[244:245], v[246:247], v[244:245], v[244:245]
	v_pk_fma_f32 v[250:251], v[252:253], v[250:251], v[250:251]
	v_pk_fma_f32 v[246:247], v[240:241], v[244:245], 1.0 op_sel_hi:[1,1,0] neg_lo:[1,0,0] neg_hi:[1,0,0]
	v_pk_fma_f32 v[252:253], v[242:243], v[250:251], 1.0 op_sel_hi:[1,1,0] neg_lo:[1,0,0] neg_hi:[1,0,0]
	v_pk_fma_f32 v[248:249], v[246:247], v[244:245], v[244:245]
	v_pk_fma_f32 v[254:255], v[252:253], v[250:251], v[250:251]
	v_pk_fma_f32 v[246:247], v[240:241], v[248:249], 1.0 op_sel_hi:[1,1,0] neg_lo:[1,0,0] neg_hi:[1,0,0]
	v_pk_fma_f32 v[252:253], v[242:243], v[254:255], 1.0 op_sel_hi:[1,1,0] neg_lo:[1,0,0] neg_hi:[1,0,0]
	v_pk_fma_f32 v[248:249], v[246:247], v[244:245], v[248:249]
	v_pk_fma_f32 v[254:255], v[252:253], v[250:251], v[254:255]
	v_div_fixup_f32 v240, v248, v240, 1.0
	v_div_fixup_f32 v241, v249, v241, 1.0
	v_div_fixup_f32 v242, v254, v242, 1.0
	v_div_fixup_f32 v243, v255, v243, 1.0
	global_store_dwordx4 v[32:33], v[24:27], off
	s_nop 0
	v_pk_mul_f32 v[20:21], v[20:21], v[236:237]
	v_pk_mul_f32 v[16:17], v[16:17], v[238:239]
	v_pk_mul_f32 v[22:23], v[22:23], v[240:241]
	v_pk_mul_f32 v[24:25], v[18:19], v[242:243]
	v_cvt_pk_bf16_f32 v18, v20, v21
	v_cvt_pk_bf16_f32 v19, v22, v23
	v_cvt_pk_bf16_f32 v20, v16, v17
	v_add_u32_e32 v16, 0xb0, v160
	v_mad_i64_i32 v[16:17], s[6:7], v16, s57, v[146:147]
	v_lshl_add_u64 v[16:17], v[16:17], 0, v[148:149]
	v_add_co_u32_e32 v26, vcc, s58, v16
	v_cvt_pk_bf16_f32 v21, v24, v25
	global_store_dwordx4 v[32:33], v[18:21], off offset:256
	s_nop 0
	v_addc_co_u32_e32 v27, vcc, 0, v17, vcc
	s_waitcnt vmcnt(7)
; __device__ __forceinline__ float sigmoidf_(float x) { return 1.0f / (1.0f + __expf(-x)); }
; __device__ __forceinline__ u32x4 pack8(const f32x4 v0, const f32x4 v1) { u32x4 w; w.x = pk2(v0[0], v0[1]); w.y = pk2(v0[2], v0[3]); w.z = pk2(v1[0], v1[1]); w.w = pk2(v1[2], v1[3]); return w; }
; __device__ __forceinline__ void unpack8(const u32x4 w, f32x4& v0, f32x4& v1) { v0 = (f32x4){bflo(w.x), bfhi(w.x), bflo(w.y), bfhi(w.y)}; v1 = (f32x4){bflo(w.z), bfhi(w.z), bflo(w.w), bfhi(w.w)}; }
;     __device__ __forceinline__ void operator()(const f32x4 (&acc)[2][2][4][2], const Unit& u, int wr, int wc, int fr, int fq) const {
;     ...
;         for (int ai = 0; ai < 2; ++ai)
; #pragma unroll
;             for (int m = 0; m < 4; ++m) {
;                 bf16_t* rowp = z + (size_t)(row0 + ai * 128 + m * 16) * DIN + col0;
; #pragma unroll
;                 for (int bj = 0; bj < 2; ++bj) {
;                     const u32x4 gw = *(const u32x4*)(rowp + (MODE == 0 ? O_GB : O_GA) + bj * 128);
;                     f32x4 g0, g1; unpack8(gw, g0, g1);
;                     f32x4 v0, v1;
; #pragma unroll
;                     for (int j = 0; j < 4; ++j) { v0[j] = sigmoidf_(g0[j]) * acc[ai][bj][m][0][j]; v1[j] = sigmoidf_(g1[j]) * acc[ai][bj][m][1][j]; }
;                     if (MODE == 1) { const u32x4 mw = *(const u32x4*)(rowp + bj * 128); f32x4 m0, m1; unpack8(mw, m0, m1); v0 += m0; v1 += m1; }
;                     *(u32x4*)(rowp + bj * 128) = pack8(v0, v1); }
	v_mov_b32_e32 v22, v208
	v_mov_b32_e32 v23, v209
	v_mov_b32_e32 v24, v210
	v_mov_b32_e32 v25, v211
	s_mov_b32 s100, 0xbfb8aa3b
	v_lshlrev_b32_e32 v236, 16, v22
	v_and_b32_e32 v237, 0xffff0000, v22
	v_lshlrev_b32_e32 v238, 16, v24
	v_and_b32_e32 v239, 0xffff0000, v24
	v_lshlrev_b32_e32 v240, 16, v23
	v_and_b32_e32 v241, 0xffff0000, v23
	v_lshlrev_b32_e32 v242, 16, v25
	v_and_b32_e32 v243, 0xffff0000, v25
	v_pk_mul_f32 v[236:237], v[236:237], s[100:101] op_sel_hi:[1,0]
	v_pk_mul_f32 v[238:239], v[238:239], s[100:101] op_sel_hi:[1,0]
	v_pk_mul_f32 v[240:241], v[240:241], s[100:101] op_sel_hi:[1,0]
	v_pk_mul_f32 v[242:243], v[242:243], s[100:101] op_sel_hi:[1,0]
	v_exp_f32_e32 v236, v236
	v_exp_f32_e32 v237, v237
	v_exp_f32_e32 v238, v238
	v_exp_f32_e32 v239, v239
	v_exp_f32_e32 v240, v240
	v_exp_f32_e32 v241, v241
	v_exp_f32_e32 v242, v242
	v_exp_f32_e32 v243, v243
	s_nop 0
	v_pk_add_f32 v[236:237], v[236:237], 1.0 op_sel_hi:[1,0]
	v_pk_add_f32 v[238:239], v[238:239], 1.0 op_sel_hi:[1,0]
	v_pk_add_f32 v[240:241], v[240:241], 1.0 op_sel_hi:[1,0]
	v_pk_add_f32 v[242:243], v[242:243], 1.0 op_sel_hi:[1,0]
	v_rcp_f32_e32 v244, v236
	v_rcp_f32_e32 v245, v237
	v_rcp_f32_e32 v250, v238
	v_rcp_f32_e32 v251, v239
	v_pk_fma_f32 v[246:247], v[236:237], v[244:245], 1.0 op_sel_hi:[1,1,0] neg_lo:[1,0,0] neg_hi:[1,0,0]
	v_pk_fma_f32 v[252:253], v[238:239], v[250:251], 1.0 op_sel_hi:[1,1,0] neg_lo:[1,0,0] neg_hi:[1,0,0]
	v_pk_fma_f32 v[244:245], v[246:247], v[244:245], v[244:245]
	v_pk_fma_f32 v[250:251], v[252:253], v[250:251], v[250:251]
	v_pk_fma_f32 v[246:247], v[236:237], v[244:245], 1.0 op_sel_hi:[1,1,0] neg_lo:[1,0,0] neg_hi:[1,0,0]
	v_pk_fma_f32 v[252:253], v[238:239], v[250:251], 1.0 op_sel_hi:[1,1,0] neg_lo:[1,0,0] neg_hi:[1,0,0]
	v_pk_fma_f32 v[248:249], v[246:247], v[244:245], v[244:245]
	v_pk_fma_f32 v[254:255], v[252:253], v[250:251], v[250:251]
	v_pk_fma_f32 v[246:247], v[236:237], v[248:249], 1.0 op_sel_hi:[1,1,0] neg_lo:[1,0,0] neg_hi:[1,0,0]
	v_pk_fma_f32 v[252:253], v[238:239], v[254:255], 1.0 op_sel_hi:[1,1,0] neg_lo:[1,0,0] neg_hi:[1,0,0]
	v_pk_fma_f32 v[248:249], v[246:247], v[244:245], v[248:249]
	v_pk_fma_f32 v[254:255], v[252:253], v[250:251], v[254:255]
	v_div_fixup_f32 v236, v248, v236, 1.0
	v_div_fixup_f32 v237, v249, v237, 1.0
	v_div_fixup_f32 v238, v254, v238, 1.0
	v_div_fixup_f32 v239, v255, v239, 1.0
	v_rcp_f32_e32 v244, v240
	v_rcp_f32_e32 v245, v241
	v_rcp_f32_e32 v250, v242
	v_rcp_f32_e32 v251, v243
	v_pk_fma_f32 v[246:247], v[240:241], v[244:245], 1.0 op_sel_hi:[1,1,0] neg_lo:[1,0,0] neg_hi:[1,0,0]
	v_pk_fma_f32 v[252:253], v[242:243], v[250:251], 1.0 op_sel_hi:[1,1,0] neg_lo:[1,0,0] neg_hi:[1,0,0]
	v_pk_fma_f32 v[244:245], v[246:247], v[244:245], v[244:245]
	v_pk_fma_f32 v[250:251], v[252:253], v[250:251], v[250:251]
	v_pk_fma_f32 v[246:247], v[240:241], v[244:245], 1.0 op_sel_hi:[1,1,0] neg_lo:[1,0,0] neg_hi:[1,0,0]
	v_pk_fma_f32 v[252:253], v[242:243], v[250:251], 1.0 op_sel_hi:[1,1,0] neg_lo:[1,0,0] neg_hi:[1,0,0]
	v_pk_fma_f32 v[248:249], v[246:247], v[244:245], v[244:245]
	v_pk_fma_f32 v[254:255], v[252:253], v[250:251], v[250:251]
	v_pk_fma_f32 v[246:247], v[240:241], v[248:249], 1.0 op_sel_hi:[1,1,0] neg_lo:[1,0,0] neg_hi:[1,0,0]
	v_pk_fma_f32 v[252:253], v[242:243], v[254:255], 1.0 op_sel_hi:[1,1,0] neg_lo:[1,0,0] neg_hi:[1,0,0]
	v_pk_fma_f32 v[248:249], v[246:247], v[244:245], v[248:249]
	v_pk_fma_f32 v[254:255], v[252:253], v[250:251], v[254:255]
	v_div_fixup_f32 v240, v248, v240, 1.0
	v_div_fixup_f32 v241, v249, v241, 1.0
	v_div_fixup_f32 v242, v254, v242, 1.0
	v_div_fixup_f32 v243, v255, v243, 1.0
	v_mul_f32_e32 v12, v12, v236
	v_mul_f32_e32 v18, v8, v238
	v_mul_f32_e32 v8, v13, v237
	v_mul_f32_e32 v13, v9, v239
	v_mul_f32_e32 v9, v14, v240
	v_mul_f32_e32 v14, v10, v242
	v_mul_f32_e32 v10, v15, v241
	v_mul_f32_e32 v11, v11, v243
	v_cvt_pk_bf16_f32 v8, v12, v8
	v_cvt_pk_bf16_f32 v9, v9, v10
	v_cvt_pk_bf16_f32 v10, v18, v13
	v_cvt_pk_bf16_f32 v11, v14, v11
	s_waitcnt vmcnt(6)
; __device__ __forceinline__ float sigmoidf_(float x) { return 1.0f / (1.0f + __expf(-x)); }
; #define PG8_WAIT_V(n) asm volatile("s_waitcnt vmcnt(" #n ")" ::: "memory")
; #define PG8_BAR __builtin_amdgcn_s_barrier()
; __device__ __forceinline__ u32x4 pack8(const f32x4 v0, const f32x4 v1) { u32x4 w; w.x = pk2(v0[0], v0[1]); w.y = pk2(v0[2], v0[3]); w.z = pk2(v1[0], v1[1]); w.w = pk2(v1[2], v1[3]); return w; }
; __device__ __forceinline__ void unpack8(const u32x4 w, f32x4& v0, f32x4& v1) { v0 = (f32x4){bflo(w.x), bfhi(w.x), bflo(w.y), bfhi(w.y)}; v1 = (f32x4){bflo(w.z), bfhi(w.z), bflo(w.w), bfhi(w.w)}; }
;     ...
;         if (!has_next) break;
; #pragma unroll
;         for (int a = 0; a < 2; ++a)
; #pragma unroll
;             for (int b = 0; b < 2; ++b)
; #pragma unroll
;                 for (int m = 0; m < 4; ++m)
; #pragma unroll
;                     for (int n = 0; n < 2; ++n) acc[a][b][m][n] = (f32x4){0.f, 0.f, 0.f, 0.f};
;         cur = nxt; cA = nA; cB = nB; ++ui;
;     }
;     PG8_WAIT_V(0);
;     if (wr == 0) PG8_BAR;
;     __device__ __forceinline__ void operator()(const f32x4 (&acc)[2][2][4][2], const Unit& u, int wr, int wc, int fr, int fq) const {
;     ...
;         for (int ai = 0; ai < 2; ++ai)
; #pragma unroll
;             for (int m = 0; m < 4; ++m) {
;                 bf16_t* rowp = z + (size_t)(row0 + ai * 128 + m * 16) * DIN + col0;
; #pragma unroll
;                 for (int bj = 0; bj < 2; ++bj) {
;                     const u32x4 gw = *(const u32x4*)(rowp + (MODE == 0 ? O_GB : O_GA) + bj * 128);
;                     f32x4 g0, g1; unpack8(gw, g0, g1);
;                     f32x4 v0, v1;
; #pragma unroll
;                     for (int j = 0; j < 4; ++j) { v0[j] = sigmoidf_(g0[j]) * acc[ai][bj][m][0][j]; v1[j] = sigmoidf_(g1[j]) * acc[ai][bj][m][1][j]; }
;                     if (MODE == 1) { const u32x4 mw = *(const u32x4*)(rowp + bj * 128); f32x4 m0, m1; unpack8(mw, m0, m1); v0 += m0; v1 += m1; }
;                     *(u32x4*)(rowp + bj * 128) = pack8(v0, v1); }
	v_mov_b32_e32 v12, v212
	v_mov_b32_e32 v13, v213
	v_mov_b32_e32 v14, v214
	v_mov_b32_e32 v15, v215
	s_mov_b32 s100, 0xbfb8aa3b
	v_lshlrev_b32_e32 v236, 16, v12
	v_and_b32_e32 v237, 0xffff0000, v12
	v_lshlrev_b32_e32 v238, 16, v14
	v_and_b32_e32 v239, 0xffff0000, v14
	v_lshlrev_b32_e32 v240, 16, v13
	v_and_b32_e32 v241, 0xffff0000, v13
	v_lshlrev_b32_e32 v242, 16, v15
	v_and_b32_e32 v243, 0xffff0000, v15
	v_pk_mul_f32 v[236:237], v[236:237], s[100:101] op_sel_hi:[1,0]
	v_pk_mul_f32 v[238:239], v[238:239], s[100:101] op_sel_hi:[1,0]
	v_pk_mul_f32 v[240:241], v[240:241], s[100:101] op_sel_hi:[1,0]
	v_pk_mul_f32 v[242:243], v[242:243], s[100:101] op_sel_hi:[1,0]
	v_exp_f32_e32 v236, v236
	v_exp_f32_e32 v237, v237
	v_exp_f32_e32 v238, v238
	v_exp_f32_e32 v239, v239
	v_exp_f32_e32 v240, v240
	v_exp_f32_e32 v241, v241
	v_exp_f32_e32 v242, v242
	v_exp_f32_e32 v243, v243
	s_nop 0
	v_pk_add_f32 v[236:237], v[236:237], 1.0 op_sel_hi:[1,0]
	v_pk_add_f32 v[238:239], v[238:239], 1.0 op_sel_hi:[1,0]
	v_pk_add_f32 v[240:241], v[240:241], 1.0 op_sel_hi:[1,0]
	v_pk_add_f32 v[242:243], v[242:243], 1.0 op_sel_hi:[1,0]
	v_rcp_f32_e32 v244, v236
	v_rcp_f32_e32 v245, v237
	v_rcp_f32_e32 v250, v238
	v_rcp_f32_e32 v251, v239
	v_pk_fma_f32 v[246:247], v[236:237], v[244:245], 1.0 op_sel_hi:[1,1,0] neg_lo:[1,0,0] neg_hi:[1,0,0]
	v_pk_fma_f32 v[252:253], v[238:239], v[250:251], 1.0 op_sel_hi:[1,1,0] neg_lo:[1,0,0] neg_hi:[1,0,0]
	v_pk_fma_f32 v[244:245], v[246:247], v[244:245], v[244:245]
	v_pk_fma_f32 v[250:251], v[252:253], v[250:251], v[250:251]
	v_pk_fma_f32 v[246:247], v[236:237], v[244:245], 1.0 op_sel_hi:[1,1,0] neg_lo:[1,0,0] neg_hi:[1,0,0]
	v_pk_fma_f32 v[252:253], v[238:239], v[250:251], 1.0 op_sel_hi:[1,1,0] neg_lo:[1,0,0] neg_hi:[1,0,0]
	v_pk_fma_f32 v[248:249], v[246:247], v[244:245], v[244:245]
	v_pk_fma_f32 v[254:255], v[252:253], v[250:251], v[250:251]
	v_pk_fma_f32 v[246:247], v[236:237], v[248:249], 1.0 op_sel_hi:[1,1,0] neg_lo:[1,0,0] neg_hi:[1,0,0]
	v_pk_fma_f32 v[252:253], v[238:239], v[254:255], 1.0 op_sel_hi:[1,1,0] neg_lo:[1,0,0] neg_hi:[1,0,0]
	v_pk_fma_f32 v[248:249], v[246:247], v[244:245], v[248:249]
	v_pk_fma_f32 v[254:255], v[252:253], v[250:251], v[254:255]
	v_div_fixup_f32 v236, v248, v236, 1.0
	v_div_fixup_f32 v237, v249, v237, 1.0
	v_div_fixup_f32 v238, v254, v238, 1.0
	v_div_fixup_f32 v239, v255, v239, 1.0
	v_rcp_f32_e32 v244, v240
	v_rcp_f32_e32 v245, v241
	v_rcp_f32_e32 v250, v242
	v_rcp_f32_e32 v251, v243
	v_pk_fma_f32 v[246:247], v[240:241], v[244:245], 1.0 op_sel_hi:[1,1,0] neg_lo:[1,0,0] neg_hi:[1,0,0]
	v_pk_fma_f32 v[252:253], v[242:243], v[250:251], 1.0 op_sel_hi:[1,1,0] neg_lo:[1,0,0] neg_hi:[1,0,0]
	v_pk_fma_f32 v[244:245], v[246:247], v[244:245], v[244:245]
	v_pk_fma_f32 v[250:251], v[252:253], v[250:251], v[250:251]
	v_pk_fma_f32 v[246:247], v[240:241], v[244:245], 1.0 op_sel_hi:[1,1,0] neg_lo:[1,0,0] neg_hi:[1,0,0]
	v_pk_fma_f32 v[252:253], v[242:243], v[250:251], 1.0 op_sel_hi:[1,1,0] neg_lo:[1,0,0] neg_hi:[1,0,0]
	v_pk_fma_f32 v[248:249], v[246:247], v[244:245], v[244:245]
	v_pk_fma_f32 v[254:255], v[252:253], v[250:251], v[250:251]
	v_pk_fma_f32 v[246:247], v[240:241], v[248:249], 1.0 op_sel_hi:[1,1,0] neg_lo:[1,0,0] neg_hi:[1,0,0]
	v_pk_fma_f32 v[252:253], v[242:243], v[254:255], 1.0 op_sel_hi:[1,1,0] neg_lo:[1,0,0] neg_hi:[1,0,0]
	v_pk_fma_f32 v[248:249], v[246:247], v[244:245], v[248:249]
	v_pk_fma_f32 v[254:255], v[252:253], v[250:251], v[254:255]
	v_div_fixup_f32 v240, v248, v240, 1.0
	v_div_fixup_f32 v241, v249, v241, 1.0
	v_div_fixup_f32 v242, v254, v242, 1.0
	v_div_fixup_f32 v243, v255, v243, 1.0
	global_store_dwordx4 v[16:17], v[8:11], off
	s_nop 0
	v_mul_f32_e32 v4, v4, v236
	v_mul_f32_e32 v8, v0, v238
	v_mul_f32_e32 v0, v5, v237
	v_mul_f32_e32 v5, v1, v239
	v_mul_f32_e32 v1, v6, v240
	v_mul_f32_e32 v6, v2, v242
	v_mul_f32_e32 v2, v7, v241
	v_mul_f32_e32 v3, v3, v243
	s_and_b64 vcc, exec, s[8:9]
	s_mov_b32 s7, s26
	s_mov_b32 s6, s59
	v_cvt_pk_bf16_f32 v0, v4, v0
	v_cvt_pk_bf16_f32 v1, v1, v2
	v_cvt_pk_bf16_f32 v2, v8, v5
	v_cvt_pk_bf16_f32 v3, v6, v3
	global_store_dwordx4 v[16:17], v[0:3], off offset:256
	s_cbranch_vccz .LBB0_1763
	s_waitcnt vmcnt(0)
	s_cmpk_gt_u32 s34, 0xff
	s_cbranch_scc1 .LBB0_1772
	s_barrier
